# v52 plus gate_up epilogue: per-lane row scales computed once per phase (first tile), parked in LDS and re-read by later tiles
# speedup vs baseline: 1.0105x; 1.0105x over previous
; __device__ __forceinline__ float row_part(const float* ss, int row, int fq) { const f32x4 a = ((const f32x4*)(ss + (size_t)row * 16))[fq]; return (a[0] + a[1]) + (a[2] + a[3]); }
; __device__ __forceinline__ float row_finish(float t) { t += shx(t, 16); t += shx(t, 32); return __builtin_amdgcn_rsqf(t * (1.0f / 1024.0f) + RMS_EPS); }
;     __device__ __forceinline__ void operator()(const f32x4 (&acc)[2][2][4][2], const Unit& u, int wr, int wc, int fr, int fq) const {
;         const int col0 = u.pn * 128 + 32 * wc + 8 * fq;
;         float rs[2][4];
; #pragma unroll
;         for (int ai = 0; ai < 2; ++ai)
; #pragma unroll
;             for (int m = 0; m < 4; ++m) rs[ai][m] = row_part(ss, u.pm * BM + ai * HALF + wr * 64 + m * 16 + fr, fq);
; #pragma unroll
;         for (int ai = 0; ai < 2; ++ai)
; #pragma unroll
;             for (int m = 0; m < 4; ++m) rs[ai][m] = row_finish(rs[ai][m]);
.LBB0_523:
	s_lshr_b32 s98, s2, 6
	s_cmp_lg_u32 s57, s98
	s_cbranch_scc1 .Lrsf_0
	v_lshl_add_u32 v170, s36, 8, v153
	v_ashrrev_i32_e32 v171, 31, v170
	v_or_b32_e32 v166, 16, v170
	v_lshlrev_b64 v[146:147], 6, v[170:171]
	v_ashrrev_i32_e32 v167, 31, v166
	v_lshl_add_u64 v[146:147], v[136:137], 0, v[146:147]
	v_lshlrev_b64 v[148:149], 6, v[166:167]
	v_lshl_add_u64 v[148:149], v[136:137], 0, v[148:149]
	ds_read_b128 v[176:179], v239
	ds_read_b128 v[180:183], v239 offset:1024
	v_or_b32_e32 v162, 32, v170
	v_ashrrev_i32_e32 v163, 31, v162
	v_or_b32_e32 v158, 48, v170
	v_lshlrev_b64 v[146:147], 6, v[162:163]
	v_ashrrev_i32_e32 v159, 31, v158
	v_lshl_add_u64 v[146:147], v[136:137], 0, v[146:147]
	v_lshlrev_b64 v[148:149], 6, v[158:159]
	v_lshl_add_u64 v[148:149], v[136:137], 0, v[148:149]
	ds_read_b128 v[184:187], v239 offset:2048
	ds_read_b128 v[188:191], v239 offset:3072
	v_add_u32_e32 v154, 0x80, v170
	v_ashrrev_i32_e32 v155, 31, v154
	v_add_u32_e32 v150, 0x90, v170
	v_lshlrev_b64 v[146:147], 6, v[154:155]
	v_ashrrev_i32_e32 v151, 31, v150
	v_lshl_add_u64 v[146:147], v[136:137], 0, v[146:147]
	v_lshlrev_b64 v[148:149], 6, v[150:151]
	v_lshl_add_u64 v[148:149], v[136:137], 0, v[148:149]
	ds_read_b128 v[192:195], v239 offset:8192
	ds_read_b128 v[196:199], v239 offset:9216
	v_add_u32_e32 v148, 0xa0, v170
	v_ashrrev_i32_e32 v149, 31, v148
	v_lshlrev_b64 v[146:147], 6, v[148:149]
	v_lshl_add_u64 v[146:147], v[136:137], 0, v[146:147]
	ds_read_b128 v[202:205], v239 offset:10240
	v_add_u32_e32 v146, 0xb0, v170
	v_ashrrev_i32_e32 v147, 31, v146
	v_lshlrev_b64 v[206:207], 6, v[146:147]
	v_lshl_add_u64 v[206:207], v[136:137], 0, v[206:207]
	ds_read_b128 v[206:209], v239 offset:11264
	v_mov_b32_e32 v147, v201
	v_mov_b32_e32 v149, v201
	v_lshlrev_b32_e32 v147, 2, v147
	v_mov_b32_e32 v151, v201
	v_xor_b32_e32 v147, 64, v147
	s_andn2_b64 vcc, exec, s[10:11]
	v_lshlrev_b32_e32 v151, 2, v151
	v_xor_b32_e32 v151, 64, v151
	v_lshlrev_b32_e32 v149, 2, v149
	v_xor_b32_e32 v149, 0x80, v149
	s_mov_b64 s[10:11], -1
	s_waitcnt lgkmcnt(0)
	v_mov_b32_e32 v210, v177
	v_mov_b32_e32 v211, v178
	v_mov_b32_e32 v177, v179
	v_pk_add_f32 v[176:177], v[210:211], v[176:177]
	v_mov_b32_e32 v178, v181
	v_add_f32_e32 v152, v176, v177
	v_mov_b32_e32 v179, v182
	v_mov_b32_e32 v181, v183
	v_mov_b32_e32 v147, v152
	s_nop 1
	v_permlane16_swap_b32_e32 v147, v152
	v_pk_add_f32 v[176:177], v[178:179], v[180:181]
	v_mov_b32_e32 v182, v185
	v_add_f32_e32 v155, v176, v177
	v_mov_b32_e32 v151, v155
	s_nop 1
	v_permlane16_swap_b32_e32 v151, v155
	s_waitcnt lgkmcnt(0)
	v_add_f32_e32 v147, v152, v147
	v_mov_b32_e32 v152, v201
	v_mov_b32_e32 v149, v147
	s_nop 1
	v_permlane32_swap_b32_e32 v149, v147
	s_waitcnt lgkmcnt(0)
	v_add_f32_e32 v151, v155, v151
	v_lshlrev_b32_e32 v152, 2, v152
	v_xor_b32_e32 v152, 0x80, v152
	v_mov_b32_e32 v152, v151
	s_nop 1
	v_permlane32_swap_b32_e32 v152, v151
	s_waitcnt lgkmcnt(0)
	v_add_f32_e32 v147, v147, v149
	v_mov_b32_e32 v149, v201
	v_mov_b32_e32 v183, v186
	v_mov_b32_e32 v185, v187
	v_pk_add_f32 v[178:179], v[182:183], v[184:185]
	v_fmamk_f32 v147, v147, 0x3a800000, v175
	v_lshlrev_b32_e32 v149, 2, v149
	v_add_f32_e32 v156, v178, v179
	v_rsq_f32_e32 v176, v147
	s_waitcnt lgkmcnt(0)
	v_add_f32_e32 v147, v151, v152
	v_xor_b32_e32 v149, 64, v149
	v_mov_b32_e32 v151, v201
	v_mov_b32_e32 v152, v201
	v_mov_b32_e32 v186, v189
	v_mov_b32_e32 v187, v190
	v_mov_b32_e32 v189, v191
	v_mov_b32_e32 v149, v156
	s_nop 1
	v_permlane16_swap_b32_e32 v149, v156
	v_pk_add_f32 v[180:181], v[186:187], v[188:189]
	v_lshlrev_b32_e32 v152, 2, v152
	v_add_f32_e32 v159, v180, v181
	v_xor_b32_e32 v152, 64, v152
	v_mov_b32_e32 v152, v159
	s_nop 1
	v_permlane16_swap_b32_e32 v152, v159
	s_waitcnt lgkmcnt(0)
	v_add_f32_e32 v149, v156, v149
	v_lshlrev_b32_e32 v151, 2, v151
	v_mov_b32_e32 v156, v201
	v_xor_b32_e32 v151, 0x80, v151
	v_mov_b32_e32 v151, v149
	s_nop 1
	v_permlane32_swap_b32_e32 v151, v149
	v_lshlrev_b32_e32 v156, 2, v156
	s_waitcnt lgkmcnt(0)
	v_add_f32_e32 v152, v159, v152
	v_xor_b32_e32 v156, 0x80, v156
	v_mov_b32_e32 v156, v152
	s_nop 1
	v_permlane32_swap_b32_e32 v156, v152
	v_fmamk_f32 v147, v147, 0x3a800000, v175
	v_rsq_f32_e32 v174, v147
	s_waitcnt lgkmcnt(0)
	v_add_f32_e32 v147, v149, v151
	v_mov_b32_e32 v149, v201
	v_mov_b32_e32 v190, v193
	v_mov_b32_e32 v191, v194
	v_mov_b32_e32 v193, v195
	v_fmamk_f32 v147, v147, 0x3a800000, v175
	v_pk_add_f32 v[182:183], v[190:191], v[192:193]
	v_rsq_f32_e32 v172, v147
	s_waitcnt lgkmcnt(0)
	v_add_f32_e32 v147, v152, v156
	v_lshlrev_b32_e32 v149, 2, v149
	v_mov_b32_e32 v151, v201
	v_mov_b32_e32 v152, v201
	v_mov_b32_e32 v194, v197
	v_mov_b32_e32 v195, v198
	v_mov_b32_e32 v197, v199
	v_add_f32_e32 v160, v182, v183
	v_xor_b32_e32 v149, 64, v149
	v_pk_add_f32 v[184:185], v[194:195], v[196:197]
	v_mov_b32_e32 v149, v160
	s_nop 1
	v_permlane16_swap_b32_e32 v149, v160
	v_lshlrev_b32_e32 v152, 2, v152
	v_add_f32_e32 v163, v184, v185
	v_xor_b32_e32 v152, 64, v152
	v_mov_b32_e32 v152, v163
	s_nop 1
	v_permlane16_swap_b32_e32 v152, v163
	v_lshlrev_b32_e32 v151, 2, v151
	v_mov_b32_e32 v156, v201
	s_waitcnt lgkmcnt(0)
	v_add_f32_e32 v149, v160, v149
	v_xor_b32_e32 v151, 0x80, v151
	v_mov_b32_e32 v151, v149
	s_nop 1
	v_permlane32_swap_b32_e32 v151, v149
	v_lshlrev_b32_e32 v156, 2, v156
	s_waitcnt lgkmcnt(0)
	v_add_f32_e32 v152, v163, v152
	v_xor_b32_e32 v156, 0x80, v156
	v_mov_b32_e32 v156, v152
	s_nop 1
	v_permlane32_swap_b32_e32 v156, v152
	v_fmamk_f32 v147, v147, 0x3a800000, v175
	v_rsq_f32_e32 v168, v147
	s_waitcnt lgkmcnt(0)
	v_add_f32_e32 v147, v149, v151
	v_fmamk_f32 v147, v147, 0x3a800000, v175
	v_rsq_f32_e32 v164, v147
	s_waitcnt lgkmcnt(0)
; __device__ __forceinline__ float row_finish(float t) { t += shx(t, 16); t += shx(t, 32); return __builtin_amdgcn_rsqf(t * (1.0f / 1024.0f) + RMS_EPS); }
; __device__ __forceinline__ u32x4 pack8(f32x4 a, f32x4 b) { u32x4 w; w.x = cvt_pk_bf16(a[0], a[1]); w.y = cvt_pk_bf16(a[2], a[3]); w.z = cvt_pk_bf16(b[0], b[1]); w.w = cvt_pk_bf16(b[2], b[3]); return w; }
; __device__ __forceinline__ float silu_f(float v) { return v * __builtin_amdgcn_rcpf(1.0f + __builtin_amdgcn_exp2f(v * -1.4426950408889634f)); }
; __device__ __forceinline__ f32x4 silu4(f32x4 v) { return (f32x4){silu_f(v[0]), silu_f(v[1]), silu_f(v[2]), silu_f(v[3])}; }
;     __device__ __forceinline__ void operator()(const f32x4 (&acc)[2][2][4][2], const Unit& u, int wr, int wc, int fr, int fq) const {
;     ...
;         for (int ai = 0; ai < 2; ++ai)
; #pragma unroll
;             for (int m = 0; m < 4; ++m) rs[ai][m] = row_finish(rs[ai][m]);
; #pragma unroll
;         for (int ai = 0; ai < 2; ++ai)
; #pragma unroll
;             for (int m = 0; m < 4; ++m) {
;                 const int row = u.pm * BM + ai * HALF + wr * 64 + m * 16 + fr;
;                 const float rstd = rs[ai][m];
;                 const f32x4 a0 = silu4(acc[ai][0][m][0] * rstd) * (acc[ai][1][m][0] * rstd);
;                 const f32x4 a1 = silu4(acc[ai][0][m][1] * rstd) * (acc[ai][1][m][1] * rstd);
;                 *(u32x4*)(ACT + (size_t)row * 2816 + col0) = pack8(a0, a1);
	v_add_f32_e32 v147, v152, v156
	v_mov_b32_e32 v149, v201
	v_mov_b32_e32 v151, v201
	v_mov_b32_e32 v152, v201
	v_mov_b32_e32 v198, v203
	v_mov_b32_e32 v199, v204
	v_mov_b32_e32 v203, v205
	v_mov_b32_e32 v204, v207
	v_mov_b32_e32 v205, v208
	v_mov_b32_e32 v207, v209
	v_pk_add_f32 v[188:189], v[204:205], v[206:207]
	v_lshlrev_b32_e32 v152, 2, v152
	v_pk_add_f32 v[186:187], v[198:199], v[202:203]
	v_add_f32_e32 v155, v188, v189
	v_lshlrev_b32_e32 v149, 2, v149
	v_xor_b32_e32 v152, 64, v152
	v_add_f32_e32 v167, v186, v187
	v_xor_b32_e32 v149, 64, v149
	v_mov_b32_e32 v152, v155
	s_nop 1
	v_permlane16_swap_b32_e32 v152, v155
	v_mov_b32_e32 v149, v167
	s_nop 1
	v_permlane16_swap_b32_e32 v149, v167
	v_lshlrev_b32_e32 v151, 2, v151
	v_xor_b32_e32 v151, 0x80, v151
	v_fmamk_f32 v147, v147, 0x3a800000, v175
	s_waitcnt lgkmcnt(0)
	v_add_f32_e32 v152, v155, v152
	v_mov_b32_e32 v155, v201
	s_waitcnt lgkmcnt(0)
	v_add_f32_e32 v149, v167, v149
	v_mov_b32_e32 v151, v149
	s_nop 1
	v_permlane32_swap_b32_e32 v151, v149
	v_lshlrev_b32_e32 v155, 2, v155
	v_xor_b32_e32 v155, 0x80, v155
	v_mov_b32_e32 v155, v152
	s_nop 1
	v_permlane32_swap_b32_e32 v155, v152
	v_rsq_f32_e32 v160, v147
	s_waitcnt lgkmcnt(0)
	v_add_f32_e32 v147, v149, v151
	v_fmamk_f32 v147, v147, 0x3a800000, v175
	v_rsq_f32_e32 v156, v147
	s_waitcnt lgkmcnt(0)
	v_add_f32_e32 v147, v152, v155
	v_fmamk_f32 v147, v147, 0x3a800000, v175
	v_pk_mul_f32 v[124:125], v[124:125], v[176:177] op_sel_hi:[1,0]
	v_rsq_f32_e32 v152, v147
	v_lshlrev_b32_e32 v251, 5, v153
	v_add_u32_e32 v251, 0x24080, v251
	ds_write_b32 v251, v176
	ds_write_b32 v251, v174 offset:4
	ds_write_b32 v251, v172 offset:8
	ds_write_b32 v251, v168 offset:12
	ds_write_b32 v251, v164 offset:16
	ds_write_b32 v251, v160 offset:20
	ds_write_b32 v251, v156 offset:24
	ds_write_b32 v251, v152 offset:28
	s_branch .Lrsj_0
.Lrsf_0:
	v_lshlrev_b32_e32 v251, 5, v153
	v_add_u32_e32 v251, 0x24080, v251
	ds_read_b32 v176, v251
	ds_read_b32 v174, v251 offset:4
	ds_read_b32 v172, v251 offset:8
	ds_read_b32 v168, v251 offset:12
	ds_read_b32 v164, v251 offset:16
	ds_read_b32 v160, v251 offset:20
	ds_read_b32 v156, v251 offset:24
	ds_read_b32 v152, v251 offset:28
	s_waitcnt lgkmcnt(0)
	v_lshl_add_u32 v170, s36, 8, v153
	v_or_b32_e32 v166, 16, v170
	v_or_b32_e32 v162, 32, v170
	v_or_b32_e32 v158, 48, v170
	v_add_u32_e32 v154, 0x80, v170
	v_add_u32_e32 v150, 0x90, v170
	v_add_u32_e32 v148, 0xa0, v170
	v_add_u32_e32 v146, 0xb0, v170
	s_andn2_b64 vcc, exec, s[10:11]
	s_mov_b64 s[10:11], -1
	s_waitcnt lgkmcnt(0)
	s_waitcnt lgkmcnt(0)
	s_waitcnt lgkmcnt(0)
	s_waitcnt lgkmcnt(0)
	s_waitcnt lgkmcnt(0)
	s_waitcnt lgkmcnt(0)
	s_waitcnt lgkmcnt(0)
	s_waitcnt lgkmcnt(0)
	s_waitcnt lgkmcnt(0)
	s_waitcnt lgkmcnt(0)
	s_waitcnt lgkmcnt(0)
	s_waitcnt lgkmcnt(0)
	s_waitcnt lgkmcnt(0)
	s_waitcnt lgkmcnt(0)
	s_waitcnt lgkmcnt(0)
	s_waitcnt lgkmcnt(0)
	s_waitcnt lgkmcnt(0)
	v_pk_mul_f32 v[124:125], v[124:125], v[176:177] op_sel_hi:[1,0]
.Lrsj_0:
	v_mul_f32_e32 v147, 0xbfb8aa3b, v124
	v_exp_f32_e32 v147, v147
	v_mul_f32_e32 v149, 0xbfb8aa3b, v125
	v_exp_f32_e32 v149, v149
	v_pk_mul_f32 v[126:127], v[126:127], v[176:177] op_sel_hi:[1,0]
	v_add_f32_e32 v147, 1.0, v147
	v_rcp_f32_e32 v178, v147
	v_add_f32_e32 v147, 1.0, v149
	v_mul_f32_e32 v149, 0xbfb8aa3b, v126
	v_exp_f32_e32 v149, v149
	v_mul_f32_e32 v151, 0xbfb8aa3b, v127
	v_exp_f32_e32 v151, v151
	v_rcp_f32_e32 v179, v147
	v_add_f32_e32 v147, 1.0, v149
	v_rcp_f32_e32 v180, v147
	v_add_f32_e32 v147, 1.0, v151
	v_pk_mul_f32 v[120:121], v[120:121], v[176:177] op_sel_hi:[1,0]
	v_rcp_f32_e32 v181, v147
	v_mul_f32_e32 v147, 0xbfb8aa3b, v120
	v_exp_f32_e32 v147, v147
	v_mul_f32_e32 v149, 0xbfb8aa3b, v121
	v_exp_f32_e32 v149, v149
	v_pk_mul_f32 v[122:123], v[122:123], v[176:177] op_sel_hi:[1,0]
	v_add_f32_e32 v147, 1.0, v147
	v_pk_mul_f32 v[124:125], v[124:125], v[178:179]
	v_rcp_f32_e32 v178, v147
	v_add_f32_e32 v147, 1.0, v149
	v_mul_f32_e32 v149, 0xbfb8aa3b, v122
	v_exp_f32_e32 v149, v149
	v_mul_f32_e32 v151, 0xbfb8aa3b, v123
	v_exp_f32_e32 v151, v151
	v_rcp_f32_e32 v179, v147
	v_add_f32_e32 v147, 1.0, v149
	v_pk_mul_f32 v[126:127], v[126:127], v[180:181]
	v_rcp_f32_e32 v180, v147
	v_add_f32_e32 v147, 1.0, v151
	v_rcp_f32_e32 v181, v147
	v_pk_mul_f32 v[116:117], v[116:117], v[176:177] op_sel_hi:[1,0]
	v_pk_mul_f32 v[118:119], v[118:119], v[176:177] op_sel_hi:[1,0]
	v_pk_mul_f32 v[120:121], v[120:121], v[178:179]
	v_pk_mul_f32 v[112:113], v[112:113], v[176:177] op_sel_hi:[1,0]
	v_lshl_or_b32 v182, s57, 7, v161
	v_pk_mul_f32 v[118:119], v[118:119], v[126:127]
	v_pk_mul_f32 v[116:117], v[116:117], v[124:125]
	v_pk_mul_f32 v[122:123], v[122:123], v[180:181]
	v_pk_mul_f32 v[114:115], v[114:115], v[176:177] op_sel_hi:[1,0]
	v_pk_mul_f32 v[112:113], v[112:113], v[120:121]
	v_ashrrev_i32_e32 v183, 31, v182
	v_pk_mul_f32 v[114:115], v[114:115], v[122:123]
	v_cvt_pk_bf16_f32 v116, v116, v117
	v_cvt_pk_bf16_f32 v117, v118, v119
	v_cvt_pk_bf16_f32 v118, v112, v113
	v_mov_b64_e32 v[112:113], s[14:15]
	v_cvt_pk_bf16_f32 v119, v114, v115
	v_mad_i64_i32 v[120:121], s[38:39], v170, s56, v[112:113]
	v_lshlrev_b64 v[114:115], 1, v[182:183]
	v_pk_mul_f32 v[108:109], v[108:109], v[174:175] op_sel_hi:[1,0]
	v_pk_mul_f32 v[110:111], v[110:111], v[174:175] op_sel_hi:[1,0]
	v_mul_f32_e32 v122, 0xbfb8aa3b, v108
	v_mul_f32_e32 v123, 0xbfb8aa3b, v109
	v_lshl_add_u64 v[120:121], v[120:121], 0, v[114:115]
	v_pk_mul_f32 v[104:105], v[104:105], v[174:175] op_sel_hi:[1,0]
	v_pk_mul_f32 v[106:107], v[106:107], v[174:175] op_sel_hi:[1,0]
	v_exp_f32_e32 v122, v122
	v_exp_f32_e32 v123, v123
	v_mul_f32_e32 v124, 0xbfb8aa3b, v110
	v_mul_f32_e32 v125, 0xbfb8aa3b, v111
; __device__ __forceinline__ u32x4 pack8(f32x4 a, f32x4 b) { u32x4 w; w.x = cvt_pk_bf16(a[0], a[1]); w.y = cvt_pk_bf16(a[2], a[3]); w.z = cvt_pk_bf16(b[0], b[1]); w.w = cvt_pk_bf16(b[2], b[3]); return w; }
; __device__ __forceinline__ float silu_f(float v) { return v * __builtin_amdgcn_rcpf(1.0f + __builtin_amdgcn_exp2f(v * -1.4426950408889634f)); }
; __device__ __forceinline__ f32x4 silu4(f32x4 v) { return (f32x4){silu_f(v[0]), silu_f(v[1]), silu_f(v[2]), silu_f(v[3])}; }
;     __device__ __forceinline__ void operator()(const f32x4 (&acc)[2][2][4][2], const Unit& u, int wr, int wc, int fr, int fq) const {
;     ...
;         for (int ai = 0; ai < 2; ++ai)
; #pragma unroll
;             for (int m = 0; m < 4; ++m) {
;                 const int row = u.pm * BM + ai * HALF + wr * 64 + m * 16 + fr;
;                 const float rstd = rs[ai][m];
;                 const f32x4 a0 = silu4(acc[ai][0][m][0] * rstd) * (acc[ai][1][m][0] * rstd);
;                 const f32x4 a1 = silu4(acc[ai][0][m][1] * rstd) * (acc[ai][1][m][1] * rstd);
;                 *(u32x4*)(ACT + (size_t)row * 2816 + col0) = pack8(a0, a1);
	global_store_dwordx4 v[120:121], v[116:119], off
	v_exp_f32_e32 v124, v124
	v_exp_f32_e32 v125, v125
	v_mul_f32_e32 v116, 0xbfb8aa3b, v104
	v_mul_f32_e32 v117, 0xbfb8aa3b, v105
	v_mul_f32_e32 v118, 0xbfb8aa3b, v106
	v_mul_f32_e32 v119, 0xbfb8aa3b, v107
	v_exp_f32_e32 v116, v116
	v_exp_f32_e32 v117, v117
	v_exp_f32_e32 v118, v118
	v_exp_f32_e32 v119, v119
	v_add_f32_e32 v122, 1.0, v122
	v_add_f32_e32 v123, 1.0, v123
	v_rcp_f32_e32 v122, v122
	v_rcp_f32_e32 v123, v123
	v_add_f32_e32 v124, 1.0, v124
	v_add_f32_e32 v125, 1.0, v125
	v_add_f32_e32 v116, 1.0, v116
	v_add_f32_e32 v117, 1.0, v117
	v_add_f32_e32 v118, 1.0, v118
	v_add_f32_e32 v119, 1.0, v119
	v_rcp_f32_e32 v124, v124
	v_rcp_f32_e32 v125, v125
	v_rcp_f32_e32 v116, v116
	v_rcp_f32_e32 v117, v117
	v_rcp_f32_e32 v118, v118
	v_rcp_f32_e32 v119, v119
	v_pk_mul_f32 v[108:109], v[108:109], v[122:123]
	v_pk_mul_f32 v[100:101], v[100:101], v[174:175] op_sel_hi:[1,0]
	v_pk_mul_f32 v[110:111], v[110:111], v[124:125]
	v_pk_mul_f32 v[102:103], v[102:103], v[174:175] op_sel_hi:[1,0]
	v_pk_mul_f32 v[100:101], v[100:101], v[108:109]
	v_pk_mul_f32 v[104:105], v[104:105], v[116:117]
	v_pk_mul_f32 v[106:107], v[106:107], v[118:119]
	v_pk_mul_f32 v[96:97], v[96:97], v[174:175] op_sel_hi:[1,0]
	v_pk_mul_f32 v[98:99], v[98:99], v[174:175] op_sel_hi:[1,0]
	v_pk_mul_f32 v[102:103], v[102:103], v[110:111]
	v_pk_mul_f32 v[106:107], v[98:99], v[106:107]
	v_pk_mul_f32 v[98:99], v[96:97], v[104:105]
	v_cvt_pk_bf16_f32 v96, v100, v101
	v_mad_i64_i32 v[100:101], s[38:39], v166, s56, v[112:113]
	v_pk_mul_f32 v[92:93], v[92:93], v[172:173] op_sel_hi:[1,0]
	v_cvt_pk_bf16_f32 v97, v102, v103
	v_cvt_pk_bf16_f32 v98, v98, v99
	v_cvt_pk_bf16_f32 v99, v106, v107
	v_pk_mul_f32 v[94:95], v[94:95], v[172:173] op_sel_hi:[1,0]
	v_mul_f32_e32 v102, 0xbfb8aa3b, v92
	v_mul_f32_e32 v103, 0xbfb8aa3b, v93
	v_lshl_add_u64 v[100:101], v[100:101], 0, v[114:115]
	v_pk_mul_f32 v[88:89], v[88:89], v[172:173] op_sel_hi:[1,0]
	v_pk_mul_f32 v[90:91], v[90:91], v[172:173] op_sel_hi:[1,0]
	v_exp_f32_e32 v102, v102
	v_exp_f32_e32 v103, v103
	v_mul_f32_e32 v104, 0xbfb8aa3b, v94
	v_mul_f32_e32 v105, 0xbfb8aa3b, v95
	global_store_dwordx4 v[100:101], v[96:99], off
	v_exp_f32_e32 v104, v104
	v_exp_f32_e32 v105, v105
	v_mul_f32_e32 v96, 0xbfb8aa3b, v88
	v_mul_f32_e32 v97, 0xbfb8aa3b, v89
	v_mul_f32_e32 v98, 0xbfb8aa3b, v90
	v_mul_f32_e32 v99, 0xbfb8aa3b, v91
	v_exp_f32_e32 v96, v96
	v_exp_f32_e32 v97, v97
	v_exp_f32_e32 v98, v98
	v_exp_f32_e32 v99, v99
	v_add_f32_e32 v102, 1.0, v102
	v_add_f32_e32 v103, 1.0, v103
	v_rcp_f32_e32 v102, v102
	v_rcp_f32_e32 v103, v103
	v_add_f32_e32 v104, 1.0, v104
	v_add_f32_e32 v105, 1.0, v105
	v_add_f32_e32 v96, 1.0, v96
	v_add_f32_e32 v97, 1.0, v97
	v_add_f32_e32 v98, 1.0, v98
	v_add_f32_e32 v99, 1.0, v99
	v_rcp_f32_e32 v104, v104
	v_rcp_f32_e32 v105, v105
	v_rcp_f32_e32 v96, v96
	v_rcp_f32_e32 v97, v97
	v_rcp_f32_e32 v98, v98
	v_rcp_f32_e32 v99, v99
	v_pk_mul_f32 v[92:93], v[92:93], v[102:103]
	v_pk_mul_f32 v[84:85], v[84:85], v[172:173] op_sel_hi:[1,0]
	v_pk_mul_f32 v[94:95], v[94:95], v[104:105]
	v_pk_mul_f32 v[86:87], v[86:87], v[172:173] op_sel_hi:[1,0]
	v_pk_mul_f32 v[84:85], v[84:85], v[92:93]
	v_pk_mul_f32 v[88:89], v[88:89], v[96:97]
	v_pk_mul_f32 v[90:91], v[90:91], v[98:99]
	v_pk_mul_f32 v[80:81], v[80:81], v[172:173] op_sel_hi:[1,0]
	v_pk_mul_f32 v[82:83], v[82:83], v[172:173] op_sel_hi:[1,0]
	v_pk_mul_f32 v[86:87], v[86:87], v[94:95]
	v_pk_mul_f32 v[90:91], v[82:83], v[90:91]
	v_pk_mul_f32 v[82:83], v[80:81], v[88:89]
	v_cvt_pk_bf16_f32 v80, v84, v85
	v_mad_i64_i32 v[84:85], s[38:39], v162, s56, v[112:113]
	v_pk_mul_f32 v[76:77], v[76:77], v[168:169] op_sel_hi:[1,0]
	v_cvt_pk_bf16_f32 v81, v86, v87
	v_cvt_pk_bf16_f32 v82, v82, v83
	v_cvt_pk_bf16_f32 v83, v90, v91
	v_pk_mul_f32 v[78:79], v[78:79], v[168:169] op_sel_hi:[1,0]
	v_mul_f32_e32 v86, 0xbfb8aa3b, v76
	v_mul_f32_e32 v87, 0xbfb8aa3b, v77
	v_lshl_add_u64 v[84:85], v[84:85], 0, v[114:115]
	v_pk_mul_f32 v[72:73], v[72:73], v[168:169] op_sel_hi:[1,0]
	v_pk_mul_f32 v[74:75], v[74:75], v[168:169] op_sel_hi:[1,0]
	v_exp_f32_e32 v86, v86
	v_exp_f32_e32 v87, v87
	v_mul_f32_e32 v88, 0xbfb8aa3b, v78
	v_mul_f32_e32 v89, 0xbfb8aa3b, v79
	global_store_dwordx4 v[84:85], v[80:83], off
	v_exp_f32_e32 v88, v88
	v_exp_f32_e32 v89, v89
	v_mul_f32_e32 v80, 0xbfb8aa3b, v72
	v_mul_f32_e32 v81, 0xbfb8aa3b, v73
	v_mul_f32_e32 v82, 0xbfb8aa3b, v74
	v_mul_f32_e32 v83, 0xbfb8aa3b, v75
	v_exp_f32_e32 v80, v80
	v_exp_f32_e32 v81, v81
	v_exp_f32_e32 v82, v82
	v_exp_f32_e32 v83, v83
	v_add_f32_e32 v86, 1.0, v86
	v_add_f32_e32 v87, 1.0, v87
	v_rcp_f32_e32 v86, v86
	v_rcp_f32_e32 v87, v87
	v_add_f32_e32 v88, 1.0, v88
	v_add_f32_e32 v89, 1.0, v89
	v_add_f32_e32 v80, 1.0, v80
	v_add_f32_e32 v81, 1.0, v81
	v_add_f32_e32 v82, 1.0, v82
	v_add_f32_e32 v83, 1.0, v83
	v_rcp_f32_e32 v88, v88
	v_rcp_f32_e32 v89, v89
	v_rcp_f32_e32 v80, v80
	v_rcp_f32_e32 v81, v81
	v_rcp_f32_e32 v82, v82
	v_rcp_f32_e32 v83, v83
	v_pk_mul_f32 v[76:77], v[76:77], v[86:87]
	v_pk_mul_f32 v[68:69], v[68:69], v[168:169] op_sel_hi:[1,0]
	v_pk_mul_f32 v[78:79], v[78:79], v[88:89]
	v_pk_mul_f32 v[70:71], v[70:71], v[168:169] op_sel_hi:[1,0]
	v_pk_mul_f32 v[68:69], v[68:69], v[76:77]
	v_pk_mul_f32 v[72:73], v[72:73], v[80:81]
	v_pk_mul_f32 v[74:75], v[74:75], v[82:83]
	v_pk_mul_f32 v[64:65], v[64:65], v[168:169] op_sel_hi:[1,0]
	v_pk_mul_f32 v[66:67], v[66:67], v[168:169] op_sel_hi:[1,0]
	v_pk_mul_f32 v[70:71], v[70:71], v[78:79]
	v_pk_mul_f32 v[74:75], v[66:67], v[74:75]
	v_pk_mul_f32 v[66:67], v[64:65], v[72:73]
	v_cvt_pk_bf16_f32 v64, v68, v69
	v_mad_i64_i32 v[68:69], s[38:39], v158, s56, v[112:113]
; __device__ __forceinline__ u32x4 pack8(f32x4 a, f32x4 b) { u32x4 w; w.x = cvt_pk_bf16(a[0], a[1]); w.y = cvt_pk_bf16(a[2], a[3]); w.z = cvt_pk_bf16(b[0], b[1]); w.w = cvt_pk_bf16(b[2], b[3]); return w; }
; __device__ __forceinline__ float silu_f(float v) { return v * __builtin_amdgcn_rcpf(1.0f + __builtin_amdgcn_exp2f(v * -1.4426950408889634f)); }
; __device__ __forceinline__ f32x4 silu4(f32x4 v) { return (f32x4){silu_f(v[0]), silu_f(v[1]), silu_f(v[2]), silu_f(v[3])}; }
;     __device__ __forceinline__ void operator()(const f32x4 (&acc)[2][2][4][2], const Unit& u, int wr, int wc, int fr, int fq) const {
;     ...
;         for (int ai = 0; ai < 2; ++ai)
; #pragma unroll
;             for (int m = 0; m < 4; ++m) {
;                 const int row = u.pm * BM + ai * HALF + wr * 64 + m * 16 + fr;
;                 const float rstd = rs[ai][m];
;                 const f32x4 a0 = silu4(acc[ai][0][m][0] * rstd) * (acc[ai][1][m][0] * rstd);
;                 const f32x4 a1 = silu4(acc[ai][0][m][1] * rstd) * (acc[ai][1][m][1] * rstd);
;                 *(u32x4*)(ACT + (size_t)row * 2816 + col0) = pack8(a0, a1);
	v_pk_mul_f32 v[60:61], v[60:61], v[164:165] op_sel_hi:[1,0]
	v_cvt_pk_bf16_f32 v65, v70, v71
	v_cvt_pk_bf16_f32 v66, v66, v67
	v_cvt_pk_bf16_f32 v67, v74, v75
	v_pk_mul_f32 v[62:63], v[62:63], v[164:165] op_sel_hi:[1,0]
	v_mul_f32_e32 v70, 0xbfb8aa3b, v60
	v_mul_f32_e32 v71, 0xbfb8aa3b, v61
	v_lshl_add_u64 v[68:69], v[68:69], 0, v[114:115]
	v_pk_mul_f32 v[56:57], v[56:57], v[164:165] op_sel_hi:[1,0]
	v_pk_mul_f32 v[58:59], v[58:59], v[164:165] op_sel_hi:[1,0]
	v_exp_f32_e32 v70, v70
	v_exp_f32_e32 v71, v71
	v_mul_f32_e32 v72, 0xbfb8aa3b, v62
	v_mul_f32_e32 v73, 0xbfb8aa3b, v63
	global_store_dwordx4 v[68:69], v[64:67], off
	v_exp_f32_e32 v72, v72
	v_exp_f32_e32 v73, v73
	v_mul_f32_e32 v64, 0xbfb8aa3b, v56
	v_mul_f32_e32 v65, 0xbfb8aa3b, v57
	v_mul_f32_e32 v66, 0xbfb8aa3b, v58
	v_mul_f32_e32 v67, 0xbfb8aa3b, v59
	v_exp_f32_e32 v64, v64
	v_exp_f32_e32 v65, v65
	v_exp_f32_e32 v66, v66
	v_exp_f32_e32 v67, v67
	v_add_f32_e32 v70, 1.0, v70
	v_add_f32_e32 v71, 1.0, v71
	v_rcp_f32_e32 v70, v70
	v_rcp_f32_e32 v71, v71
	v_add_f32_e32 v72, 1.0, v72
	v_add_f32_e32 v73, 1.0, v73
	v_add_f32_e32 v64, 1.0, v64
	v_add_f32_e32 v65, 1.0, v65
	v_add_f32_e32 v66, 1.0, v66
	v_add_f32_e32 v67, 1.0, v67
	v_rcp_f32_e32 v72, v72
	v_rcp_f32_e32 v73, v73
	v_rcp_f32_e32 v64, v64
	v_rcp_f32_e32 v65, v65
	v_rcp_f32_e32 v66, v66
	v_rcp_f32_e32 v67, v67
	v_pk_mul_f32 v[60:61], v[60:61], v[70:71]
	v_pk_mul_f32 v[52:53], v[52:53], v[164:165] op_sel_hi:[1,0]
	v_pk_mul_f32 v[62:63], v[62:63], v[72:73]
	v_pk_mul_f32 v[54:55], v[54:55], v[164:165] op_sel_hi:[1,0]
	v_pk_mul_f32 v[52:53], v[52:53], v[60:61]
	v_pk_mul_f32 v[56:57], v[56:57], v[64:65]
	v_pk_mul_f32 v[58:59], v[58:59], v[66:67]
	v_pk_mul_f32 v[48:49], v[48:49], v[164:165] op_sel_hi:[1,0]
	v_pk_mul_f32 v[50:51], v[50:51], v[164:165] op_sel_hi:[1,0]
	v_pk_mul_f32 v[54:55], v[54:55], v[62:63]
	v_pk_mul_f32 v[58:59], v[50:51], v[58:59]
	v_pk_mul_f32 v[50:51], v[48:49], v[56:57]
	v_cvt_pk_bf16_f32 v48, v52, v53
	v_mad_i64_i32 v[52:53], s[38:39], v154, s56, v[112:113]
	v_pk_mul_f32 v[44:45], v[44:45], v[160:161] op_sel_hi:[1,0]
	v_cvt_pk_bf16_f32 v49, v54, v55
	v_cvt_pk_bf16_f32 v50, v50, v51
	v_cvt_pk_bf16_f32 v51, v58, v59
	v_pk_mul_f32 v[46:47], v[46:47], v[160:161] op_sel_hi:[1,0]
	v_mul_f32_e32 v54, 0xbfb8aa3b, v44
	v_mul_f32_e32 v55, 0xbfb8aa3b, v45
	v_lshl_add_u64 v[52:53], v[52:53], 0, v[114:115]
	v_pk_mul_f32 v[40:41], v[40:41], v[160:161] op_sel_hi:[1,0]
	v_pk_mul_f32 v[42:43], v[42:43], v[160:161] op_sel_hi:[1,0]
	v_exp_f32_e32 v54, v54
	v_exp_f32_e32 v55, v55
	v_mul_f32_e32 v56, 0xbfb8aa3b, v46
	v_mul_f32_e32 v57, 0xbfb8aa3b, v47
	global_store_dwordx4 v[52:53], v[48:51], off
	v_exp_f32_e32 v56, v56
	v_exp_f32_e32 v57, v57
	v_mul_f32_e32 v48, 0xbfb8aa3b, v40
	v_mul_f32_e32 v49, 0xbfb8aa3b, v41
	v_mul_f32_e32 v50, 0xbfb8aa3b, v42
	v_mul_f32_e32 v51, 0xbfb8aa3b, v43
	v_exp_f32_e32 v48, v48
	v_exp_f32_e32 v49, v49
	v_exp_f32_e32 v50, v50
	v_exp_f32_e32 v51, v51
	v_add_f32_e32 v54, 1.0, v54
	v_add_f32_e32 v55, 1.0, v55
	v_rcp_f32_e32 v54, v54
	v_rcp_f32_e32 v55, v55
	v_add_f32_e32 v56, 1.0, v56
	v_add_f32_e32 v57, 1.0, v57
	v_add_f32_e32 v48, 1.0, v48
	v_add_f32_e32 v49, 1.0, v49
	v_add_f32_e32 v50, 1.0, v50
	v_add_f32_e32 v51, 1.0, v51
	v_rcp_f32_e32 v56, v56
	v_rcp_f32_e32 v57, v57
	v_rcp_f32_e32 v48, v48
	v_rcp_f32_e32 v49, v49
	v_rcp_f32_e32 v50, v50
	v_rcp_f32_e32 v51, v51
	v_pk_mul_f32 v[44:45], v[44:45], v[54:55]
	v_pk_mul_f32 v[36:37], v[36:37], v[160:161] op_sel_hi:[1,0]
	v_pk_mul_f32 v[46:47], v[46:47], v[56:57]
	v_pk_mul_f32 v[38:39], v[38:39], v[160:161] op_sel_hi:[1,0]
	v_pk_mul_f32 v[36:37], v[36:37], v[44:45]
	v_pk_mul_f32 v[40:41], v[40:41], v[48:49]
	v_pk_mul_f32 v[42:43], v[42:43], v[50:51]
	v_pk_mul_f32 v[32:33], v[32:33], v[160:161] op_sel_hi:[1,0]
	v_pk_mul_f32 v[34:35], v[34:35], v[160:161] op_sel_hi:[1,0]
	v_pk_mul_f32 v[38:39], v[38:39], v[46:47]
	v_pk_mul_f32 v[42:43], v[34:35], v[42:43]
	v_pk_mul_f32 v[34:35], v[32:33], v[40:41]
	v_cvt_pk_bf16_f32 v32, v36, v37
	v_mad_i64_i32 v[36:37], s[38:39], v150, s56, v[112:113]
	v_pk_mul_f32 v[28:29], v[28:29], v[156:157] op_sel_hi:[1,0]
	v_cvt_pk_bf16_f32 v33, v38, v39
	v_cvt_pk_bf16_f32 v34, v34, v35
; __device__ __forceinline__ unsigned cvt_pk_bf16(float lo, float hi) { unsigned r; asm volatile("v_cvt_pk_bf16_f32 %0, %1, %2" : "=v"(r) : "v"(lo), "v"(hi)); return r; }
; __device__ __forceinline__ float silu_f(float v) { return v * __builtin_amdgcn_rcpf(1.0f + __builtin_amdgcn_exp2f(v * -1.4426950408889634f)); }
; __device__ __forceinline__ f32x4 silu4(f32x4 v) { return (f32x4){silu_f(v[0]), silu_f(v[1]), silu_f(v[2]), silu_f(v[3])}; }
; __device__ __forceinline__ float sq4(f32x4 v) { return (v[0] * v[0] + v[1] * v[1]) + (v[2] * v[2] + v[3] * v[3]); }
; __device__ __forceinline__ u32x4 pack8(f32x4 a, f32x4 b) { u32x4 w; w.x = cvt_pk_bf16(a[0], a[1]); w.y = cvt_pk_bf16(a[2], a[3]); w.z = cvt_pk_bf16(b[0], b[1]); w.w = cvt_pk_bf16(b[2], b[3]); return w; }
;     __device__ __forceinline__ void operator()(const f32x4 (&acc)[2][2][4][2], const Unit& u, int wr, int wc, int fr, int fq) const {
;     ...
;         for (int ai = 0; ai < 2; ++ai)
; #pragma unroll
;             for (int m = 0; m < 4; ++m) {
;                 const int row = u.pm * BM + ai * HALF + wr * 64 + m * 16 + fr;
;                 const float rstd = rs[ai][m];
;                 const f32x4 a0 = silu4(acc[ai][0][m][0] * rstd) * (acc[ai][1][m][0] * rstd);
;                 const f32x4 a1 = silu4(acc[ai][0][m][1] * rstd) * (acc[ai][1][m][1] * rstd);
;                 *(u32x4*)(ACT + (size_t)row * 2816 + col0) = pack8(a0, a1);
;             }
	v_cvt_pk_bf16_f32 v35, v42, v43
	v_pk_mul_f32 v[30:31], v[30:31], v[156:157] op_sel_hi:[1,0]
	v_mul_f32_e32 v38, 0xbfb8aa3b, v28
	v_mul_f32_e32 v39, 0xbfb8aa3b, v29
	v_lshl_add_u64 v[36:37], v[36:37], 0, v[114:115]
	v_pk_mul_f32 v[24:25], v[24:25], v[156:157] op_sel_hi:[1,0]
	v_pk_mul_f32 v[26:27], v[26:27], v[156:157] op_sel_hi:[1,0]
	v_exp_f32_e32 v38, v38
	v_exp_f32_e32 v39, v39
	v_mul_f32_e32 v40, 0xbfb8aa3b, v30
	v_mul_f32_e32 v41, 0xbfb8aa3b, v31
	global_store_dwordx4 v[36:37], v[32:35], off
	v_exp_f32_e32 v40, v40
	v_exp_f32_e32 v41, v41
	v_mul_f32_e32 v32, 0xbfb8aa3b, v24
	v_mul_f32_e32 v33, 0xbfb8aa3b, v25
	v_mul_f32_e32 v34, 0xbfb8aa3b, v26
	v_mul_f32_e32 v35, 0xbfb8aa3b, v27
	v_exp_f32_e32 v32, v32
	v_exp_f32_e32 v33, v33
	v_exp_f32_e32 v34, v34
	v_exp_f32_e32 v35, v35
	v_add_f32_e32 v38, 1.0, v38
	v_add_f32_e32 v39, 1.0, v39
	v_rcp_f32_e32 v38, v38
	v_rcp_f32_e32 v39, v39
	v_add_f32_e32 v40, 1.0, v40
	v_add_f32_e32 v41, 1.0, v41
	v_add_f32_e32 v32, 1.0, v32
	v_add_f32_e32 v33, 1.0, v33
	v_add_f32_e32 v34, 1.0, v34
	v_add_f32_e32 v35, 1.0, v35
	v_rcp_f32_e32 v40, v40
	v_rcp_f32_e32 v41, v41
	v_rcp_f32_e32 v32, v32
	v_rcp_f32_e32 v33, v33
	v_rcp_f32_e32 v34, v34
	v_rcp_f32_e32 v35, v35
	v_pk_mul_f32 v[28:29], v[28:29], v[38:39]
	v_pk_mul_f32 v[20:21], v[20:21], v[156:157] op_sel_hi:[1,0]
	v_pk_mul_f32 v[30:31], v[30:31], v[40:41]
	v_pk_mul_f32 v[22:23], v[22:23], v[156:157] op_sel_hi:[1,0]
	v_pk_mul_f32 v[20:21], v[20:21], v[28:29]
	v_pk_mul_f32 v[24:25], v[24:25], v[32:33]
	v_pk_mul_f32 v[26:27], v[26:27], v[34:35]
	v_pk_mul_f32 v[16:17], v[16:17], v[156:157] op_sel_hi:[1,0]
	v_pk_mul_f32 v[18:19], v[18:19], v[156:157] op_sel_hi:[1,0]
	v_pk_mul_f32 v[22:23], v[22:23], v[30:31]
	v_pk_mul_f32 v[26:27], v[18:19], v[26:27]
	v_pk_mul_f32 v[18:19], v[16:17], v[24:25]
	v_cvt_pk_bf16_f32 v16, v20, v21
	v_mad_i64_i32 v[20:21], s[38:39], v148, s56, v[112:113]
	v_pk_mul_f32 v[12:13], v[12:13], v[152:153] op_sel_hi:[1,0]
	v_cvt_pk_bf16_f32 v17, v22, v23
	v_cvt_pk_bf16_f32 v18, v18, v19
	v_cvt_pk_bf16_f32 v19, v26, v27
	v_lshl_add_u64 v[20:21], v[20:21], 0, v[114:115]
	v_mul_f32_e32 v22, 0xbfb8aa3b, v12
	v_mul_f32_e32 v23, 0xbfb8aa3b, v13
	v_pk_mul_f32 v[8:9], v[8:9], v[152:153] op_sel_hi:[1,0]
	v_pk_mul_f32 v[10:11], v[10:11], v[152:153] op_sel_hi:[1,0]
	v_exp_f32_e32 v22, v22
	v_exp_f32_e32 v23, v23
	global_store_dwordx4 v[20:21], v[16:19], off
	v_pk_mul_f32 v[14:15], v[14:15], v[152:153] op_sel_hi:[1,0]
	v_add_f32_e32 v22, 1.0, v22
	v_mul_f32_e32 v16, 0xbfb8aa3b, v8
	v_mul_f32_e32 v17, 0xbfb8aa3b, v9
	v_mul_f32_e32 v18, 0xbfb8aa3b, v10
	v_mul_f32_e32 v19, 0xbfb8aa3b, v11
	v_exp_f32_e32 v16, v16
	v_exp_f32_e32 v17, v17
	v_exp_f32_e32 v18, v18
	v_exp_f32_e32 v19, v19
	v_mul_f32_e32 v24, 0xbfb8aa3b, v14
	v_mul_f32_e32 v25, 0xbfb8aa3b, v15
	v_exp_f32_e32 v24, v24
	v_exp_f32_e32 v25, v25
	v_add_f32_e32 v23, 1.0, v23
	v_rcp_f32_e32 v22, v22
	v_rcp_f32_e32 v23, v23
	v_add_f32_e32 v16, 1.0, v16
	v_add_f32_e32 v17, 1.0, v17
	v_add_f32_e32 v18, 1.0, v18
	v_add_f32_e32 v19, 1.0, v19
	v_rcp_f32_e32 v16, v16
	v_rcp_f32_e32 v17, v17
	v_rcp_f32_e32 v18, v18
	v_rcp_f32_e32 v19, v19
	v_add_f32_e32 v24, 1.0, v24
	v_add_f32_e32 v25, 1.0, v25
	v_rcp_f32_e32 v24, v24
	v_rcp_f32_e32 v25, v25
	v_pk_mul_f32 v[12:13], v[12:13], v[22:23]
	v_pk_mul_f32 v[4:5], v[4:5], v[152:153] op_sel_hi:[1,0]
	v_pk_mul_f32 v[8:9], v[8:9], v[16:17]
	v_pk_mul_f32 v[4:5], v[4:5], v[12:13]
	v_pk_mul_f32 v[10:11], v[10:11], v[18:19]
	v_pk_mul_f32 v[0:1], v[0:1], v[152:153] op_sel_hi:[1,0]
	v_pk_mul_f32 v[2:3], v[2:3], v[152:153] op_sel_hi:[1,0]
	v_pk_mul_f32 v[14:15], v[14:15], v[24:25]
	v_pk_mul_f32 v[10:11], v[2:3], v[10:11]
	v_pk_mul_f32 v[2:3], v[0:1], v[8:9]
	v_cvt_pk_bf16_f32 v0, v4, v5
	v_mad_i64_i32 v[4:5], s[38:39], v146, s56, v[112:113]
	v_pk_mul_f32 v[6:7], v[6:7], v[152:153] op_sel_hi:[1,0]
	v_lshl_add_u64 v[4:5], v[4:5], 0, v[114:115]
	v_pk_mul_f32 v[6:7], v[6:7], v[14:15]
	s_nop 0
	v_cvt_pk_bf16_f32 v1, v6, v7
	v_cvt_pk_bf16_f32 v2, v2, v3
	v_cvt_pk_bf16_f32 v3, v10, v11
	global_store_dwordx4 v[4:5], v[0:3], off
	s_cbranch_vccnz .LBB0_516
	s_andn2_b64 vcc, exec, s[12:13]
	s_cbranch_vccnz .LBB0_515
	s_barrier
	s_branch .LBB0_515

; __device__ __forceinline__ float row_part(const float* ss, int row, int fq) { const f32x4 a = ((const f32x4*)(ss + (size_t)row * 16))[fq]; return (a[0] + a[1]) + (a[2] + a[3]); }
; __device__ __forceinline__ float row_finish(float t) { t += shx(t, 16); t += shx(t, 32); return __builtin_amdgcn_rsqf(t * (1.0f / 1024.0f) + RMS_EPS); }
;     __device__ __forceinline__ void operator()(const f32x4 (&acc)[2][2][4][2], const Unit& u, int wr, int wc, int fr, int fq) const {
;     ...
;         float rs[2][4];
; #pragma unroll
;         for (int ai = 0; ai < 2; ++ai)
; #pragma unroll
;             for (int m = 0; m < 4; ++m) rs[ai][m] = row_part(ss, u.pm * BM + ai * HALF + wr * 64 + m * 16 + fr, fq);
; #pragma unroll
;         for (int ai = 0; ai < 2; ++ai)
; #pragma unroll
;             for (int m = 0; m < 4; ++m) rs[ai][m] = row_finish(rs[ai][m]);
.LBB0_999:
	s_lshr_b32 s98, s2, 6
	s_cmp_lg_u32 s49, s98
	s_cbranch_scc1 .Lrsf_1
	v_lshl_add_u32 v168, s48, 8, v155
	v_ashrrev_i32_e32 v169, 31, v168
	v_lshlrev_b64 v[146:147], 6, v[168:169]
	v_lshl_add_u64 v[146:147], v[136:137], 0, v[146:147]
	ds_read_b128 v[146:149], v239
	v_or_b32_e32 v164, 16, v168
	v_ashrrev_i32_e32 v165, 31, v164
	v_or_b32_e32 v160, 32, v168
	v_ashrrev_i32_e32 v161, 31, v160
	v_or_b32_e32 v156, 48, v168
	v_ashrrev_i32_e32 v157, 31, v156
	v_add_u32_e32 v152, 0x80, v168
	v_ashrrev_i32_e32 v153, 31, v152
	v_mov_b32_e32 v162, v201
	s_andn2_b64 vcc, exec, s[16:17]
	s_waitcnt lgkmcnt(0)
	v_mov_b32_e32 v150, v147
	v_mov_b32_e32 v151, v148
	v_mov_b32_e32 v147, v149
	v_pk_add_f32 v[146:147], v[150:151], v[146:147]
	s_nop 0
	v_add_f32_e32 v154, v146, v147
	v_lshlrev_b64 v[146:147], 6, v[164:165]
	v_lshl_add_u64 v[146:147], v[136:137], 0, v[146:147]
	ds_read_b128 v[146:149], v239 offset:1024
	s_waitcnt lgkmcnt(0)
	v_mov_b32_e32 v150, v147
	v_mov_b32_e32 v151, v148
	v_mov_b32_e32 v147, v149
	v_pk_add_f32 v[146:147], v[150:151], v[146:147]
	s_nop 0
	v_add_f32_e32 v158, v146, v147
	v_lshlrev_b64 v[146:147], 6, v[160:161]
	v_lshl_add_u64 v[146:147], v[136:137], 0, v[146:147]
	ds_read_b128 v[146:149], v239 offset:2048
	s_waitcnt lgkmcnt(0)
	v_mov_b32_e32 v150, v147
	v_mov_b32_e32 v151, v148
	v_mov_b32_e32 v147, v149
	v_pk_add_f32 v[146:147], v[150:151], v[146:147]
	s_nop 0
	v_add_f32_e32 v161, v146, v147
	v_lshlrev_b64 v[146:147], 6, v[156:157]
	v_lshl_add_u64 v[146:147], v[136:137], 0, v[146:147]
	ds_read_b128 v[146:149], v239 offset:3072
	s_waitcnt lgkmcnt(0)
	v_mov_b32_e32 v150, v147
	v_mov_b32_e32 v151, v148
	v_mov_b32_e32 v147, v149
	v_pk_add_f32 v[146:147], v[150:151], v[146:147]
	s_nop 0
	v_add_f32_e32 v157, v146, v147
	v_lshlrev_b64 v[146:147], 6, v[152:153]
	v_lshl_add_u64 v[146:147], v[136:137], 0, v[146:147]
	ds_read_b128 v[146:149], v239 offset:8192
	s_waitcnt lgkmcnt(0)
	v_mov_b32_e32 v150, v147
	v_mov_b32_e32 v151, v148
	v_mov_b32_e32 v147, v149
	v_pk_add_f32 v[146:147], v[150:151], v[146:147]
	v_add_u32_e32 v150, 0x90, v168
	v_ashrrev_i32_e32 v151, 31, v150
	v_add_f32_e32 v153, v146, v147
	v_lshlrev_b64 v[146:147], 6, v[150:151]
	v_lshl_add_u64 v[146:147], v[136:137], 0, v[146:147]
	ds_read_b128 v[146:149], v239 offset:9216
	s_waitcnt lgkmcnt(0)
	v_mov_b32_e32 v176, v147
	v_mov_b32_e32 v177, v148
	v_mov_b32_e32 v147, v149
	v_add_u32_e32 v148, 0xa0, v168
	v_pk_add_f32 v[146:147], v[176:177], v[146:147]
	v_ashrrev_i32_e32 v149, 31, v148
	v_add_f32_e32 v151, v146, v147
	v_lshlrev_b64 v[146:147], 6, v[148:149]
	v_lshl_add_u64 v[146:147], v[136:137], 0, v[146:147]
	ds_read_b128 v[176:179], v239 offset:10240
	s_waitcnt lgkmcnt(0)
	v_mov_b32_e32 v146, v177
	v_mov_b32_e32 v147, v178
	v_mov_b32_e32 v177, v179
	v_pk_add_f32 v[146:147], v[146:147], v[176:177]
	s_nop 0
	v_add_f32_e32 v149, v146, v147
	v_add_u32_e32 v146, 0xb0, v168
	v_ashrrev_i32_e32 v147, 31, v146
	v_lshlrev_b64 v[176:177], 6, v[146:147]
	v_lshl_add_u64 v[176:177], v[136:137], 0, v[176:177]
	ds_read_b128 v[176:179], v239 offset:11264
	s_waitcnt lgkmcnt(0)
	v_mov_b32_e32 v180, v177
	v_lshlrev_b32_e32 v162, 2, v162
	v_xor_b32_e32 v162, 64, v162
	v_mov_b32_e32 v162, v154
	s_nop 1
	v_permlane16_swap_b32_e32 v162, v154
	v_mov_b32_e32 v181, v178
	v_mov_b32_e32 v177, v179
	v_pk_add_f32 v[176:177], v[180:181], v[176:177]
	v_lshl_or_b32 v178, s49, 7, v163
	s_waitcnt lgkmcnt(0)
	v_add_f32_e32 v154, v154, v162
	v_mov_b32_e32 v162, v201
	v_add_f32_e32 v147, v176, v177
	v_lshlrev_b32_e32 v162, 2, v162
	v_xor_b32_e32 v162, 0x80, v162
	v_mov_b32_e32 v162, v154
	s_nop 1
	v_permlane32_swap_b32_e32 v162, v154
	v_ashrrev_i32_e32 v179, 31, v178
	s_mov_b64 s[48:49], -1
	s_waitcnt lgkmcnt(0)
	v_add_f32_e32 v154, v154, v162
	v_fmamk_f32 v154, v154, 0x3a800000, v175
	v_rsq_f32_e32 v174, v154
	v_mov_b32_e32 v154, v201
	v_pk_mul_f32 v[124:125], v[124:125], v[174:175] op_sel_hi:[1,0]
	v_lshlrev_b32_e32 v154, 2, v154
	v_xor_b32_e32 v154, 64, v154
	v_mov_b32_e32 v154, v158
	s_nop 1
	v_permlane16_swap_b32_e32 v154, v158
	v_pk_mul_f32 v[126:127], v[126:127], v[174:175] op_sel_hi:[1,0]
	v_pk_mul_f32 v[116:117], v[116:117], v[174:175] op_sel_hi:[1,0]
	v_pk_mul_f32 v[120:121], v[120:121], v[174:175] op_sel_hi:[1,0]
	v_pk_mul_f32 v[118:119], v[118:119], v[174:175] op_sel_hi:[1,0]
	s_waitcnt lgkmcnt(0)
	v_add_f32_e32 v154, v158, v154
	v_mov_b32_e32 v158, v201
	v_pk_mul_f32 v[122:123], v[122:123], v[174:175] op_sel_hi:[1,0]
	v_lshlrev_b32_e32 v158, 2, v158
	v_xor_b32_e32 v158, 0x80, v158
	v_mov_b32_e32 v158, v154
	s_nop 1
	v_permlane32_swap_b32_e32 v158, v154
	v_pk_mul_f32 v[112:113], v[112:113], v[174:175] op_sel_hi:[1,0]
	v_pk_mul_f32 v[114:115], v[114:115], v[174:175] op_sel_hi:[1,0]
	s_waitcnt lgkmcnt(0)
	v_add_f32_e32 v154, v154, v158
	v_fmamk_f32 v154, v154, 0x3a800000, v175
	v_rsq_f32_e32 v176, v154
	v_mov_b32_e32 v154, v201
	v_mov_b32_e32 v158, v201
	v_lshlrev_b32_e32 v154, 2, v154
	v_xor_b32_e32 v154, 64, v154
	v_mov_b32_e32 v154, v161
	s_nop 1
	v_permlane16_swap_b32_e32 v154, v161
	v_pk_mul_f32 v[110:111], v[110:111], v[176:177] op_sel_hi:[1,0]
	v_lshlrev_b32_e32 v158, 2, v158
	v_xor_b32_e32 v158, 0x80, v158
	s_waitcnt lgkmcnt(0)
	v_add_f32_e32 v154, v161, v154
	v_mov_b32_e32 v158, v154
	s_nop 1
	v_permlane32_swap_b32_e32 v158, v154
	v_pk_mul_f32 v[108:109], v[108:109], v[176:177] op_sel_hi:[1,0]
	v_pk_mul_f32 v[100:101], v[100:101], v[176:177] op_sel_hi:[1,0]
	v_pk_mul_f32 v[102:103], v[102:103], v[176:177] op_sel_hi:[1,0]
	v_pk_mul_f32 v[106:107], v[106:107], v[176:177] op_sel_hi:[1,0]
	s_waitcnt lgkmcnt(0)
; __device__ __forceinline__ f32x4 silu4(f32x4 v) { return (f32x4){silu_f(v[0]), silu_f(v[1]), silu_f(v[2]), silu_f(v[3])}; }
; __device__ __forceinline__ float row_finish(float t) { t += shx(t, 16); t += shx(t, 32); return __builtin_amdgcn_rsqf(t * (1.0f / 1024.0f) + RMS_EPS); }
;     __device__ __forceinline__ void operator()(const f32x4 (&acc)[2][2][4][2], const Unit& u, int wr, int wc, int fr, int fq) const {
;     ...
;         for (int ai = 0; ai < 2; ++ai)
; #pragma unroll
;             for (int m = 0; m < 4; ++m) rs[ai][m] = row_finish(rs[ai][m]);
; #pragma unroll
;         for (int ai = 0; ai < 2; ++ai)
; #pragma unroll
;             for (int m = 0; m < 4; ++m) {
;                 const int row = u.pm * BM + ai * HALF + wr * 64 + m * 16 + fr;
;                 const float rstd = rs[ai][m];
;                 const f32x4 a0 = silu4(acc[ai][0][m][0] * rstd) * (acc[ai][1][m][0] * rstd);
	v_add_f32_e32 v154, v154, v158
	v_fmamk_f32 v154, v154, 0x3a800000, v175
	v_rsq_f32_e32 v172, v154
	v_mov_b32_e32 v154, v201
	v_pk_mul_f32 v[104:105], v[104:105], v[176:177] op_sel_hi:[1,0]
	v_lshlrev_b32_e32 v154, 2, v154
	v_xor_b32_e32 v154, 64, v154
	v_mov_b32_e32 v154, v157
	s_nop 1
	v_permlane16_swap_b32_e32 v154, v157
	v_pk_mul_f32 v[96:97], v[96:97], v[176:177] op_sel_hi:[1,0]
	v_pk_mul_f32 v[98:99], v[98:99], v[176:177] op_sel_hi:[1,0]
	v_pk_mul_f32 v[94:95], v[94:95], v[172:173] op_sel_hi:[1,0]
	v_pk_mul_f32 v[92:93], v[92:93], v[172:173] op_sel_hi:[1,0]
	s_waitcnt lgkmcnt(0)
	v_add_f32_e32 v154, v157, v154
	v_mov_b32_e32 v157, v201
	v_pk_mul_f32 v[84:85], v[84:85], v[172:173] op_sel_hi:[1,0]
	v_lshlrev_b32_e32 v157, 2, v157
	v_xor_b32_e32 v157, 0x80, v157
	v_mov_b32_e32 v157, v154
	s_nop 1
	v_permlane32_swap_b32_e32 v157, v154
	v_pk_mul_f32 v[86:87], v[86:87], v[172:173] op_sel_hi:[1,0]
	v_pk_mul_f32 v[90:91], v[90:91], v[172:173] op_sel_hi:[1,0]
	v_pk_mul_f32 v[88:89], v[88:89], v[172:173] op_sel_hi:[1,0]
	v_pk_mul_f32 v[80:81], v[80:81], v[172:173] op_sel_hi:[1,0]
	s_waitcnt lgkmcnt(0)
	v_add_f32_e32 v154, v154, v157
	v_fmamk_f32 v154, v154, 0x3a800000, v175
	v_rsq_f32_e32 v170, v154
	v_mov_b32_e32 v154, v201
	v_pk_mul_f32 v[82:83], v[82:83], v[172:173] op_sel_hi:[1,0]
	v_lshlrev_b32_e32 v154, 2, v154
	v_xor_b32_e32 v154, 64, v154
	v_mov_b32_e32 v154, v153
	s_nop 1
	v_permlane16_swap_b32_e32 v154, v153
	v_pk_mul_f32 v[78:79], v[78:79], v[170:171] op_sel_hi:[1,0]
	v_pk_mul_f32 v[76:77], v[76:77], v[170:171] op_sel_hi:[1,0]
	v_pk_mul_f32 v[68:69], v[68:69], v[170:171] op_sel_hi:[1,0]
	v_pk_mul_f32 v[70:71], v[70:71], v[170:171] op_sel_hi:[1,0]
	s_waitcnt lgkmcnt(0)
	v_add_f32_e32 v153, v153, v154
	v_mov_b32_e32 v154, v201
	v_pk_mul_f32 v[74:75], v[74:75], v[170:171] op_sel_hi:[1,0]
	v_lshlrev_b32_e32 v154, 2, v154
	v_xor_b32_e32 v154, 0x80, v154
	v_mov_b32_e32 v154, v153
	s_nop 1
	v_permlane32_swap_b32_e32 v154, v153
	v_pk_mul_f32 v[72:73], v[72:73], v[170:171] op_sel_hi:[1,0]
	v_pk_mul_f32 v[64:65], v[64:65], v[170:171] op_sel_hi:[1,0]
	v_pk_mul_f32 v[66:67], v[66:67], v[170:171] op_sel_hi:[1,0]
	s_waitcnt lgkmcnt(0)
	v_add_f32_e32 v153, v153, v154
	v_fmamk_f32 v153, v153, 0x3a800000, v175
	v_rsq_f32_e32 v166, v153
	v_mov_b32_e32 v153, v201
	v_pk_mul_f32 v[62:63], v[62:63], v[166:167] op_sel_hi:[1,0]
	v_lshlrev_b32_e32 v153, 2, v153
	v_xor_b32_e32 v153, 64, v153
	v_mov_b32_e32 v153, v151
	s_nop 1
	v_permlane16_swap_b32_e32 v153, v151
	v_pk_mul_f32 v[60:61], v[60:61], v[166:167] op_sel_hi:[1,0]
	v_pk_mul_f32 v[52:53], v[52:53], v[166:167] op_sel_hi:[1,0]
	v_pk_mul_f32 v[54:55], v[54:55], v[166:167] op_sel_hi:[1,0]
	v_pk_mul_f32 v[58:59], v[58:59], v[166:167] op_sel_hi:[1,0]
	s_waitcnt lgkmcnt(0)
	v_add_f32_e32 v151, v151, v153
	v_mov_b32_e32 v153, v201
	v_pk_mul_f32 v[56:57], v[56:57], v[166:167] op_sel_hi:[1,0]
	v_lshlrev_b32_e32 v153, 2, v153
	v_xor_b32_e32 v153, 0x80, v153
	v_mov_b32_e32 v153, v151
	s_nop 1
	v_permlane32_swap_b32_e32 v153, v151
	v_pk_mul_f32 v[48:49], v[48:49], v[166:167] op_sel_hi:[1,0]
	v_pk_mul_f32 v[50:51], v[50:51], v[166:167] op_sel_hi:[1,0]
	s_waitcnt lgkmcnt(0)
	v_add_f32_e32 v151, v151, v153
	v_fmamk_f32 v151, v151, 0x3a800000, v175
	v_rsq_f32_e32 v162, v151
	v_mov_b32_e32 v151, v201
	v_pk_mul_f32 v[46:47], v[46:47], v[162:163] op_sel_hi:[1,0]
	v_lshlrev_b32_e32 v151, 2, v151
	v_xor_b32_e32 v151, 64, v151
	v_mov_b32_e32 v151, v149
	s_nop 1
	v_permlane16_swap_b32_e32 v151, v149
	v_pk_mul_f32 v[44:45], v[44:45], v[162:163] op_sel_hi:[1,0]
	v_pk_mul_f32 v[36:37], v[36:37], v[162:163] op_sel_hi:[1,0]
	v_pk_mul_f32 v[38:39], v[38:39], v[162:163] op_sel_hi:[1,0]
	v_pk_mul_f32 v[42:43], v[42:43], v[162:163] op_sel_hi:[1,0]
	s_waitcnt lgkmcnt(0)
	v_add_f32_e32 v149, v149, v151
	v_mov_b32_e32 v151, v201
	v_pk_mul_f32 v[40:41], v[40:41], v[162:163] op_sel_hi:[1,0]
	v_lshlrev_b32_e32 v151, 2, v151
	v_xor_b32_e32 v151, 0x80, v151
	v_mov_b32_e32 v151, v149
	s_nop 1
	v_permlane32_swap_b32_e32 v151, v149
	v_pk_mul_f32 v[32:33], v[32:33], v[162:163] op_sel_hi:[1,0]
	v_pk_mul_f32 v[34:35], v[34:35], v[162:163] op_sel_hi:[1,0]
	s_waitcnt lgkmcnt(0)
	v_add_f32_e32 v149, v149, v151
	v_fmamk_f32 v149, v149, 0x3a800000, v175
	v_rsq_f32_e32 v158, v149
	v_mov_b32_e32 v149, v201
	v_pk_mul_f32 v[30:31], v[30:31], v[158:159] op_sel_hi:[1,0]
	v_lshlrev_b32_e32 v149, 2, v149
	v_xor_b32_e32 v149, 64, v149
	v_mov_b32_e32 v149, v147
	s_nop 1
	v_permlane16_swap_b32_e32 v149, v147
	v_pk_mul_f32 v[28:29], v[28:29], v[158:159] op_sel_hi:[1,0]
	v_pk_mul_f32 v[20:21], v[20:21], v[158:159] op_sel_hi:[1,0]
	v_pk_mul_f32 v[22:23], v[22:23], v[158:159] op_sel_hi:[1,0]
	v_pk_mul_f32 v[26:27], v[26:27], v[158:159] op_sel_hi:[1,0]
	s_waitcnt lgkmcnt(0)
	v_add_f32_e32 v147, v147, v149
	v_mov_b32_e32 v149, v201
	v_pk_mul_f32 v[24:25], v[24:25], v[158:159] op_sel_hi:[1,0]
	v_lshlrev_b32_e32 v149, 2, v149
	v_xor_b32_e32 v149, 0x80, v149
	v_mov_b32_e32 v149, v147
	s_nop 1
	v_permlane32_swap_b32_e32 v149, v147
	v_pk_mul_f32 v[16:17], v[16:17], v[158:159] op_sel_hi:[1,0]
	v_pk_mul_f32 v[18:19], v[18:19], v[158:159] op_sel_hi:[1,0]
	s_waitcnt lgkmcnt(0)
	v_add_f32_e32 v147, v147, v149
	v_fmamk_f32 v147, v147, 0x3a800000, v175
	v_rsq_f32_e32 v154, v147
	v_lshlrev_b32_e32 v251, 5, v155
	v_add_u32_e32 v251, 0x24080, v251
	ds_write_b32 v251, v174
	ds_write_b32 v251, v176 offset:4
	ds_write_b32 v251, v172 offset:8
	ds_write_b32 v251, v170 offset:12
	ds_write_b32 v251, v166 offset:16
	ds_write_b32 v251, v162 offset:20
	ds_write_b32 v251, v158 offset:24
	ds_write_b32 v251, v154 offset:28
	s_branch .Lrsj_1
; __device__ __forceinline__ float row_part(const float* ss, int row, int fq) { const f32x4 a = ((const f32x4*)(ss + (size_t)row * 16))[fq]; return (a[0] + a[1]) + (a[2] + a[3]); }
; __device__ __forceinline__ float row_finish(float t) { t += shx(t, 16); t += shx(t, 32); return __builtin_amdgcn_rsqf(t * (1.0f / 1024.0f) + RMS_EPS); }
; __device__ __forceinline__ f32x4 silu4(f32x4 v) { return (f32x4){silu_f(v[0]), silu_f(v[1]), silu_f(v[2]), silu_f(v[3])}; }
;     __device__ __forceinline__ void operator()(const f32x4 (&acc)[2][2][4][2], const Unit& u, int wr, int wc, int fr, int fq) const {
;     ...
;         float rs[2][4];
; #pragma unroll
;         for (int ai = 0; ai < 2; ++ai)
; #pragma unroll
;             for (int m = 0; m < 4; ++m) rs[ai][m] = row_part(ss, u.pm * BM + ai * HALF + wr * 64 + m * 16 + fr, fq);
; #pragma unroll
;         for (int ai = 0; ai < 2; ++ai)
; #pragma unroll
;             for (int m = 0; m < 4; ++m) rs[ai][m] = row_finish(rs[ai][m]);
; #pragma unroll
;         for (int ai = 0; ai < 2; ++ai)
; #pragma unroll
;             for (int m = 0; m < 4; ++m) {
;                 const int row = u.pm * BM + ai * HALF + wr * 64 + m * 16 + fr;
;                 const float rstd = rs[ai][m];
;                 const f32x4 a0 = silu4(acc[ai][0][m][0] * rstd) * (acc[ai][1][m][0] * rstd);
.Lrsf_1:
	v_lshlrev_b32_e32 v251, 5, v155
	v_add_u32_e32 v251, 0x24080, v251
	ds_read_b32 v174, v251
	ds_read_b32 v176, v251 offset:4
	ds_read_b32 v172, v251 offset:8
	ds_read_b32 v170, v251 offset:12
	ds_read_b32 v166, v251 offset:16
	ds_read_b32 v162, v251 offset:20
	ds_read_b32 v158, v251 offset:24
	ds_read_b32 v154, v251 offset:28
	s_waitcnt lgkmcnt(0)
	v_lshl_add_u32 v168, s48, 8, v155
	v_or_b32_e32 v164, 16, v168
	v_or_b32_e32 v160, 32, v168
	v_or_b32_e32 v156, 48, v168
	v_add_u32_e32 v152, 0x80, v168
	s_andn2_b64 vcc, exec, s[16:17]
	s_waitcnt lgkmcnt(0)
	s_nop 0
	s_waitcnt lgkmcnt(0)
	s_nop 0
	s_waitcnt lgkmcnt(0)
	s_nop 0
	s_waitcnt lgkmcnt(0)
	s_nop 0
	s_waitcnt lgkmcnt(0)
	v_add_u32_e32 v150, 0x90, v168
	s_waitcnt lgkmcnt(0)
	v_add_u32_e32 v148, 0xa0, v168
	s_waitcnt lgkmcnt(0)
	s_nop 0
	v_add_u32_e32 v146, 0xb0, v168
	s_waitcnt lgkmcnt(0)
	v_lshl_or_b32 v178, s49, 7, v163
	s_waitcnt lgkmcnt(0)
	v_ashrrev_i32_e32 v179, 31, v178
	s_mov_b64 s[48:49], -1
	s_waitcnt lgkmcnt(0)
	v_pk_mul_f32 v[124:125], v[124:125], v[174:175] op_sel_hi:[1,0]
	v_pk_mul_f32 v[126:127], v[126:127], v[174:175] op_sel_hi:[1,0]
	v_pk_mul_f32 v[116:117], v[116:117], v[174:175] op_sel_hi:[1,0]
	v_pk_mul_f32 v[120:121], v[120:121], v[174:175] op_sel_hi:[1,0]
	v_pk_mul_f32 v[118:119], v[118:119], v[174:175] op_sel_hi:[1,0]
	s_waitcnt lgkmcnt(0)
	v_pk_mul_f32 v[122:123], v[122:123], v[174:175] op_sel_hi:[1,0]
	v_pk_mul_f32 v[112:113], v[112:113], v[174:175] op_sel_hi:[1,0]
	v_pk_mul_f32 v[114:115], v[114:115], v[174:175] op_sel_hi:[1,0]
	s_waitcnt lgkmcnt(0)
	v_pk_mul_f32 v[110:111], v[110:111], v[176:177] op_sel_hi:[1,0]
	s_waitcnt lgkmcnt(0)
	v_pk_mul_f32 v[108:109], v[108:109], v[176:177] op_sel_hi:[1,0]
	v_pk_mul_f32 v[100:101], v[100:101], v[176:177] op_sel_hi:[1,0]
	v_pk_mul_f32 v[102:103], v[102:103], v[176:177] op_sel_hi:[1,0]
	v_pk_mul_f32 v[106:107], v[106:107], v[176:177] op_sel_hi:[1,0]
	s_waitcnt lgkmcnt(0)
	v_pk_mul_f32 v[104:105], v[104:105], v[176:177] op_sel_hi:[1,0]
	v_pk_mul_f32 v[96:97], v[96:97], v[176:177] op_sel_hi:[1,0]
	v_pk_mul_f32 v[98:99], v[98:99], v[176:177] op_sel_hi:[1,0]
	v_pk_mul_f32 v[94:95], v[94:95], v[172:173] op_sel_hi:[1,0]
	v_pk_mul_f32 v[92:93], v[92:93], v[172:173] op_sel_hi:[1,0]
	s_waitcnt lgkmcnt(0)
	v_pk_mul_f32 v[84:85], v[84:85], v[172:173] op_sel_hi:[1,0]
	v_pk_mul_f32 v[86:87], v[86:87], v[172:173] op_sel_hi:[1,0]
	v_pk_mul_f32 v[90:91], v[90:91], v[172:173] op_sel_hi:[1,0]
	v_pk_mul_f32 v[88:89], v[88:89], v[172:173] op_sel_hi:[1,0]
	v_pk_mul_f32 v[80:81], v[80:81], v[172:173] op_sel_hi:[1,0]
	s_waitcnt lgkmcnt(0)
	v_pk_mul_f32 v[82:83], v[82:83], v[172:173] op_sel_hi:[1,0]
	v_pk_mul_f32 v[78:79], v[78:79], v[170:171] op_sel_hi:[1,0]
	v_pk_mul_f32 v[76:77], v[76:77], v[170:171] op_sel_hi:[1,0]
	v_pk_mul_f32 v[68:69], v[68:69], v[170:171] op_sel_hi:[1,0]
	v_pk_mul_f32 v[70:71], v[70:71], v[170:171] op_sel_hi:[1,0]
	s_waitcnt lgkmcnt(0)
	v_pk_mul_f32 v[74:75], v[74:75], v[170:171] op_sel_hi:[1,0]
	v_pk_mul_f32 v[72:73], v[72:73], v[170:171] op_sel_hi:[1,0]
	v_pk_mul_f32 v[64:65], v[64:65], v[170:171] op_sel_hi:[1,0]
	v_pk_mul_f32 v[66:67], v[66:67], v[170:171] op_sel_hi:[1,0]
	s_waitcnt lgkmcnt(0)
	v_pk_mul_f32 v[62:63], v[62:63], v[166:167] op_sel_hi:[1,0]
	v_pk_mul_f32 v[60:61], v[60:61], v[166:167] op_sel_hi:[1,0]
	v_pk_mul_f32 v[52:53], v[52:53], v[166:167] op_sel_hi:[1,0]
	v_pk_mul_f32 v[54:55], v[54:55], v[166:167] op_sel_hi:[1,0]
	v_pk_mul_f32 v[58:59], v[58:59], v[166:167] op_sel_hi:[1,0]
	s_waitcnt lgkmcnt(0)
	v_pk_mul_f32 v[56:57], v[56:57], v[166:167] op_sel_hi:[1,0]
	v_pk_mul_f32 v[48:49], v[48:49], v[166:167] op_sel_hi:[1,0]
	v_pk_mul_f32 v[50:51], v[50:51], v[166:167] op_sel_hi:[1,0]
	s_waitcnt lgkmcnt(0)
	v_pk_mul_f32 v[46:47], v[46:47], v[162:163] op_sel_hi:[1,0]
	v_pk_mul_f32 v[44:45], v[44:45], v[162:163] op_sel_hi:[1,0]
	v_pk_mul_f32 v[36:37], v[36:37], v[162:163] op_sel_hi:[1,0]
	v_pk_mul_f32 v[38:39], v[38:39], v[162:163] op_sel_hi:[1,0]
	v_pk_mul_f32 v[42:43], v[42:43], v[162:163] op_sel_hi:[1,0]
	s_waitcnt lgkmcnt(0)
	v_pk_mul_f32 v[40:41], v[40:41], v[162:163] op_sel_hi:[1,0]
	v_pk_mul_f32 v[32:33], v[32:33], v[162:163] op_sel_hi:[1,0]
	v_pk_mul_f32 v[34:35], v[34:35], v[162:163] op_sel_hi:[1,0]
	s_waitcnt lgkmcnt(0)
	v_pk_mul_f32 v[30:31], v[30:31], v[158:159] op_sel_hi:[1,0]
	v_pk_mul_f32 v[28:29], v[28:29], v[158:159] op_sel_hi:[1,0]
	v_pk_mul_f32 v[20:21], v[20:21], v[158:159] op_sel_hi:[1,0]
	v_pk_mul_f32 v[22:23], v[22:23], v[158:159] op_sel_hi:[1,0]
	v_pk_mul_f32 v[26:27], v[26:27], v[158:159] op_sel_hi:[1,0]
	s_waitcnt lgkmcnt(0)
	v_pk_mul_f32 v[24:25], v[24:25], v[158:159] op_sel_hi:[1,0]
	v_pk_mul_f32 v[16:17], v[16:17], v[158:159] op_sel_hi:[1,0]
	v_pk_mul_f32 v[18:19], v[18:19], v[158:159] op_sel_hi:[1,0]
	s_waitcnt lgkmcnt(0)
; __device__ __forceinline__ unsigned cvt_pk_bf16(float lo, float hi) { unsigned r; asm volatile("v_cvt_pk_bf16_f32 %0, %1, %2" : "=v"(r) : "v"(lo), "v"(hi)); return r; }
; __device__ __forceinline__ float silu_f(float v) { return v * __builtin_amdgcn_rcpf(1.0f + __builtin_amdgcn_exp2f(v * -1.4426950408889634f)); }
; __device__ __forceinline__ f32x4 silu4(f32x4 v) { return (f32x4){silu_f(v[0]), silu_f(v[1]), silu_f(v[2]), silu_f(v[3])}; }
; __device__ __forceinline__ float sq4(f32x4 v) { return (v[0] * v[0] + v[1] * v[1]) + (v[2] * v[2] + v[3] * v[3]); }
; __device__ __forceinline__ u32x4 pack8(f32x4 a, f32x4 b) { u32x4 w; w.x = cvt_pk_bf16(a[0], a[1]); w.y = cvt_pk_bf16(a[2], a[3]); w.z = cvt_pk_bf16(b[0], b[1]); w.w = cvt_pk_bf16(b[2], b[3]); return w; }
;     __device__ __forceinline__ void operator()(const f32x4 (&acc)[2][2][4][2], const Unit& u, int wr, int wc, int fr, int fq) const {
;     ...
;         for (int ai = 0; ai < 2; ++ai)
; #pragma unroll
;             for (int m = 0; m < 4; ++m) {
;                 const int row = u.pm * BM + ai * HALF + wr * 64 + m * 16 + fr;
;                 const float rstd = rs[ai][m];
;                 const f32x4 a0 = silu4(acc[ai][0][m][0] * rstd) * (acc[ai][1][m][0] * rstd);
;                 const f32x4 a1 = silu4(acc[ai][0][m][1] * rstd) * (acc[ai][1][m][1] * rstd);
;                 *(u32x4*)(ACT + (size_t)row * 2816 + col0) = pack8(a0, a1);
;             }
.Lrsj_1:
	v_mul_f32_e32 v147, 0xbfb8aa3b, v124
	v_exp_f32_e32 v147, v147
	v_pk_mul_f32 v[14:15], v[14:15], v[154:155] op_sel_hi:[1,0]
	v_pk_mul_f32 v[12:13], v[12:13], v[154:155] op_sel_hi:[1,0]
	v_add_f32_e32 v147, 1.0, v147
	v_rcp_f32_e32 v180, v147
	v_mul_f32_e32 v147, 0xbfb8aa3b, v125
	v_exp_f32_e32 v147, v147
	v_pk_mul_f32 v[4:5], v[4:5], v[154:155] op_sel_hi:[1,0]
	v_pk_mul_f32 v[6:7], v[6:7], v[154:155] op_sel_hi:[1,0]
	v_pk_mul_f32 v[10:11], v[10:11], v[154:155] op_sel_hi:[1,0]
	v_add_f32_e32 v147, 1.0, v147
	v_rcp_f32_e32 v181, v147
	v_mul_f32_e32 v147, 0xbfb8aa3b, v126
	v_exp_f32_e32 v147, v147
	v_pk_mul_f32 v[8:9], v[8:9], v[154:155] op_sel_hi:[1,0]
	v_pk_mul_f32 v[124:125], v[124:125], v[180:181]
	v_pk_mul_f32 v[0:1], v[0:1], v[154:155] op_sel_hi:[1,0]
	v_add_f32_e32 v147, 1.0, v147
	v_rcp_f32_e32 v182, v147
	v_mul_f32_e32 v147, 0xbfb8aa3b, v127
	v_exp_f32_e32 v147, v147
	v_pk_mul_f32 v[116:117], v[116:117], v[124:125]
	v_mul_f32_e32 v124, 0xbfb8aa3b, v120
	v_mul_f32_e32 v125, 0xbfb8aa3b, v121
	v_add_f32_e32 v147, 1.0, v147
	v_rcp_f32_e32 v183, v147
	v_exp_f32_e32 v124, v124
	v_exp_f32_e32 v125, v125
	v_cvt_pk_bf16_f32 v116, v116, v117
	v_pk_mul_f32 v[126:127], v[126:127], v[182:183]
	v_add_f32_e32 v124, 1.0, v124
	v_pk_mul_f32 v[118:119], v[118:119], v[126:127]
	v_mul_f32_e32 v126, 0xbfb8aa3b, v122
	v_mul_f32_e32 v127, 0xbfb8aa3b, v123
	v_exp_f32_e32 v126, v126
	v_exp_f32_e32 v127, v127
	v_add_f32_e32 v125, 1.0, v125
	v_rcp_f32_e32 v124, v124
	v_rcp_f32_e32 v125, v125
	v_add_f32_e32 v126, 1.0, v126
	v_add_f32_e32 v127, 1.0, v127
	v_rcp_f32_e32 v126, v126
	v_rcp_f32_e32 v127, v127
	v_pk_mul_f32 v[120:121], v[120:121], v[124:125]
	v_cvt_pk_bf16_f32 v117, v118, v119
	v_pk_mul_f32 v[2:3], v[2:3], v[154:155] op_sel_hi:[1,0]
	v_pk_mul_f32 v[122:123], v[122:123], v[126:127]
	v_pk_mul_f32 v[112:113], v[112:113], v[120:121]
	v_pk_mul_f32 v[114:115], v[114:115], v[122:123]
	v_cvt_pk_bf16_f32 v118, v112, v113
	v_mov_b64_e32 v[112:113], s[20:21]
	v_cvt_pk_bf16_f32 v119, v114, v115
	v_mad_i64_i32 v[120:121], s[14:15], v168, s68, v[112:113]
	v_lshlrev_b64 v[114:115], 1, v[178:179]
	v_lshl_add_u64 v[120:121], v[120:121], 0, v[114:115]
	global_store_dwordx4 v[120:121], v[116:119], off
	s_nop 1
	v_mul_f32_e32 v116, 0xbfb8aa3b, v108
	v_mul_f32_e32 v117, 0xbfb8aa3b, v109
	v_mul_f32_e32 v118, 0xbfb8aa3b, v110
	v_mul_f32_e32 v119, 0xbfb8aa3b, v111
	v_exp_f32_e32 v116, v116
	v_exp_f32_e32 v117, v117
	v_exp_f32_e32 v118, v118
	v_exp_f32_e32 v119, v119
	v_add_f32_e32 v116, 1.0, v116
	v_add_f32_e32 v117, 1.0, v117
	v_add_f32_e32 v118, 1.0, v118
	v_add_f32_e32 v119, 1.0, v119
	v_rcp_f32_e32 v116, v116
	v_rcp_f32_e32 v117, v117
	v_rcp_f32_e32 v118, v118
	v_rcp_f32_e32 v119, v119
	v_pk_mul_f32 v[108:109], v[108:109], v[116:117]
	s_nop 0
	v_pk_mul_f32 v[100:101], v[100:101], v[108:109]
	v_pk_mul_f32 v[110:111], v[110:111], v[118:119]
	v_mul_f32_e32 v108, 0xbfb8aa3b, v104
	v_pk_mul_f32 v[102:103], v[102:103], v[110:111]
	v_mul_f32_e32 v109, 0xbfb8aa3b, v105
	v_mul_f32_e32 v110, 0xbfb8aa3b, v106
	v_mul_f32_e32 v111, 0xbfb8aa3b, v107
	v_exp_f32_e32 v108, v108
	v_exp_f32_e32 v109, v109
	v_exp_f32_e32 v110, v110
	v_exp_f32_e32 v111, v111
	v_add_f32_e32 v108, 1.0, v108
	v_add_f32_e32 v109, 1.0, v109
	v_add_f32_e32 v110, 1.0, v110
	v_add_f32_e32 v111, 1.0, v111
	v_rcp_f32_e32 v108, v108
	v_rcp_f32_e32 v109, v109
	v_rcp_f32_e32 v110, v110
	v_rcp_f32_e32 v111, v111
	v_pk_mul_f32 v[104:105], v[104:105], v[108:109]
	v_pk_mul_f32 v[106:107], v[106:107], v[110:111]
	s_nop 0
	v_pk_mul_f32 v[106:107], v[98:99], v[106:107]
	v_pk_mul_f32 v[98:99], v[96:97], v[104:105]
	v_cvt_pk_bf16_f32 v96, v100, v101
	v_mad_i64_i32 v[100:101], s[14:15], v164, s68, v[112:113]
	v_cvt_pk_bf16_f32 v97, v102, v103
	v_cvt_pk_bf16_f32 v98, v98, v99
	v_cvt_pk_bf16_f32 v99, v106, v107
	v_lshl_add_u64 v[100:101], v[100:101], 0, v[114:115]
	global_store_dwordx4 v[100:101], v[96:99], off
	s_nop 1
	v_mul_f32_e32 v96, 0xbfb8aa3b, v92
	v_mul_f32_e32 v97, 0xbfb8aa3b, v93
	v_mul_f32_e32 v98, 0xbfb8aa3b, v94
	v_mul_f32_e32 v99, 0xbfb8aa3b, v95
	v_exp_f32_e32 v96, v96
	v_exp_f32_e32 v97, v97
	v_exp_f32_e32 v98, v98
	v_exp_f32_e32 v99, v99
	v_add_f32_e32 v96, 1.0, v96
	v_add_f32_e32 v97, 1.0, v97
	v_add_f32_e32 v98, 1.0, v98
	v_add_f32_e32 v99, 1.0, v99
	v_rcp_f32_e32 v96, v96
	v_rcp_f32_e32 v97, v97
	v_rcp_f32_e32 v98, v98
	v_rcp_f32_e32 v99, v99
	v_pk_mul_f32 v[92:93], v[92:93], v[96:97]
	s_nop 0
	v_pk_mul_f32 v[84:85], v[84:85], v[92:93]
	v_pk_mul_f32 v[94:95], v[94:95], v[98:99]
	v_mul_f32_e32 v92, 0xbfb8aa3b, v88
	v_pk_mul_f32 v[86:87], v[86:87], v[94:95]
	v_mul_f32_e32 v93, 0xbfb8aa3b, v89
	v_mul_f32_e32 v94, 0xbfb8aa3b, v90
	v_mul_f32_e32 v95, 0xbfb8aa3b, v91
	v_exp_f32_e32 v92, v92
	v_exp_f32_e32 v93, v93
	v_exp_f32_e32 v94, v94
	v_exp_f32_e32 v95, v95
	v_add_f32_e32 v92, 1.0, v92
	v_add_f32_e32 v93, 1.0, v93
	v_add_f32_e32 v94, 1.0, v94
	v_add_f32_e32 v95, 1.0, v95
	v_rcp_f32_e32 v92, v92
	v_rcp_f32_e32 v93, v93
	v_rcp_f32_e32 v94, v94
	v_rcp_f32_e32 v95, v95
	v_pk_mul_f32 v[88:89], v[88:89], v[92:93]
	v_pk_mul_f32 v[90:91], v[90:91], v[94:95]
	s_nop 0
	v_pk_mul_f32 v[90:91], v[82:83], v[90:91]
	v_pk_mul_f32 v[82:83], v[80:81], v[88:89]
	v_cvt_pk_bf16_f32 v80, v84, v85
	v_mad_i64_i32 v[84:85], s[14:15], v160, s68, v[112:113]
	v_cvt_pk_bf16_f32 v81, v86, v87
	v_cvt_pk_bf16_f32 v82, v82, v83
	v_cvt_pk_bf16_f32 v83, v90, v91
	v_lshl_add_u64 v[84:85], v[84:85], 0, v[114:115]
	global_store_dwordx4 v[84:85], v[80:83], off
	s_nop 1
	v_mul_f32_e32 v80, 0xbfb8aa3b, v76
	v_mul_f32_e32 v81, 0xbfb8aa3b, v77
	v_mul_f32_e32 v82, 0xbfb8aa3b, v78
	v_mul_f32_e32 v83, 0xbfb8aa3b, v79
	v_exp_f32_e32 v80, v80
; __device__ __forceinline__ unsigned cvt_pk_bf16(float lo, float hi) { unsigned r; asm volatile("v_cvt_pk_bf16_f32 %0, %1, %2" : "=v"(r) : "v"(lo), "v"(hi)); return r; }
; __device__ __forceinline__ float silu_f(float v) { return v * __builtin_amdgcn_rcpf(1.0f + __builtin_amdgcn_exp2f(v * -1.4426950408889634f)); }
; __device__ __forceinline__ f32x4 silu4(f32x4 v) { return (f32x4){silu_f(v[0]), silu_f(v[1]), silu_f(v[2]), silu_f(v[3])}; }
; __device__ __forceinline__ float sq4(f32x4 v) { return (v[0] * v[0] + v[1] * v[1]) + (v[2] * v[2] + v[3] * v[3]); }
; __device__ __forceinline__ u32x4 pack8(f32x4 a, f32x4 b) { u32x4 w; w.x = cvt_pk_bf16(a[0], a[1]); w.y = cvt_pk_bf16(a[2], a[3]); w.z = cvt_pk_bf16(b[0], b[1]); w.w = cvt_pk_bf16(b[2], b[3]); return w; }
;     __device__ __forceinline__ void operator()(const f32x4 (&acc)[2][2][4][2], const Unit& u, int wr, int wc, int fr, int fq) const {
;     ...
;         for (int ai = 0; ai < 2; ++ai)
; #pragma unroll
;             for (int m = 0; m < 4; ++m) {
;                 const int row = u.pm * BM + ai * HALF + wr * 64 + m * 16 + fr;
;                 const float rstd = rs[ai][m];
;                 const f32x4 a0 = silu4(acc[ai][0][m][0] * rstd) * (acc[ai][1][m][0] * rstd);
;                 const f32x4 a1 = silu4(acc[ai][0][m][1] * rstd) * (acc[ai][1][m][1] * rstd);
;                 *(u32x4*)(ACT + (size_t)row * 2816 + col0) = pack8(a0, a1);
;             }
	v_exp_f32_e32 v81, v81
	v_exp_f32_e32 v82, v82
	v_exp_f32_e32 v83, v83
	v_add_f32_e32 v80, 1.0, v80
	v_add_f32_e32 v81, 1.0, v81
	v_add_f32_e32 v82, 1.0, v82
	v_add_f32_e32 v83, 1.0, v83
	v_rcp_f32_e32 v80, v80
	v_rcp_f32_e32 v81, v81
	v_rcp_f32_e32 v82, v82
	v_rcp_f32_e32 v83, v83
	v_pk_mul_f32 v[76:77], v[76:77], v[80:81]
	s_nop 0
	v_pk_mul_f32 v[68:69], v[68:69], v[76:77]
	v_pk_mul_f32 v[78:79], v[78:79], v[82:83]
	v_mul_f32_e32 v76, 0xbfb8aa3b, v72
	v_pk_mul_f32 v[70:71], v[70:71], v[78:79]
	v_mul_f32_e32 v77, 0xbfb8aa3b, v73
	v_mul_f32_e32 v78, 0xbfb8aa3b, v74
	v_mul_f32_e32 v79, 0xbfb8aa3b, v75
	v_exp_f32_e32 v76, v76
	v_exp_f32_e32 v77, v77
	v_exp_f32_e32 v78, v78
	v_exp_f32_e32 v79, v79
	v_add_f32_e32 v76, 1.0, v76
	v_add_f32_e32 v77, 1.0, v77
	v_add_f32_e32 v78, 1.0, v78
	v_add_f32_e32 v79, 1.0, v79
	v_rcp_f32_e32 v76, v76
	v_rcp_f32_e32 v77, v77
	v_rcp_f32_e32 v78, v78
	v_rcp_f32_e32 v79, v79
	v_pk_mul_f32 v[72:73], v[72:73], v[76:77]
	v_pk_mul_f32 v[74:75], v[74:75], v[78:79]
	s_nop 0
	v_pk_mul_f32 v[74:75], v[66:67], v[74:75]
	v_pk_mul_f32 v[66:67], v[64:65], v[72:73]
	v_cvt_pk_bf16_f32 v64, v68, v69
	v_mad_i64_i32 v[68:69], s[14:15], v156, s68, v[112:113]
	v_cvt_pk_bf16_f32 v65, v70, v71
	v_cvt_pk_bf16_f32 v66, v66, v67
	v_cvt_pk_bf16_f32 v67, v74, v75
	v_lshl_add_u64 v[68:69], v[68:69], 0, v[114:115]
	global_store_dwordx4 v[68:69], v[64:67], off
	s_nop 1
	v_mul_f32_e32 v64, 0xbfb8aa3b, v60
	v_mul_f32_e32 v65, 0xbfb8aa3b, v61
	v_mul_f32_e32 v66, 0xbfb8aa3b, v62
	v_mul_f32_e32 v67, 0xbfb8aa3b, v63
	v_exp_f32_e32 v64, v64
	v_exp_f32_e32 v65, v65
	v_exp_f32_e32 v66, v66
	v_exp_f32_e32 v67, v67
	v_add_f32_e32 v64, 1.0, v64
	v_add_f32_e32 v65, 1.0, v65
	v_add_f32_e32 v66, 1.0, v66
	v_add_f32_e32 v67, 1.0, v67
	v_rcp_f32_e32 v64, v64
	v_rcp_f32_e32 v65, v65
	v_rcp_f32_e32 v66, v66
	v_rcp_f32_e32 v67, v67
	v_pk_mul_f32 v[60:61], v[60:61], v[64:65]
	s_nop 0
	v_pk_mul_f32 v[52:53], v[52:53], v[60:61]
	v_pk_mul_f32 v[62:63], v[62:63], v[66:67]
	v_mul_f32_e32 v60, 0xbfb8aa3b, v56
	v_pk_mul_f32 v[54:55], v[54:55], v[62:63]
	v_mul_f32_e32 v61, 0xbfb8aa3b, v57
	v_mul_f32_e32 v62, 0xbfb8aa3b, v58
	v_mul_f32_e32 v63, 0xbfb8aa3b, v59
	v_exp_f32_e32 v60, v60
	v_exp_f32_e32 v61, v61
	v_exp_f32_e32 v62, v62
	v_exp_f32_e32 v63, v63
	v_add_f32_e32 v60, 1.0, v60
	v_add_f32_e32 v61, 1.0, v61
	v_add_f32_e32 v62, 1.0, v62
	v_add_f32_e32 v63, 1.0, v63
	v_rcp_f32_e32 v60, v60
	v_rcp_f32_e32 v61, v61
	v_rcp_f32_e32 v62, v62
	v_rcp_f32_e32 v63, v63
	v_pk_mul_f32 v[56:57], v[56:57], v[60:61]
	v_pk_mul_f32 v[58:59], v[58:59], v[62:63]
	s_nop 0
	v_pk_mul_f32 v[58:59], v[50:51], v[58:59]
	v_pk_mul_f32 v[50:51], v[48:49], v[56:57]
	v_cvt_pk_bf16_f32 v48, v52, v53
	v_mad_i64_i32 v[52:53], s[14:15], v152, s68, v[112:113]
	v_cvt_pk_bf16_f32 v49, v54, v55
	v_cvt_pk_bf16_f32 v50, v50, v51
	v_cvt_pk_bf16_f32 v51, v58, v59
	v_lshl_add_u64 v[52:53], v[52:53], 0, v[114:115]
	global_store_dwordx4 v[52:53], v[48:51], off
	s_nop 1
	v_mul_f32_e32 v48, 0xbfb8aa3b, v44
	v_mul_f32_e32 v49, 0xbfb8aa3b, v45
	v_mul_f32_e32 v50, 0xbfb8aa3b, v46
	v_mul_f32_e32 v51, 0xbfb8aa3b, v47
	v_exp_f32_e32 v48, v48
	v_exp_f32_e32 v49, v49
	v_exp_f32_e32 v50, v50
	v_exp_f32_e32 v51, v51
	v_add_f32_e32 v48, 1.0, v48
	v_add_f32_e32 v49, 1.0, v49
	v_add_f32_e32 v50, 1.0, v50
	v_add_f32_e32 v51, 1.0, v51
	v_rcp_f32_e32 v48, v48
	v_rcp_f32_e32 v49, v49
	v_rcp_f32_e32 v50, v50
	v_rcp_f32_e32 v51, v51
	v_pk_mul_f32 v[44:45], v[44:45], v[48:49]
	s_nop 0
	v_pk_mul_f32 v[36:37], v[36:37], v[44:45]
	v_pk_mul_f32 v[46:47], v[46:47], v[50:51]
	v_mul_f32_e32 v44, 0xbfb8aa3b, v40
	v_pk_mul_f32 v[38:39], v[38:39], v[46:47]
	v_mul_f32_e32 v45, 0xbfb8aa3b, v41
	v_mul_f32_e32 v46, 0xbfb8aa3b, v42
	v_mul_f32_e32 v47, 0xbfb8aa3b, v43
	v_exp_f32_e32 v44, v44
	v_exp_f32_e32 v45, v45
	v_exp_f32_e32 v46, v46
	v_exp_f32_e32 v47, v47
	v_add_f32_e32 v44, 1.0, v44
; __device__ __forceinline__ unsigned cvt_pk_bf16(float lo, float hi) { unsigned r; asm volatile("v_cvt_pk_bf16_f32 %0, %1, %2" : "=v"(r) : "v"(lo), "v"(hi)); return r; }
; __device__ __forceinline__ float silu_f(float v) { return v * __builtin_amdgcn_rcpf(1.0f + __builtin_amdgcn_exp2f(v * -1.4426950408889634f)); }
; __device__ __forceinline__ f32x4 silu4(f32x4 v) { return (f32x4){silu_f(v[0]), silu_f(v[1]), silu_f(v[2]), silu_f(v[3])}; }
; __device__ __forceinline__ float sq4(f32x4 v) { return (v[0] * v[0] + v[1] * v[1]) + (v[2] * v[2] + v[3] * v[3]); }
; __device__ __forceinline__ u32x4 pack8(f32x4 a, f32x4 b) { u32x4 w; w.x = cvt_pk_bf16(a[0], a[1]); w.y = cvt_pk_bf16(a[2], a[3]); w.z = cvt_pk_bf16(b[0], b[1]); w.w = cvt_pk_bf16(b[2], b[3]); return w; }
;     __device__ __forceinline__ void operator()(const f32x4 (&acc)[2][2][4][2], const Unit& u, int wr, int wc, int fr, int fq) const {
;     ...
;         for (int ai = 0; ai < 2; ++ai)
; #pragma unroll
;             for (int m = 0; m < 4; ++m) {
;                 const int row = u.pm * BM + ai * HALF + wr * 64 + m * 16 + fr;
;                 const float rstd = rs[ai][m];
;                 const f32x4 a0 = silu4(acc[ai][0][m][0] * rstd) * (acc[ai][1][m][0] * rstd);
;                 const f32x4 a1 = silu4(acc[ai][0][m][1] * rstd) * (acc[ai][1][m][1] * rstd);
;                 *(u32x4*)(ACT + (size_t)row * 2816 + col0) = pack8(a0, a1);
;             }
	v_add_f32_e32 v45, 1.0, v45
	v_add_f32_e32 v46, 1.0, v46
	v_add_f32_e32 v47, 1.0, v47
	v_rcp_f32_e32 v44, v44
	v_rcp_f32_e32 v45, v45
	v_rcp_f32_e32 v46, v46
	v_rcp_f32_e32 v47, v47
	v_pk_mul_f32 v[40:41], v[40:41], v[44:45]
	v_pk_mul_f32 v[42:43], v[42:43], v[46:47]
	s_nop 0
	v_pk_mul_f32 v[42:43], v[34:35], v[42:43]
	v_pk_mul_f32 v[34:35], v[32:33], v[40:41]
	v_cvt_pk_bf16_f32 v32, v36, v37
	v_mad_i64_i32 v[36:37], s[14:15], v150, s68, v[112:113]
	v_cvt_pk_bf16_f32 v33, v38, v39
	v_cvt_pk_bf16_f32 v34, v34, v35
	v_cvt_pk_bf16_f32 v35, v42, v43
	v_lshl_add_u64 v[36:37], v[36:37], 0, v[114:115]
	global_store_dwordx4 v[36:37], v[32:35], off
	s_nop 1
	v_mul_f32_e32 v32, 0xbfb8aa3b, v28
	v_mul_f32_e32 v33, 0xbfb8aa3b, v29
	v_mul_f32_e32 v34, 0xbfb8aa3b, v30
	v_mul_f32_e32 v35, 0xbfb8aa3b, v31
	v_exp_f32_e32 v32, v32
	v_exp_f32_e32 v33, v33
	v_exp_f32_e32 v34, v34
	v_exp_f32_e32 v35, v35
	v_add_f32_e32 v32, 1.0, v32
	v_add_f32_e32 v33, 1.0, v33
	v_add_f32_e32 v34, 1.0, v34
	v_add_f32_e32 v35, 1.0, v35
	v_rcp_f32_e32 v32, v32
	v_rcp_f32_e32 v33, v33
	v_rcp_f32_e32 v34, v34
	v_rcp_f32_e32 v35, v35
	v_pk_mul_f32 v[28:29], v[28:29], v[32:33]
	s_nop 0
	v_pk_mul_f32 v[20:21], v[20:21], v[28:29]
	v_pk_mul_f32 v[30:31], v[30:31], v[34:35]
	v_mul_f32_e32 v28, 0xbfb8aa3b, v24
	v_pk_mul_f32 v[22:23], v[22:23], v[30:31]
	v_mul_f32_e32 v29, 0xbfb8aa3b, v25
	v_mul_f32_e32 v30, 0xbfb8aa3b, v26
	v_mul_f32_e32 v31, 0xbfb8aa3b, v27
	v_exp_f32_e32 v28, v28
	v_exp_f32_e32 v29, v29
	v_exp_f32_e32 v30, v30
	v_exp_f32_e32 v31, v31
	v_add_f32_e32 v28, 1.0, v28
	v_add_f32_e32 v29, 1.0, v29
	v_add_f32_e32 v30, 1.0, v30
	v_add_f32_e32 v31, 1.0, v31
	v_rcp_f32_e32 v28, v28
	v_rcp_f32_e32 v29, v29
	v_rcp_f32_e32 v30, v30
	v_rcp_f32_e32 v31, v31
	v_pk_mul_f32 v[24:25], v[24:25], v[28:29]
	v_pk_mul_f32 v[26:27], v[26:27], v[30:31]
	s_nop 0
	v_pk_mul_f32 v[26:27], v[18:19], v[26:27]
	v_pk_mul_f32 v[18:19], v[16:17], v[24:25]
	v_cvt_pk_bf16_f32 v16, v20, v21
	v_mad_i64_i32 v[20:21], s[14:15], v148, s68, v[112:113]
	v_cvt_pk_bf16_f32 v17, v22, v23
	v_cvt_pk_bf16_f32 v18, v18, v19
	v_cvt_pk_bf16_f32 v19, v26, v27
	v_lshl_add_u64 v[20:21], v[20:21], 0, v[114:115]
	global_store_dwordx4 v[20:21], v[16:19], off
	s_nop 1
	v_mul_f32_e32 v16, 0xbfb8aa3b, v12
	v_mul_f32_e32 v17, 0xbfb8aa3b, v13
	v_mul_f32_e32 v18, 0xbfb8aa3b, v14
	v_mul_f32_e32 v19, 0xbfb8aa3b, v15
	v_exp_f32_e32 v16, v16
	v_exp_f32_e32 v17, v17
	v_exp_f32_e32 v18, v18
	v_exp_f32_e32 v19, v19
	v_add_f32_e32 v16, 1.0, v16
	v_add_f32_e32 v17, 1.0, v17
	v_add_f32_e32 v18, 1.0, v18
	v_add_f32_e32 v19, 1.0, v19
	v_rcp_f32_e32 v16, v16
	v_rcp_f32_e32 v17, v17
	v_rcp_f32_e32 v18, v18
	v_rcp_f32_e32 v19, v19
	v_pk_mul_f32 v[12:13], v[12:13], v[16:17]
	s_nop 0
	v_pk_mul_f32 v[4:5], v[4:5], v[12:13]
	v_pk_mul_f32 v[14:15], v[14:15], v[18:19]
	v_mul_f32_e32 v12, 0xbfb8aa3b, v8
	v_pk_mul_f32 v[6:7], v[6:7], v[14:15]
	v_mul_f32_e32 v13, 0xbfb8aa3b, v9
	v_mul_f32_e32 v14, 0xbfb8aa3b, v10
	v_mul_f32_e32 v15, 0xbfb8aa3b, v11
	v_exp_f32_e32 v12, v12
	v_exp_f32_e32 v13, v13
	v_exp_f32_e32 v14, v14
	v_exp_f32_e32 v15, v15
	v_add_f32_e32 v12, 1.0, v12
	v_add_f32_e32 v13, 1.0, v13
	v_add_f32_e32 v14, 1.0, v14
	v_add_f32_e32 v15, 1.0, v15
	v_rcp_f32_e32 v12, v12
	v_rcp_f32_e32 v13, v13
	v_rcp_f32_e32 v14, v14
	v_rcp_f32_e32 v15, v15
	v_pk_mul_f32 v[8:9], v[8:9], v[12:13]
	v_pk_mul_f32 v[10:11], v[10:11], v[14:15]
	s_nop 0
	v_pk_mul_f32 v[10:11], v[2:3], v[10:11]
	v_pk_mul_f32 v[2:3], v[0:1], v[8:9]
	v_cvt_pk_bf16_f32 v0, v4, v5
	v_mad_i64_i32 v[4:5], s[14:15], v146, s68, v[112:113]
	v_lshl_add_u64 v[4:5], v[4:5], 0, v[114:115]
	v_cvt_pk_bf16_f32 v1, v6, v7
	v_cvt_pk_bf16_f32 v2, v2, v3
	v_cvt_pk_bf16_f32 v3, v10, v11
	global_store_dwordx4 v[4:5], v[0:3], off
	s_cbranch_vccnz .LBB0_992
	s_andn2_b64 vcc, exec, s[18:19]
	s_cbranch_vccnz .LBB0_991
	s_barrier
	s_branch .LBB0_991

; __device__ __forceinline__ float row_part(const float* ss, int row, int fq) { const f32x4 a = ((const f32x4*)(ss + (size_t)row * 16))[fq]; return (a[0] + a[1]) + (a[2] + a[3]); }
; __device__ __forceinline__ float row_finish(float t) { t += shx(t, 16); t += shx(t, 32); return __builtin_amdgcn_rsqf(t * (1.0f / 1024.0f) + RMS_EPS); }
;     __device__ __forceinline__ void operator()(const f32x4 (&acc)[2][2][4][2], const Unit& u, int wr, int wc, int fr, int fq) const {
;     ...
;         float rs[2][4];
; #pragma unroll
;         for (int ai = 0; ai < 2; ++ai)
; #pragma unroll
;             for (int m = 0; m < 4; ++m) rs[ai][m] = row_part(ss, u.pm * BM + ai * HALF + wr * 64 + m * 16 + fr, fq);
; #pragma unroll
;         for (int ai = 0; ai < 2; ++ai)
; #pragma unroll
;             for (int m = 0; m < 4; ++m) rs[ai][m] = row_finish(rs[ai][m]);
.LBB0_1591:
	s_lshr_b32 s98, s2, 6
	s_cmp_lg_u32 s61, s98
	s_cbranch_scc1 .Lrsf_2
	v_lshl_add_u32 v170, s44, 8, v153
	v_ashrrev_i32_e32 v171, 31, v170
	v_or_b32_e32 v166, 16, v170
	v_lshlrev_b64 v[146:147], 6, v[170:171]
	v_ashrrev_i32_e32 v167, 31, v166
	v_lshl_add_u64 v[146:147], v[136:137], 0, v[146:147]
	v_lshlrev_b64 v[148:149], 6, v[166:167]
	v_lshl_add_u64 v[148:149], v[136:137], 0, v[148:149]
	ds_read_b128 v[176:179], v239
	ds_read_b128 v[180:183], v239 offset:1024
	v_or_b32_e32 v162, 32, v170
	v_ashrrev_i32_e32 v163, 31, v162
	v_or_b32_e32 v158, 48, v170
	v_lshlrev_b64 v[146:147], 6, v[162:163]
	v_ashrrev_i32_e32 v159, 31, v158
	v_lshl_add_u64 v[146:147], v[136:137], 0, v[146:147]
	v_lshlrev_b64 v[148:149], 6, v[158:159]
	v_lshl_add_u64 v[148:149], v[136:137], 0, v[148:149]
	ds_read_b128 v[184:187], v239 offset:2048
	ds_read_b128 v[188:191], v239 offset:3072
	v_add_u32_e32 v154, 0x80, v170
	v_ashrrev_i32_e32 v155, 31, v154
	v_add_u32_e32 v150, 0x90, v170
	v_lshlrev_b64 v[146:147], 6, v[154:155]
	v_ashrrev_i32_e32 v151, 31, v150
	v_lshl_add_u64 v[146:147], v[136:137], 0, v[146:147]
	v_lshlrev_b64 v[148:149], 6, v[150:151]
	v_lshl_add_u64 v[148:149], v[136:137], 0, v[148:149]
	ds_read_b128 v[192:195], v239 offset:8192
	ds_read_b128 v[196:199], v239 offset:9216
	v_add_u32_e32 v148, 0xa0, v170
	v_ashrrev_i32_e32 v149, 31, v148
	v_lshlrev_b64 v[146:147], 6, v[148:149]
	v_lshl_add_u64 v[146:147], v[136:137], 0, v[146:147]
	ds_read_b128 v[202:205], v239 offset:10240
	v_add_u32_e32 v146, 0xb0, v170
	v_ashrrev_i32_e32 v147, 31, v146
	v_lshlrev_b64 v[206:207], 6, v[146:147]
	v_lshl_add_u64 v[206:207], v[136:137], 0, v[206:207]
	ds_read_b128 v[206:209], v239 offset:11264
	v_mov_b32_e32 v147, v201
	v_mov_b32_e32 v149, v201
	v_lshlrev_b32_e32 v147, 2, v147
	v_mov_b32_e32 v151, v201
	v_xor_b32_e32 v147, 64, v147
	s_andn2_b64 vcc, exec, s[8:9]
	v_lshlrev_b32_e32 v151, 2, v151
	v_xor_b32_e32 v151, 64, v151
	v_lshlrev_b32_e32 v149, 2, v149
	v_xor_b32_e32 v149, 0x80, v149
	s_mov_b64 s[8:9], -1
	s_waitcnt lgkmcnt(0)
	v_mov_b32_e32 v210, v177
	v_mov_b32_e32 v211, v178
	v_mov_b32_e32 v177, v179
	v_pk_add_f32 v[176:177], v[210:211], v[176:177]
	v_mov_b32_e32 v178, v181
	v_add_f32_e32 v152, v176, v177
	v_mov_b32_e32 v179, v182
	v_mov_b32_e32 v181, v183
	v_mov_b32_e32 v147, v152
	s_nop 1
	v_permlane16_swap_b32_e32 v147, v152
	v_pk_add_f32 v[176:177], v[178:179], v[180:181]
	v_mov_b32_e32 v182, v185
	v_add_f32_e32 v155, v176, v177
	v_mov_b32_e32 v151, v155
	s_nop 1
	v_permlane16_swap_b32_e32 v151, v155
	s_waitcnt lgkmcnt(0)
	v_add_f32_e32 v147, v152, v147
	v_mov_b32_e32 v152, v201
	v_mov_b32_e32 v149, v147
	s_nop 1
	v_permlane32_swap_b32_e32 v149, v147
	s_waitcnt lgkmcnt(0)
	v_add_f32_e32 v151, v155, v151
	v_lshlrev_b32_e32 v152, 2, v152
	v_xor_b32_e32 v152, 0x80, v152
	v_mov_b32_e32 v152, v151
	s_nop 1
	v_permlane32_swap_b32_e32 v152, v151
	s_waitcnt lgkmcnt(0)
	v_add_f32_e32 v147, v147, v149
	v_mov_b32_e32 v149, v201
	v_mov_b32_e32 v183, v186
	v_mov_b32_e32 v185, v187
	v_pk_add_f32 v[178:179], v[182:183], v[184:185]
	v_fmamk_f32 v147, v147, 0x3a800000, v175
	v_lshlrev_b32_e32 v149, 2, v149
	v_add_f32_e32 v156, v178, v179
	v_rsq_f32_e32 v176, v147
	s_waitcnt lgkmcnt(0)
	v_add_f32_e32 v147, v151, v152
	v_xor_b32_e32 v149, 64, v149
	v_mov_b32_e32 v151, v201
	v_mov_b32_e32 v152, v201
	v_mov_b32_e32 v186, v189
	v_mov_b32_e32 v187, v190
	v_mov_b32_e32 v189, v191
	v_mov_b32_e32 v149, v156
	s_nop 1
	v_permlane16_swap_b32_e32 v149, v156
	v_pk_add_f32 v[180:181], v[186:187], v[188:189]
	v_lshlrev_b32_e32 v152, 2, v152
	v_add_f32_e32 v159, v180, v181
	v_xor_b32_e32 v152, 64, v152
	v_mov_b32_e32 v152, v159
	s_nop 1
	v_permlane16_swap_b32_e32 v152, v159
	s_waitcnt lgkmcnt(0)
	v_add_f32_e32 v149, v156, v149
	v_lshlrev_b32_e32 v151, 2, v151
	v_mov_b32_e32 v156, v201
	v_xor_b32_e32 v151, 0x80, v151
	v_mov_b32_e32 v151, v149
	s_nop 1
	v_permlane32_swap_b32_e32 v151, v149
	v_lshlrev_b32_e32 v156, 2, v156
	s_waitcnt lgkmcnt(0)
	v_add_f32_e32 v152, v159, v152
	v_xor_b32_e32 v156, 0x80, v156
	v_mov_b32_e32 v156, v152
	s_nop 1
	v_permlane32_swap_b32_e32 v156, v152
	v_fmamk_f32 v147, v147, 0x3a800000, v175
	v_rsq_f32_e32 v174, v147
	s_waitcnt lgkmcnt(0)
	v_add_f32_e32 v147, v149, v151
	v_mov_b32_e32 v149, v201
	v_mov_b32_e32 v190, v193
	v_mov_b32_e32 v191, v194
	v_mov_b32_e32 v193, v195
	v_fmamk_f32 v147, v147, 0x3a800000, v175
	v_pk_add_f32 v[182:183], v[190:191], v[192:193]
	v_rsq_f32_e32 v172, v147
	s_waitcnt lgkmcnt(0)
	v_add_f32_e32 v147, v152, v156
	v_lshlrev_b32_e32 v149, 2, v149
	v_mov_b32_e32 v151, v201
	v_mov_b32_e32 v152, v201
	v_mov_b32_e32 v194, v197
	v_mov_b32_e32 v195, v198
	v_mov_b32_e32 v197, v199
	v_add_f32_e32 v160, v182, v183
	v_xor_b32_e32 v149, 64, v149
	v_pk_add_f32 v[184:185], v[194:195], v[196:197]
	v_mov_b32_e32 v149, v160
	s_nop 1
	v_permlane16_swap_b32_e32 v149, v160
	v_lshlrev_b32_e32 v152, 2, v152
	v_add_f32_e32 v163, v184, v185
	v_xor_b32_e32 v152, 64, v152
	v_mov_b32_e32 v152, v163
	s_nop 1
	v_permlane16_swap_b32_e32 v152, v163
	v_lshlrev_b32_e32 v151, 2, v151
	v_mov_b32_e32 v156, v201
	s_waitcnt lgkmcnt(0)
	v_add_f32_e32 v149, v160, v149
	v_xor_b32_e32 v151, 0x80, v151
	v_mov_b32_e32 v151, v149
	s_nop 1
	v_permlane32_swap_b32_e32 v151, v149
	v_lshlrev_b32_e32 v156, 2, v156
	s_waitcnt lgkmcnt(0)
	v_add_f32_e32 v152, v163, v152
	v_xor_b32_e32 v156, 0x80, v156
	v_mov_b32_e32 v156, v152
	s_nop 1
	v_permlane32_swap_b32_e32 v156, v152
	v_fmamk_f32 v147, v147, 0x3a800000, v175
	v_rsq_f32_e32 v168, v147
	s_waitcnt lgkmcnt(0)
	v_add_f32_e32 v147, v149, v151
	v_fmamk_f32 v147, v147, 0x3a800000, v175
	v_rsq_f32_e32 v164, v147
	s_waitcnt lgkmcnt(0)
; __device__ __forceinline__ float row_part(const float* ss, int row, int fq) { const f32x4 a = ((const f32x4*)(ss + (size_t)row * 16))[fq]; return (a[0] + a[1]) + (a[2] + a[3]); }
; __device__ __forceinline__ float row_finish(float t) { t += shx(t, 16); t += shx(t, 32); return __builtin_amdgcn_rsqf(t * (1.0f / 1024.0f) + RMS_EPS); }
; __device__ __forceinline__ f32x4 silu4(f32x4 v) { return (f32x4){silu_f(v[0]), silu_f(v[1]), silu_f(v[2]), silu_f(v[3])}; }
; __device__ __forceinline__ u32x4 pack8(f32x4 a, f32x4 b) { u32x4 w; w.x = cvt_pk_bf16(a[0], a[1]); w.y = cvt_pk_bf16(a[2], a[3]); w.z = cvt_pk_bf16(b[0], b[1]); w.w = cvt_pk_bf16(b[2], b[3]); return w; }
;     __device__ __forceinline__ void operator()(const f32x4 (&acc)[2][2][4][2], const Unit& u, int wr, int wc, int fr, int fq) const {
;     ...
;         float rs[2][4];
; #pragma unroll
;         for (int ai = 0; ai < 2; ++ai)
; #pragma unroll
;             for (int m = 0; m < 4; ++m) rs[ai][m] = row_part(ss, u.pm * BM + ai * HALF + wr * 64 + m * 16 + fr, fq);
; #pragma unroll
;         for (int ai = 0; ai < 2; ++ai)
; #pragma unroll
;             for (int m = 0; m < 4; ++m) rs[ai][m] = row_finish(rs[ai][m]);
; #pragma unroll
;         for (int ai = 0; ai < 2; ++ai)
; #pragma unroll
;             for (int m = 0; m < 4; ++m) {
;                 const int row = u.pm * BM + ai * HALF + wr * 64 + m * 16 + fr;
;                 const float rstd = rs[ai][m];
;                 const f32x4 a0 = silu4(acc[ai][0][m][0] * rstd) * (acc[ai][1][m][0] * rstd);
;                 const f32x4 a1 = silu4(acc[ai][0][m][1] * rstd) * (acc[ai][1][m][1] * rstd);
;                 *(u32x4*)(ACT + (size_t)row * 2816 + col0) = pack8(a0, a1);
;             }
	v_add_f32_e32 v147, v152, v156
	v_mov_b32_e32 v149, v201
	v_mov_b32_e32 v151, v201
	v_mov_b32_e32 v152, v201
	v_mov_b32_e32 v198, v203
	v_mov_b32_e32 v199, v204
	v_mov_b32_e32 v203, v205
	v_mov_b32_e32 v204, v207
	v_mov_b32_e32 v205, v208
	v_mov_b32_e32 v207, v209
	v_pk_add_f32 v[188:189], v[204:205], v[206:207]
	v_lshlrev_b32_e32 v152, 2, v152
	v_pk_add_f32 v[186:187], v[198:199], v[202:203]
	v_add_f32_e32 v155, v188, v189
	v_lshlrev_b32_e32 v149, 2, v149
	v_xor_b32_e32 v152, 64, v152
	v_add_f32_e32 v167, v186, v187
	v_xor_b32_e32 v149, 64, v149
	v_mov_b32_e32 v152, v155
	s_nop 1
	v_permlane16_swap_b32_e32 v152, v155
	v_mov_b32_e32 v149, v167
	s_nop 1
	v_permlane16_swap_b32_e32 v149, v167
	v_lshlrev_b32_e32 v151, 2, v151
	v_xor_b32_e32 v151, 0x80, v151
	v_fmamk_f32 v147, v147, 0x3a800000, v175
	s_waitcnt lgkmcnt(0)
	v_add_f32_e32 v152, v155, v152
	v_mov_b32_e32 v155, v201
	s_waitcnt lgkmcnt(0)
	v_add_f32_e32 v149, v167, v149
	v_mov_b32_e32 v151, v149
	s_nop 1
	v_permlane32_swap_b32_e32 v151, v149
	v_lshlrev_b32_e32 v155, 2, v155
	v_xor_b32_e32 v155, 0x80, v155
	v_mov_b32_e32 v155, v152
	s_nop 1
	v_permlane32_swap_b32_e32 v155, v152
	v_rsq_f32_e32 v160, v147
	s_waitcnt lgkmcnt(0)
	v_add_f32_e32 v147, v149, v151
	v_fmamk_f32 v147, v147, 0x3a800000, v175
	v_rsq_f32_e32 v156, v147
	s_waitcnt lgkmcnt(0)
	v_add_f32_e32 v147, v152, v155
	v_fmamk_f32 v147, v147, 0x3a800000, v175
	v_pk_mul_f32 v[124:125], v[124:125], v[176:177] op_sel_hi:[1,0]
	v_rsq_f32_e32 v152, v147
	v_lshlrev_b32_e32 v251, 5, v153
	v_add_u32_e32 v251, 0x24080, v251
	ds_write_b32 v251, v176
	ds_write_b32 v251, v174 offset:4
	ds_write_b32 v251, v172 offset:8
	ds_write_b32 v251, v168 offset:12
	ds_write_b32 v251, v164 offset:16
	ds_write_b32 v251, v160 offset:20
	ds_write_b32 v251, v156 offset:24
	ds_write_b32 v251, v152 offset:28
	s_branch .Lrsj_2
.Lrsf_2:
	v_lshlrev_b32_e32 v251, 5, v153
	v_add_u32_e32 v251, 0x24080, v251
	ds_read_b32 v176, v251
	ds_read_b32 v174, v251 offset:4
	ds_read_b32 v172, v251 offset:8
	ds_read_b32 v168, v251 offset:12
	ds_read_b32 v164, v251 offset:16
	ds_read_b32 v160, v251 offset:20
	ds_read_b32 v156, v251 offset:24
	ds_read_b32 v152, v251 offset:28
	s_waitcnt lgkmcnt(0)
	v_lshl_add_u32 v170, s44, 8, v153
	v_or_b32_e32 v166, 16, v170
	v_or_b32_e32 v162, 32, v170
	v_or_b32_e32 v158, 48, v170
	v_add_u32_e32 v154, 0x80, v170
	v_add_u32_e32 v150, 0x90, v170
	v_add_u32_e32 v148, 0xa0, v170
	v_add_u32_e32 v146, 0xb0, v170
	s_andn2_b64 vcc, exec, s[8:9]
	s_mov_b64 s[8:9], -1
	s_waitcnt lgkmcnt(0)
	s_waitcnt lgkmcnt(0)
	s_waitcnt lgkmcnt(0)
	s_waitcnt lgkmcnt(0)
	s_waitcnt lgkmcnt(0)
	s_waitcnt lgkmcnt(0)
	s_waitcnt lgkmcnt(0)
	s_waitcnt lgkmcnt(0)
	s_waitcnt lgkmcnt(0)
	s_waitcnt lgkmcnt(0)
	s_waitcnt lgkmcnt(0)
	s_waitcnt lgkmcnt(0)
	s_waitcnt lgkmcnt(0)
	s_waitcnt lgkmcnt(0)
	s_waitcnt lgkmcnt(0)
	s_waitcnt lgkmcnt(0)
	s_waitcnt lgkmcnt(0)
	v_pk_mul_f32 v[124:125], v[124:125], v[176:177] op_sel_hi:[1,0]
.Lrsj_2:
	v_mul_f32_e32 v147, 0xbfb8aa3b, v124
	v_exp_f32_e32 v147, v147
	v_mul_f32_e32 v149, 0xbfb8aa3b, v125
	v_exp_f32_e32 v149, v149
	v_pk_mul_f32 v[126:127], v[126:127], v[176:177] op_sel_hi:[1,0]
	v_add_f32_e32 v147, 1.0, v147
	v_rcp_f32_e32 v178, v147
	v_add_f32_e32 v147, 1.0, v149
	v_mul_f32_e32 v149, 0xbfb8aa3b, v126
	v_exp_f32_e32 v149, v149
	v_mul_f32_e32 v151, 0xbfb8aa3b, v127
	v_exp_f32_e32 v151, v151
	v_rcp_f32_e32 v179, v147
	v_add_f32_e32 v147, 1.0, v149
	v_rcp_f32_e32 v180, v147
	v_add_f32_e32 v147, 1.0, v151
	v_pk_mul_f32 v[120:121], v[120:121], v[176:177] op_sel_hi:[1,0]
	v_rcp_f32_e32 v181, v147
	v_mul_f32_e32 v147, 0xbfb8aa3b, v120
	v_exp_f32_e32 v147, v147
	v_mul_f32_e32 v149, 0xbfb8aa3b, v121
	v_exp_f32_e32 v149, v149
	v_pk_mul_f32 v[122:123], v[122:123], v[176:177] op_sel_hi:[1,0]
	v_add_f32_e32 v147, 1.0, v147
	v_pk_mul_f32 v[124:125], v[124:125], v[178:179]
	v_rcp_f32_e32 v178, v147
	v_add_f32_e32 v147, 1.0, v149
	v_mul_f32_e32 v149, 0xbfb8aa3b, v122
	v_exp_f32_e32 v149, v149
	v_mul_f32_e32 v151, 0xbfb8aa3b, v123
	v_exp_f32_e32 v151, v151
	v_rcp_f32_e32 v179, v147
	v_add_f32_e32 v147, 1.0, v149
	v_pk_mul_f32 v[126:127], v[126:127], v[180:181]
	v_rcp_f32_e32 v180, v147
	v_add_f32_e32 v147, 1.0, v151
	v_rcp_f32_e32 v181, v147
	v_pk_mul_f32 v[116:117], v[116:117], v[176:177] op_sel_hi:[1,0]
	v_pk_mul_f32 v[118:119], v[118:119], v[176:177] op_sel_hi:[1,0]
	v_pk_mul_f32 v[120:121], v[120:121], v[178:179]
	v_pk_mul_f32 v[112:113], v[112:113], v[176:177] op_sel_hi:[1,0]
	v_lshl_or_b32 v182, s61, 7, v161
	v_pk_mul_f32 v[118:119], v[118:119], v[126:127]
	v_pk_mul_f32 v[116:117], v[116:117], v[124:125]
	v_pk_mul_f32 v[122:123], v[122:123], v[180:181]
	v_pk_mul_f32 v[114:115], v[114:115], v[176:177] op_sel_hi:[1,0]
	v_pk_mul_f32 v[112:113], v[112:113], v[120:121]
	v_ashrrev_i32_e32 v183, 31, v182
	v_pk_mul_f32 v[114:115], v[114:115], v[122:123]
	v_cvt_pk_bf16_f32 v116, v116, v117
	v_cvt_pk_bf16_f32 v117, v118, v119
	v_cvt_pk_bf16_f32 v118, v112, v113
	v_mov_b64_e32 v[112:113], s[16:17]
	v_cvt_pk_bf16_f32 v119, v114, v115
	v_mad_i64_i32 v[120:121], s[46:47], v170, s60, v[112:113]
	v_lshlrev_b64 v[114:115], 1, v[182:183]
	v_pk_mul_f32 v[108:109], v[108:109], v[174:175] op_sel_hi:[1,0]
	v_pk_mul_f32 v[110:111], v[110:111], v[174:175] op_sel_hi:[1,0]
	v_mul_f32_e32 v122, 0xbfb8aa3b, v108
	v_mul_f32_e32 v123, 0xbfb8aa3b, v109
	v_lshl_add_u64 v[120:121], v[120:121], 0, v[114:115]
	v_pk_mul_f32 v[104:105], v[104:105], v[174:175] op_sel_hi:[1,0]
	v_pk_mul_f32 v[106:107], v[106:107], v[174:175] op_sel_hi:[1,0]
	v_exp_f32_e32 v122, v122
	v_exp_f32_e32 v123, v123
	v_mul_f32_e32 v124, 0xbfb8aa3b, v110
	v_mul_f32_e32 v125, 0xbfb8aa3b, v111
; __device__ __forceinline__ unsigned cvt_pk_bf16(float lo, float hi) { unsigned r; asm volatile("v_cvt_pk_bf16_f32 %0, %1, %2" : "=v"(r) : "v"(lo), "v"(hi)); return r; }
; __device__ __forceinline__ float silu_f(float v) { return v * __builtin_amdgcn_rcpf(1.0f + __builtin_amdgcn_exp2f(v * -1.4426950408889634f)); }
; __device__ __forceinline__ f32x4 silu4(f32x4 v) { return (f32x4){silu_f(v[0]), silu_f(v[1]), silu_f(v[2]), silu_f(v[3])}; }
; __device__ __forceinline__ float sq4(f32x4 v) { return (v[0] * v[0] + v[1] * v[1]) + (v[2] * v[2] + v[3] * v[3]); }
; __device__ __forceinline__ u32x4 pack8(f32x4 a, f32x4 b) { u32x4 w; w.x = cvt_pk_bf16(a[0], a[1]); w.y = cvt_pk_bf16(a[2], a[3]); w.z = cvt_pk_bf16(b[0], b[1]); w.w = cvt_pk_bf16(b[2], b[3]); return w; }
;     __device__ __forceinline__ void operator()(const f32x4 (&acc)[2][2][4][2], const Unit& u, int wr, int wc, int fr, int fq) const {
;     ...
;         for (int ai = 0; ai < 2; ++ai)
; #pragma unroll
;             for (int m = 0; m < 4; ++m) {
;                 const int row = u.pm * BM + ai * HALF + wr * 64 + m * 16 + fr;
;                 const float rstd = rs[ai][m];
;                 const f32x4 a0 = silu4(acc[ai][0][m][0] * rstd) * (acc[ai][1][m][0] * rstd);
;                 const f32x4 a1 = silu4(acc[ai][0][m][1] * rstd) * (acc[ai][1][m][1] * rstd);
;                 *(u32x4*)(ACT + (size_t)row * 2816 + col0) = pack8(a0, a1);
;             }
	global_store_dwordx4 v[120:121], v[116:119], off
	v_exp_f32_e32 v124, v124
	v_exp_f32_e32 v125, v125
	v_mul_f32_e32 v116, 0xbfb8aa3b, v104
	v_mul_f32_e32 v117, 0xbfb8aa3b, v105
	v_mul_f32_e32 v118, 0xbfb8aa3b, v106
	v_mul_f32_e32 v119, 0xbfb8aa3b, v107
	v_exp_f32_e32 v116, v116
	v_exp_f32_e32 v117, v117
	v_exp_f32_e32 v118, v118
	v_exp_f32_e32 v119, v119
	v_add_f32_e32 v122, 1.0, v122
	v_add_f32_e32 v123, 1.0, v123
	v_rcp_f32_e32 v122, v122
	v_rcp_f32_e32 v123, v123
	v_add_f32_e32 v124, 1.0, v124
	v_add_f32_e32 v125, 1.0, v125
	v_add_f32_e32 v116, 1.0, v116
	v_add_f32_e32 v117, 1.0, v117
	v_add_f32_e32 v118, 1.0, v118
	v_add_f32_e32 v119, 1.0, v119
	v_rcp_f32_e32 v124, v124
	v_rcp_f32_e32 v125, v125
	v_rcp_f32_e32 v116, v116
	v_rcp_f32_e32 v117, v117
	v_rcp_f32_e32 v118, v118
	v_rcp_f32_e32 v119, v119
	v_pk_mul_f32 v[108:109], v[108:109], v[122:123]
	v_pk_mul_f32 v[100:101], v[100:101], v[174:175] op_sel_hi:[1,0]
	v_pk_mul_f32 v[110:111], v[110:111], v[124:125]
	v_pk_mul_f32 v[102:103], v[102:103], v[174:175] op_sel_hi:[1,0]
	v_pk_mul_f32 v[100:101], v[100:101], v[108:109]
	v_pk_mul_f32 v[104:105], v[104:105], v[116:117]
	v_pk_mul_f32 v[106:107], v[106:107], v[118:119]
	v_pk_mul_f32 v[96:97], v[96:97], v[174:175] op_sel_hi:[1,0]
	v_pk_mul_f32 v[98:99], v[98:99], v[174:175] op_sel_hi:[1,0]
	v_pk_mul_f32 v[102:103], v[102:103], v[110:111]
	v_pk_mul_f32 v[106:107], v[98:99], v[106:107]
	v_pk_mul_f32 v[98:99], v[96:97], v[104:105]
	v_cvt_pk_bf16_f32 v96, v100, v101
	v_mad_i64_i32 v[100:101], s[46:47], v166, s60, v[112:113]
	v_pk_mul_f32 v[92:93], v[92:93], v[172:173] op_sel_hi:[1,0]
	v_cvt_pk_bf16_f32 v97, v102, v103
	v_cvt_pk_bf16_f32 v98, v98, v99
	v_cvt_pk_bf16_f32 v99, v106, v107
	v_pk_mul_f32 v[94:95], v[94:95], v[172:173] op_sel_hi:[1,0]
	v_mul_f32_e32 v102, 0xbfb8aa3b, v92
	v_mul_f32_e32 v103, 0xbfb8aa3b, v93
	v_lshl_add_u64 v[100:101], v[100:101], 0, v[114:115]
	v_pk_mul_f32 v[88:89], v[88:89], v[172:173] op_sel_hi:[1,0]
	v_pk_mul_f32 v[90:91], v[90:91], v[172:173] op_sel_hi:[1,0]
	v_exp_f32_e32 v102, v102
	v_exp_f32_e32 v103, v103
	v_mul_f32_e32 v104, 0xbfb8aa3b, v94
	v_mul_f32_e32 v105, 0xbfb8aa3b, v95
	global_store_dwordx4 v[100:101], v[96:99], off
	v_exp_f32_e32 v104, v104
	v_exp_f32_e32 v105, v105
	v_mul_f32_e32 v96, 0xbfb8aa3b, v88
	v_mul_f32_e32 v97, 0xbfb8aa3b, v89
	v_mul_f32_e32 v98, 0xbfb8aa3b, v90
	v_mul_f32_e32 v99, 0xbfb8aa3b, v91
	v_exp_f32_e32 v96, v96
	v_exp_f32_e32 v97, v97
	v_exp_f32_e32 v98, v98
	v_exp_f32_e32 v99, v99
	v_add_f32_e32 v102, 1.0, v102
	v_add_f32_e32 v103, 1.0, v103
	v_rcp_f32_e32 v102, v102
	v_rcp_f32_e32 v103, v103
	v_add_f32_e32 v104, 1.0, v104
	v_add_f32_e32 v105, 1.0, v105
	v_add_f32_e32 v96, 1.0, v96
	v_add_f32_e32 v97, 1.0, v97
	v_add_f32_e32 v98, 1.0, v98
	v_add_f32_e32 v99, 1.0, v99
	v_rcp_f32_e32 v104, v104
	v_rcp_f32_e32 v105, v105
	v_rcp_f32_e32 v96, v96
	v_rcp_f32_e32 v97, v97
	v_rcp_f32_e32 v98, v98
	v_rcp_f32_e32 v99, v99
	v_pk_mul_f32 v[92:93], v[92:93], v[102:103]
	v_pk_mul_f32 v[84:85], v[84:85], v[172:173] op_sel_hi:[1,0]
	v_pk_mul_f32 v[94:95], v[94:95], v[104:105]
	v_pk_mul_f32 v[86:87], v[86:87], v[172:173] op_sel_hi:[1,0]
	v_pk_mul_f32 v[84:85], v[84:85], v[92:93]
	v_pk_mul_f32 v[88:89], v[88:89], v[96:97]
	v_pk_mul_f32 v[90:91], v[90:91], v[98:99]
	v_pk_mul_f32 v[80:81], v[80:81], v[172:173] op_sel_hi:[1,0]
	v_pk_mul_f32 v[82:83], v[82:83], v[172:173] op_sel_hi:[1,0]
	v_pk_mul_f32 v[86:87], v[86:87], v[94:95]
	v_pk_mul_f32 v[90:91], v[82:83], v[90:91]
	v_pk_mul_f32 v[82:83], v[80:81], v[88:89]
	v_cvt_pk_bf16_f32 v80, v84, v85
	v_mad_i64_i32 v[84:85], s[46:47], v162, s60, v[112:113]
	v_pk_mul_f32 v[76:77], v[76:77], v[168:169] op_sel_hi:[1,0]
	v_cvt_pk_bf16_f32 v81, v86, v87
	v_cvt_pk_bf16_f32 v82, v82, v83
	v_cvt_pk_bf16_f32 v83, v90, v91
	v_pk_mul_f32 v[78:79], v[78:79], v[168:169] op_sel_hi:[1,0]
	v_mul_f32_e32 v86, 0xbfb8aa3b, v76
	v_mul_f32_e32 v87, 0xbfb8aa3b, v77
	v_lshl_add_u64 v[84:85], v[84:85], 0, v[114:115]
	v_pk_mul_f32 v[72:73], v[72:73], v[168:169] op_sel_hi:[1,0]
	v_pk_mul_f32 v[74:75], v[74:75], v[168:169] op_sel_hi:[1,0]
	v_exp_f32_e32 v86, v86
	v_exp_f32_e32 v87, v87
	v_mul_f32_e32 v88, 0xbfb8aa3b, v78
	v_mul_f32_e32 v89, 0xbfb8aa3b, v79
	global_store_dwordx4 v[84:85], v[80:83], off
	v_exp_f32_e32 v88, v88
	v_exp_f32_e32 v89, v89
	v_mul_f32_e32 v80, 0xbfb8aa3b, v72
	v_mul_f32_e32 v81, 0xbfb8aa3b, v73
	v_mul_f32_e32 v82, 0xbfb8aa3b, v74
	v_mul_f32_e32 v83, 0xbfb8aa3b, v75
	v_exp_f32_e32 v80, v80
	v_exp_f32_e32 v81, v81
	v_exp_f32_e32 v82, v82
	v_exp_f32_e32 v83, v83
	v_add_f32_e32 v86, 1.0, v86
	v_add_f32_e32 v87, 1.0, v87
	v_rcp_f32_e32 v86, v86
	v_rcp_f32_e32 v87, v87
	v_add_f32_e32 v88, 1.0, v88
	v_add_f32_e32 v89, 1.0, v89
	v_add_f32_e32 v80, 1.0, v80
	v_add_f32_e32 v81, 1.0, v81
	v_add_f32_e32 v82, 1.0, v82
	v_add_f32_e32 v83, 1.0, v83
	v_rcp_f32_e32 v88, v88
	v_rcp_f32_e32 v89, v89
	v_rcp_f32_e32 v80, v80
	v_rcp_f32_e32 v81, v81
	v_rcp_f32_e32 v82, v82
	v_rcp_f32_e32 v83, v83
	v_pk_mul_f32 v[76:77], v[76:77], v[86:87]
	v_pk_mul_f32 v[68:69], v[68:69], v[168:169] op_sel_hi:[1,0]
	v_pk_mul_f32 v[78:79], v[78:79], v[88:89]
	v_pk_mul_f32 v[70:71], v[70:71], v[168:169] op_sel_hi:[1,0]
	v_pk_mul_f32 v[68:69], v[68:69], v[76:77]
	v_pk_mul_f32 v[72:73], v[72:73], v[80:81]
	v_pk_mul_f32 v[74:75], v[74:75], v[82:83]
	v_pk_mul_f32 v[64:65], v[64:65], v[168:169] op_sel_hi:[1,0]
	v_pk_mul_f32 v[66:67], v[66:67], v[168:169] op_sel_hi:[1,0]
	v_pk_mul_f32 v[70:71], v[70:71], v[78:79]
	v_pk_mul_f32 v[74:75], v[66:67], v[74:75]
	v_pk_mul_f32 v[66:67], v[64:65], v[72:73]
	v_cvt_pk_bf16_f32 v64, v68, v69
	v_mad_i64_i32 v[68:69], s[46:47], v158, s60, v[112:113]
; __device__ __forceinline__ unsigned cvt_pk_bf16(float lo, float hi) { unsigned r; asm volatile("v_cvt_pk_bf16_f32 %0, %1, %2" : "=v"(r) : "v"(lo), "v"(hi)); return r; }
; __device__ __forceinline__ float silu_f(float v) { return v * __builtin_amdgcn_rcpf(1.0f + __builtin_amdgcn_exp2f(v * -1.4426950408889634f)); }
; __device__ __forceinline__ f32x4 silu4(f32x4 v) { return (f32x4){silu_f(v[0]), silu_f(v[1]), silu_f(v[2]), silu_f(v[3])}; }
; __device__ __forceinline__ float sq4(f32x4 v) { return (v[0] * v[0] + v[1] * v[1]) + (v[2] * v[2] + v[3] * v[3]); }
; __device__ __forceinline__ u32x4 pack8(f32x4 a, f32x4 b) { u32x4 w; w.x = cvt_pk_bf16(a[0], a[1]); w.y = cvt_pk_bf16(a[2], a[3]); w.z = cvt_pk_bf16(b[0], b[1]); w.w = cvt_pk_bf16(b[2], b[3]); return w; }
;     __device__ __forceinline__ void operator()(const f32x4 (&acc)[2][2][4][2], const Unit& u, int wr, int wc, int fr, int fq) const {
;     ...
;         for (int ai = 0; ai < 2; ++ai)
; #pragma unroll
;             for (int m = 0; m < 4; ++m) {
;                 const int row = u.pm * BM + ai * HALF + wr * 64 + m * 16 + fr;
;                 const float rstd = rs[ai][m];
;                 const f32x4 a0 = silu4(acc[ai][0][m][0] * rstd) * (acc[ai][1][m][0] * rstd);
;                 const f32x4 a1 = silu4(acc[ai][0][m][1] * rstd) * (acc[ai][1][m][1] * rstd);
;                 *(u32x4*)(ACT + (size_t)row * 2816 + col0) = pack8(a0, a1);
;             }
	v_pk_mul_f32 v[60:61], v[60:61], v[164:165] op_sel_hi:[1,0]
	v_cvt_pk_bf16_f32 v65, v70, v71
	v_cvt_pk_bf16_f32 v66, v66, v67
	v_cvt_pk_bf16_f32 v67, v74, v75
	v_pk_mul_f32 v[62:63], v[62:63], v[164:165] op_sel_hi:[1,0]
	v_mul_f32_e32 v70, 0xbfb8aa3b, v60
	v_mul_f32_e32 v71, 0xbfb8aa3b, v61
	v_lshl_add_u64 v[68:69], v[68:69], 0, v[114:115]
	v_pk_mul_f32 v[56:57], v[56:57], v[164:165] op_sel_hi:[1,0]
	v_pk_mul_f32 v[58:59], v[58:59], v[164:165] op_sel_hi:[1,0]
	v_exp_f32_e32 v70, v70
	v_exp_f32_e32 v71, v71
	v_mul_f32_e32 v72, 0xbfb8aa3b, v62
	v_mul_f32_e32 v73, 0xbfb8aa3b, v63
	global_store_dwordx4 v[68:69], v[64:67], off
	v_exp_f32_e32 v72, v72
	v_exp_f32_e32 v73, v73
	v_mul_f32_e32 v64, 0xbfb8aa3b, v56
	v_mul_f32_e32 v65, 0xbfb8aa3b, v57
	v_mul_f32_e32 v66, 0xbfb8aa3b, v58
	v_mul_f32_e32 v67, 0xbfb8aa3b, v59
	v_exp_f32_e32 v64, v64
	v_exp_f32_e32 v65, v65
	v_exp_f32_e32 v66, v66
	v_exp_f32_e32 v67, v67
	v_add_f32_e32 v70, 1.0, v70
	v_add_f32_e32 v71, 1.0, v71
	v_rcp_f32_e32 v70, v70
	v_rcp_f32_e32 v71, v71
	v_add_f32_e32 v72, 1.0, v72
	v_add_f32_e32 v73, 1.0, v73
	v_add_f32_e32 v64, 1.0, v64
	v_add_f32_e32 v65, 1.0, v65
	v_add_f32_e32 v66, 1.0, v66
	v_add_f32_e32 v67, 1.0, v67
	v_rcp_f32_e32 v72, v72
	v_rcp_f32_e32 v73, v73
	v_rcp_f32_e32 v64, v64
	v_rcp_f32_e32 v65, v65
	v_rcp_f32_e32 v66, v66
	v_rcp_f32_e32 v67, v67
	v_pk_mul_f32 v[60:61], v[60:61], v[70:71]
	v_pk_mul_f32 v[52:53], v[52:53], v[164:165] op_sel_hi:[1,0]
	v_pk_mul_f32 v[62:63], v[62:63], v[72:73]
	v_pk_mul_f32 v[54:55], v[54:55], v[164:165] op_sel_hi:[1,0]
	v_pk_mul_f32 v[52:53], v[52:53], v[60:61]
	v_pk_mul_f32 v[56:57], v[56:57], v[64:65]
	v_pk_mul_f32 v[58:59], v[58:59], v[66:67]
	v_pk_mul_f32 v[48:49], v[48:49], v[164:165] op_sel_hi:[1,0]
	v_pk_mul_f32 v[50:51], v[50:51], v[164:165] op_sel_hi:[1,0]
	v_pk_mul_f32 v[54:55], v[54:55], v[62:63]
	v_pk_mul_f32 v[58:59], v[50:51], v[58:59]
	v_pk_mul_f32 v[50:51], v[48:49], v[56:57]
	v_cvt_pk_bf16_f32 v48, v52, v53
	v_mad_i64_i32 v[52:53], s[46:47], v154, s60, v[112:113]
	v_pk_mul_f32 v[44:45], v[44:45], v[160:161] op_sel_hi:[1,0]
	v_cvt_pk_bf16_f32 v49, v54, v55
	v_cvt_pk_bf16_f32 v50, v50, v51
	v_cvt_pk_bf16_f32 v51, v58, v59
	v_pk_mul_f32 v[46:47], v[46:47], v[160:161] op_sel_hi:[1,0]
	v_mul_f32_e32 v54, 0xbfb8aa3b, v44
	v_mul_f32_e32 v55, 0xbfb8aa3b, v45
	v_lshl_add_u64 v[52:53], v[52:53], 0, v[114:115]
	v_pk_mul_f32 v[40:41], v[40:41], v[160:161] op_sel_hi:[1,0]
	v_pk_mul_f32 v[42:43], v[42:43], v[160:161] op_sel_hi:[1,0]
	v_exp_f32_e32 v54, v54
	v_exp_f32_e32 v55, v55
	v_mul_f32_e32 v56, 0xbfb8aa3b, v46
	v_mul_f32_e32 v57, 0xbfb8aa3b, v47
	global_store_dwordx4 v[52:53], v[48:51], off
	v_exp_f32_e32 v56, v56
	v_exp_f32_e32 v57, v57
	v_mul_f32_e32 v48, 0xbfb8aa3b, v40
	v_mul_f32_e32 v49, 0xbfb8aa3b, v41
	v_mul_f32_e32 v50, 0xbfb8aa3b, v42
	v_mul_f32_e32 v51, 0xbfb8aa3b, v43
	v_exp_f32_e32 v48, v48
	v_exp_f32_e32 v49, v49
	v_exp_f32_e32 v50, v50
	v_exp_f32_e32 v51, v51
	v_add_f32_e32 v54, 1.0, v54
	v_add_f32_e32 v55, 1.0, v55
	v_rcp_f32_e32 v54, v54
	v_rcp_f32_e32 v55, v55
	v_add_f32_e32 v56, 1.0, v56
	v_add_f32_e32 v57, 1.0, v57
	v_add_f32_e32 v48, 1.0, v48
	v_add_f32_e32 v49, 1.0, v49
	v_add_f32_e32 v50, 1.0, v50
	v_add_f32_e32 v51, 1.0, v51
	v_rcp_f32_e32 v56, v56
	v_rcp_f32_e32 v57, v57
	v_rcp_f32_e32 v48, v48
	v_rcp_f32_e32 v49, v49
	v_rcp_f32_e32 v50, v50
	v_rcp_f32_e32 v51, v51
	v_pk_mul_f32 v[44:45], v[44:45], v[54:55]
	v_pk_mul_f32 v[36:37], v[36:37], v[160:161] op_sel_hi:[1,0]
	v_pk_mul_f32 v[46:47], v[46:47], v[56:57]
	v_pk_mul_f32 v[38:39], v[38:39], v[160:161] op_sel_hi:[1,0]
	v_pk_mul_f32 v[36:37], v[36:37], v[44:45]
	v_pk_mul_f32 v[40:41], v[40:41], v[48:49]
	v_pk_mul_f32 v[42:43], v[42:43], v[50:51]
	v_pk_mul_f32 v[32:33], v[32:33], v[160:161] op_sel_hi:[1,0]
	v_pk_mul_f32 v[34:35], v[34:35], v[160:161] op_sel_hi:[1,0]
	v_pk_mul_f32 v[38:39], v[38:39], v[46:47]
	v_pk_mul_f32 v[42:43], v[34:35], v[42:43]
	v_pk_mul_f32 v[34:35], v[32:33], v[40:41]
	v_cvt_pk_bf16_f32 v32, v36, v37
	v_mad_i64_i32 v[36:37], s[46:47], v150, s60, v[112:113]
	v_pk_mul_f32 v[28:29], v[28:29], v[156:157] op_sel_hi:[1,0]
	v_cvt_pk_bf16_f32 v33, v38, v39
	v_cvt_pk_bf16_f32 v34, v34, v35
; __device__ __forceinline__ unsigned cvt_pk_bf16(float lo, float hi) { unsigned r; asm volatile("v_cvt_pk_bf16_f32 %0, %1, %2" : "=v"(r) : "v"(lo), "v"(hi)); return r; }
; __device__ __forceinline__ float silu_f(float v) { return v * __builtin_amdgcn_rcpf(1.0f + __builtin_amdgcn_exp2f(v * -1.4426950408889634f)); }
; __device__ __forceinline__ f32x4 silu4(f32x4 v) { return (f32x4){silu_f(v[0]), silu_f(v[1]), silu_f(v[2]), silu_f(v[3])}; }
; __device__ __forceinline__ float sq4(f32x4 v) { return (v[0] * v[0] + v[1] * v[1]) + (v[2] * v[2] + v[3] * v[3]); }
; __device__ __forceinline__ u32x4 pack8(f32x4 a, f32x4 b) { u32x4 w; w.x = cvt_pk_bf16(a[0], a[1]); w.y = cvt_pk_bf16(a[2], a[3]); w.z = cvt_pk_bf16(b[0], b[1]); w.w = cvt_pk_bf16(b[2], b[3]); return w; }
;     __device__ __forceinline__ void operator()(const f32x4 (&acc)[2][2][4][2], const Unit& u, int wr, int wc, int fr, int fq) const {
;     ...
;         for (int ai = 0; ai < 2; ++ai)
; #pragma unroll
;             for (int m = 0; m < 4; ++m) {
;                 const int row = u.pm * BM + ai * HALF + wr * 64 + m * 16 + fr;
;                 const float rstd = rs[ai][m];
;                 const f32x4 a0 = silu4(acc[ai][0][m][0] * rstd) * (acc[ai][1][m][0] * rstd);
;                 const f32x4 a1 = silu4(acc[ai][0][m][1] * rstd) * (acc[ai][1][m][1] * rstd);
;                 *(u32x4*)(ACT + (size_t)row * 2816 + col0) = pack8(a0, a1);
;             }
	v_cvt_pk_bf16_f32 v35, v42, v43
	v_pk_mul_f32 v[30:31], v[30:31], v[156:157] op_sel_hi:[1,0]
	v_mul_f32_e32 v38, 0xbfb8aa3b, v28
	v_mul_f32_e32 v39, 0xbfb8aa3b, v29
	v_lshl_add_u64 v[36:37], v[36:37], 0, v[114:115]
	v_pk_mul_f32 v[24:25], v[24:25], v[156:157] op_sel_hi:[1,0]
	v_pk_mul_f32 v[26:27], v[26:27], v[156:157] op_sel_hi:[1,0]
	v_exp_f32_e32 v38, v38
	v_exp_f32_e32 v39, v39
	v_mul_f32_e32 v40, 0xbfb8aa3b, v30
	v_mul_f32_e32 v41, 0xbfb8aa3b, v31
	global_store_dwordx4 v[36:37], v[32:35], off
	v_exp_f32_e32 v40, v40
	v_exp_f32_e32 v41, v41
	v_mul_f32_e32 v32, 0xbfb8aa3b, v24
	v_mul_f32_e32 v33, 0xbfb8aa3b, v25
	v_mul_f32_e32 v34, 0xbfb8aa3b, v26
	v_mul_f32_e32 v35, 0xbfb8aa3b, v27
	v_exp_f32_e32 v32, v32
	v_exp_f32_e32 v33, v33
	v_exp_f32_e32 v34, v34
	v_exp_f32_e32 v35, v35
	v_add_f32_e32 v38, 1.0, v38
	v_add_f32_e32 v39, 1.0, v39
	v_rcp_f32_e32 v38, v38
	v_rcp_f32_e32 v39, v39
	v_add_f32_e32 v40, 1.0, v40
	v_add_f32_e32 v41, 1.0, v41
	v_add_f32_e32 v32, 1.0, v32
	v_add_f32_e32 v33, 1.0, v33
	v_add_f32_e32 v34, 1.0, v34
	v_add_f32_e32 v35, 1.0, v35
	v_rcp_f32_e32 v40, v40
	v_rcp_f32_e32 v41, v41
	v_rcp_f32_e32 v32, v32
	v_rcp_f32_e32 v33, v33
	v_rcp_f32_e32 v34, v34
	v_rcp_f32_e32 v35, v35
	v_pk_mul_f32 v[28:29], v[28:29], v[38:39]
	v_pk_mul_f32 v[20:21], v[20:21], v[156:157] op_sel_hi:[1,0]
	v_pk_mul_f32 v[30:31], v[30:31], v[40:41]
	v_pk_mul_f32 v[22:23], v[22:23], v[156:157] op_sel_hi:[1,0]
	v_pk_mul_f32 v[20:21], v[20:21], v[28:29]
	v_pk_mul_f32 v[24:25], v[24:25], v[32:33]
	v_pk_mul_f32 v[26:27], v[26:27], v[34:35]
	v_pk_mul_f32 v[16:17], v[16:17], v[156:157] op_sel_hi:[1,0]
	v_pk_mul_f32 v[18:19], v[18:19], v[156:157] op_sel_hi:[1,0]
	v_pk_mul_f32 v[22:23], v[22:23], v[30:31]
	v_pk_mul_f32 v[26:27], v[18:19], v[26:27]
	v_pk_mul_f32 v[18:19], v[16:17], v[24:25]
	v_cvt_pk_bf16_f32 v16, v20, v21
	v_mad_i64_i32 v[20:21], s[46:47], v148, s60, v[112:113]
	v_pk_mul_f32 v[12:13], v[12:13], v[152:153] op_sel_hi:[1,0]
	v_cvt_pk_bf16_f32 v17, v22, v23
	v_cvt_pk_bf16_f32 v18, v18, v19
	v_cvt_pk_bf16_f32 v19, v26, v27
	v_lshl_add_u64 v[20:21], v[20:21], 0, v[114:115]
	v_mul_f32_e32 v22, 0xbfb8aa3b, v12
	v_mul_f32_e32 v23, 0xbfb8aa3b, v13
	v_pk_mul_f32 v[8:9], v[8:9], v[152:153] op_sel_hi:[1,0]
	v_pk_mul_f32 v[10:11], v[10:11], v[152:153] op_sel_hi:[1,0]
	v_exp_f32_e32 v22, v22
	v_exp_f32_e32 v23, v23
	global_store_dwordx4 v[20:21], v[16:19], off
	v_pk_mul_f32 v[14:15], v[14:15], v[152:153] op_sel_hi:[1,0]
	v_add_f32_e32 v22, 1.0, v22
	v_mul_f32_e32 v16, 0xbfb8aa3b, v8
	v_mul_f32_e32 v17, 0xbfb8aa3b, v9
	v_mul_f32_e32 v18, 0xbfb8aa3b, v10
	v_mul_f32_e32 v19, 0xbfb8aa3b, v11
	v_exp_f32_e32 v16, v16
	v_exp_f32_e32 v17, v17
	v_exp_f32_e32 v18, v18
	v_exp_f32_e32 v19, v19
	v_mul_f32_e32 v24, 0xbfb8aa3b, v14
	v_mul_f32_e32 v25, 0xbfb8aa3b, v15
	v_exp_f32_e32 v24, v24
	v_exp_f32_e32 v25, v25
	v_add_f32_e32 v23, 1.0, v23
	v_rcp_f32_e32 v22, v22
	v_rcp_f32_e32 v23, v23
	v_add_f32_e32 v16, 1.0, v16
	v_add_f32_e32 v17, 1.0, v17
	v_add_f32_e32 v18, 1.0, v18
	v_add_f32_e32 v19, 1.0, v19
	v_rcp_f32_e32 v16, v16
	v_rcp_f32_e32 v17, v17
	v_rcp_f32_e32 v18, v18
	v_rcp_f32_e32 v19, v19
	v_add_f32_e32 v24, 1.0, v24
	v_add_f32_e32 v25, 1.0, v25
	v_rcp_f32_e32 v24, v24
	v_rcp_f32_e32 v25, v25
	v_pk_mul_f32 v[12:13], v[12:13], v[22:23]
	v_pk_mul_f32 v[4:5], v[4:5], v[152:153] op_sel_hi:[1,0]
	v_pk_mul_f32 v[8:9], v[8:9], v[16:17]
	v_pk_mul_f32 v[4:5], v[4:5], v[12:13]
	v_pk_mul_f32 v[10:11], v[10:11], v[18:19]
	v_pk_mul_f32 v[0:1], v[0:1], v[152:153] op_sel_hi:[1,0]
	v_pk_mul_f32 v[2:3], v[2:3], v[152:153] op_sel_hi:[1,0]
	v_pk_mul_f32 v[14:15], v[14:15], v[24:25]
	v_pk_mul_f32 v[10:11], v[2:3], v[10:11]
	v_pk_mul_f32 v[2:3], v[0:1], v[8:9]
	v_cvt_pk_bf16_f32 v0, v4, v5
	v_mad_i64_i32 v[4:5], s[46:47], v146, s60, v[112:113]
	v_pk_mul_f32 v[6:7], v[6:7], v[152:153] op_sel_hi:[1,0]
	v_lshl_add_u64 v[4:5], v[4:5], 0, v[114:115]
	v_pk_mul_f32 v[6:7], v[6:7], v[14:15]
	s_nop 0
	v_cvt_pk_bf16_f32 v1, v6, v7
	v_cvt_pk_bf16_f32 v2, v2, v3
	v_cvt_pk_bf16_f32 v3, v10, v11
	global_store_dwordx4 v[4:5], v[0:3], off
	s_cbranch_vccnz .LBB0_1584
	s_andn2_b64 vcc, exec, s[14:15]
	s_cbranch_vccnz .LBB0_1583
	s_barrier
	s_branch .LBB0_1583

; __device__ __forceinline__ float row_part(const float* ss, int row, int fq) { const f32x4 a = ((const f32x4*)(ss + (size_t)row * 16))[fq]; return (a[0] + a[1]) + (a[2] + a[3]); }
; __device__ __forceinline__ float row_finish(float t) { t += shx(t, 16); t += shx(t, 32); return __builtin_amdgcn_rsqf(t * (1.0f / 1024.0f) + RMS_EPS); }
;     __device__ __forceinline__ void operator()(const f32x4 (&acc)[2][2][4][2], const Unit& u, int wr, int wc, int fr, int fq) const {
;     ...
;         float rs[2][4];
; #pragma unroll
;         for (int ai = 0; ai < 2; ++ai)
; #pragma unroll
;             for (int m = 0; m < 4; ++m) rs[ai][m] = row_part(ss, u.pm * BM + ai * HALF + wr * 64 + m * 16 + fr, fq);
; #pragma unroll
;         for (int ai = 0; ai < 2; ++ai)
; #pragma unroll
;             for (int m = 0; m < 4; ++m) rs[ai][m] = row_finish(rs[ai][m]);
.LBB0_2043:
	s_lshr_b32 s98, s2, 6
	s_cmp_lg_u32 s48, s98
	s_cbranch_scc1 .Lrsf_3
	v_lshl_add_u32 v170, s24, 8, v153
	v_ashrrev_i32_e32 v171, 31, v170
	v_or_b32_e32 v166, 16, v170
	v_lshlrev_b64 v[146:147], 6, v[170:171]
	v_ashrrev_i32_e32 v167, 31, v166
	v_lshl_add_u64 v[146:147], v[136:137], 0, v[146:147]
	v_lshlrev_b64 v[148:149], 6, v[166:167]
	v_lshl_add_u64 v[148:149], v[136:137], 0, v[148:149]
	ds_read_b128 v[176:179], v239
	ds_read_b128 v[180:183], v239 offset:1024
	v_or_b32_e32 v162, 32, v170
	v_ashrrev_i32_e32 v163, 31, v162
	v_or_b32_e32 v158, 48, v170
	v_lshlrev_b64 v[146:147], 6, v[162:163]
	v_ashrrev_i32_e32 v159, 31, v158
	v_lshl_add_u64 v[146:147], v[136:137], 0, v[146:147]
	v_lshlrev_b64 v[148:149], 6, v[158:159]
	v_lshl_add_u64 v[148:149], v[136:137], 0, v[148:149]
	ds_read_b128 v[184:187], v239 offset:2048
	ds_read_b128 v[188:191], v239 offset:3072
	v_add_u32_e32 v154, 0x80, v170
	v_ashrrev_i32_e32 v155, 31, v154
	v_add_u32_e32 v150, 0x90, v170
	v_lshlrev_b64 v[146:147], 6, v[154:155]
	v_ashrrev_i32_e32 v151, 31, v150
	v_lshl_add_u64 v[146:147], v[136:137], 0, v[146:147]
	v_lshlrev_b64 v[148:149], 6, v[150:151]
	v_lshl_add_u64 v[148:149], v[136:137], 0, v[148:149]
	ds_read_b128 v[192:195], v239 offset:8192
	ds_read_b128 v[196:199], v239 offset:9216
	v_add_u32_e32 v148, 0xa0, v170
	v_ashrrev_i32_e32 v149, 31, v148
	v_lshlrev_b64 v[146:147], 6, v[148:149]
	v_lshl_add_u64 v[146:147], v[136:137], 0, v[146:147]
	ds_read_b128 v[202:205], v239 offset:10240
	v_add_u32_e32 v146, 0xb0, v170
	v_ashrrev_i32_e32 v147, 31, v146
	v_lshlrev_b64 v[206:207], 6, v[146:147]
	v_lshl_add_u64 v[206:207], v[136:137], 0, v[206:207]
	ds_read_b128 v[206:209], v239 offset:11264
	v_mov_b32_e32 v147, v201
	v_mov_b32_e32 v149, v201
	v_lshlrev_b32_e32 v147, 2, v147
	v_mov_b32_e32 v151, v201
	v_xor_b32_e32 v147, 64, v147
	s_andn2_b64 vcc, exec, s[6:7]
	v_lshlrev_b32_e32 v151, 2, v151
	v_xor_b32_e32 v151, 64, v151
	v_lshlrev_b32_e32 v149, 2, v149
	v_xor_b32_e32 v149, 0x80, v149
	s_mov_b64 s[6:7], -1
	s_waitcnt lgkmcnt(0)
	v_mov_b32_e32 v210, v177
	v_mov_b32_e32 v211, v178
	v_mov_b32_e32 v177, v179
	v_pk_add_f32 v[176:177], v[210:211], v[176:177]
	v_mov_b32_e32 v178, v181
	v_add_f32_e32 v152, v176, v177
	v_mov_b32_e32 v179, v182
	v_mov_b32_e32 v181, v183
	v_mov_b32_e32 v147, v152
	s_nop 1
	v_permlane16_swap_b32_e32 v147, v152
	v_pk_add_f32 v[176:177], v[178:179], v[180:181]
	v_mov_b32_e32 v182, v185
	v_add_f32_e32 v155, v176, v177
	v_mov_b32_e32 v151, v155
	s_nop 1
	v_permlane16_swap_b32_e32 v151, v155
	s_waitcnt lgkmcnt(0)
	v_add_f32_e32 v147, v152, v147
	v_mov_b32_e32 v152, v201
	v_mov_b32_e32 v149, v147
	s_nop 1
	v_permlane32_swap_b32_e32 v149, v147
	s_waitcnt lgkmcnt(0)
	v_add_f32_e32 v151, v155, v151
	v_lshlrev_b32_e32 v152, 2, v152
	v_xor_b32_e32 v152, 0x80, v152
	v_mov_b32_e32 v152, v151
	s_nop 1
	v_permlane32_swap_b32_e32 v152, v151
	s_waitcnt lgkmcnt(0)
	v_add_f32_e32 v147, v147, v149
	v_mov_b32_e32 v149, v201
	v_mov_b32_e32 v183, v186
	v_mov_b32_e32 v185, v187
	v_pk_add_f32 v[178:179], v[182:183], v[184:185]
	v_fmamk_f32 v147, v147, 0x3a800000, v175
	v_lshlrev_b32_e32 v149, 2, v149
	v_add_f32_e32 v156, v178, v179
	v_rsq_f32_e32 v176, v147
	s_waitcnt lgkmcnt(0)
	v_add_f32_e32 v147, v151, v152
	v_xor_b32_e32 v149, 64, v149
	v_mov_b32_e32 v151, v201
	v_mov_b32_e32 v152, v201
	v_mov_b32_e32 v186, v189
	v_mov_b32_e32 v187, v190
	v_mov_b32_e32 v189, v191
	v_mov_b32_e32 v149, v156
	s_nop 1
	v_permlane16_swap_b32_e32 v149, v156
	v_pk_add_f32 v[180:181], v[186:187], v[188:189]
	v_lshlrev_b32_e32 v152, 2, v152
	v_add_f32_e32 v159, v180, v181
	v_xor_b32_e32 v152, 64, v152
	v_mov_b32_e32 v152, v159
	s_nop 1
	v_permlane16_swap_b32_e32 v152, v159
	s_waitcnt lgkmcnt(0)
	v_add_f32_e32 v149, v156, v149
	v_lshlrev_b32_e32 v151, 2, v151
	v_mov_b32_e32 v156, v201
	v_xor_b32_e32 v151, 0x80, v151
	v_mov_b32_e32 v151, v149
	s_nop 1
	v_permlane32_swap_b32_e32 v151, v149
	v_lshlrev_b32_e32 v156, 2, v156
	s_waitcnt lgkmcnt(0)
	v_add_f32_e32 v152, v159, v152
	v_xor_b32_e32 v156, 0x80, v156
	v_mov_b32_e32 v156, v152
	s_nop 1
	v_permlane32_swap_b32_e32 v156, v152
	v_fmamk_f32 v147, v147, 0x3a800000, v175
	v_rsq_f32_e32 v174, v147
	s_waitcnt lgkmcnt(0)
	v_add_f32_e32 v147, v149, v151
	v_mov_b32_e32 v149, v201
	v_mov_b32_e32 v190, v193
	v_mov_b32_e32 v191, v194
	v_mov_b32_e32 v193, v195
	v_fmamk_f32 v147, v147, 0x3a800000, v175
	v_pk_add_f32 v[182:183], v[190:191], v[192:193]
	v_rsq_f32_e32 v172, v147
	s_waitcnt lgkmcnt(0)
	v_add_f32_e32 v147, v152, v156
	v_lshlrev_b32_e32 v149, 2, v149
	v_mov_b32_e32 v151, v201
	v_mov_b32_e32 v152, v201
	v_mov_b32_e32 v194, v197
	v_mov_b32_e32 v195, v198
	v_mov_b32_e32 v197, v199
	v_add_f32_e32 v160, v182, v183
	v_xor_b32_e32 v149, 64, v149
	v_pk_add_f32 v[184:185], v[194:195], v[196:197]
	v_mov_b32_e32 v149, v160
	s_nop 1
	v_permlane16_swap_b32_e32 v149, v160
	v_lshlrev_b32_e32 v152, 2, v152
	v_add_f32_e32 v163, v184, v185
	v_xor_b32_e32 v152, 64, v152
	v_mov_b32_e32 v152, v163
	s_nop 1
	v_permlane16_swap_b32_e32 v152, v163
	v_lshlrev_b32_e32 v151, 2, v151
	v_mov_b32_e32 v156, v201
	s_waitcnt lgkmcnt(0)
	v_add_f32_e32 v149, v160, v149
	v_xor_b32_e32 v151, 0x80, v151
	v_mov_b32_e32 v151, v149
	s_nop 1
	v_permlane32_swap_b32_e32 v151, v149
	v_lshlrev_b32_e32 v156, 2, v156
	s_waitcnt lgkmcnt(0)
	v_add_f32_e32 v152, v163, v152
	v_xor_b32_e32 v156, 0x80, v156
	v_mov_b32_e32 v156, v152
	s_nop 1
	v_permlane32_swap_b32_e32 v156, v152
	v_fmamk_f32 v147, v147, 0x3a800000, v175
	v_rsq_f32_e32 v168, v147
	s_waitcnt lgkmcnt(0)
	v_add_f32_e32 v147, v149, v151
	v_fmamk_f32 v147, v147, 0x3a800000, v175
	v_rsq_f32_e32 v164, v147
	s_waitcnt lgkmcnt(0)
; __device__ __forceinline__ float row_part(const float* ss, int row, int fq) { const f32x4 a = ((const f32x4*)(ss + (size_t)row * 16))[fq]; return (a[0] + a[1]) + (a[2] + a[3]); }
; __device__ __forceinline__ float row_finish(float t) { t += shx(t, 16); t += shx(t, 32); return __builtin_amdgcn_rsqf(t * (1.0f / 1024.0f) + RMS_EPS); }
; __device__ __forceinline__ f32x4 silu4(f32x4 v) { return (f32x4){silu_f(v[0]), silu_f(v[1]), silu_f(v[2]), silu_f(v[3])}; }
; __device__ __forceinline__ u32x4 pack8(f32x4 a, f32x4 b) { u32x4 w; w.x = cvt_pk_bf16(a[0], a[1]); w.y = cvt_pk_bf16(a[2], a[3]); w.z = cvt_pk_bf16(b[0], b[1]); w.w = cvt_pk_bf16(b[2], b[3]); return w; }
;     __device__ __forceinline__ void operator()(const f32x4 (&acc)[2][2][4][2], const Unit& u, int wr, int wc, int fr, int fq) const {
;     ...
;         float rs[2][4];
; #pragma unroll
;         for (int ai = 0; ai < 2; ++ai)
; #pragma unroll
;             for (int m = 0; m < 4; ++m) rs[ai][m] = row_part(ss, u.pm * BM + ai * HALF + wr * 64 + m * 16 + fr, fq);
; #pragma unroll
;         for (int ai = 0; ai < 2; ++ai)
; #pragma unroll
;             for (int m = 0; m < 4; ++m) rs[ai][m] = row_finish(rs[ai][m]);
; #pragma unroll
;         for (int ai = 0; ai < 2; ++ai)
; #pragma unroll
;             for (int m = 0; m < 4; ++m) {
;                 const int row = u.pm * BM + ai * HALF + wr * 64 + m * 16 + fr;
;                 const float rstd = rs[ai][m];
;                 const f32x4 a0 = silu4(acc[ai][0][m][0] * rstd) * (acc[ai][1][m][0] * rstd);
;                 const f32x4 a1 = silu4(acc[ai][0][m][1] * rstd) * (acc[ai][1][m][1] * rstd);
;                 *(u32x4*)(ACT + (size_t)row * 2816 + col0) = pack8(a0, a1);
;             }
	v_add_f32_e32 v147, v152, v156
	v_mov_b32_e32 v149, v201
	v_mov_b32_e32 v151, v201
	v_mov_b32_e32 v152, v201
	v_mov_b32_e32 v198, v203
	v_mov_b32_e32 v199, v204
	v_mov_b32_e32 v203, v205
	v_mov_b32_e32 v204, v207
	v_mov_b32_e32 v205, v208
	v_mov_b32_e32 v207, v209
	v_pk_add_f32 v[188:189], v[204:205], v[206:207]
	v_lshlrev_b32_e32 v152, 2, v152
	v_pk_add_f32 v[186:187], v[198:199], v[202:203]
	v_add_f32_e32 v155, v188, v189
	v_lshlrev_b32_e32 v149, 2, v149
	v_xor_b32_e32 v152, 64, v152
	v_add_f32_e32 v167, v186, v187
	v_xor_b32_e32 v149, 64, v149
	v_mov_b32_e32 v152, v155
	s_nop 1
	v_permlane16_swap_b32_e32 v152, v155
	v_mov_b32_e32 v149, v167
	s_nop 1
	v_permlane16_swap_b32_e32 v149, v167
	v_lshlrev_b32_e32 v151, 2, v151
	v_xor_b32_e32 v151, 0x80, v151
	v_fmamk_f32 v147, v147, 0x3a800000, v175
	s_waitcnt lgkmcnt(0)
	v_add_f32_e32 v152, v155, v152
	v_mov_b32_e32 v155, v201
	s_waitcnt lgkmcnt(0)
	v_add_f32_e32 v149, v167, v149
	v_mov_b32_e32 v151, v149
	s_nop 1
	v_permlane32_swap_b32_e32 v151, v149
	v_lshlrev_b32_e32 v155, 2, v155
	v_xor_b32_e32 v155, 0x80, v155
	v_mov_b32_e32 v155, v152
	s_nop 1
	v_permlane32_swap_b32_e32 v155, v152
	v_rsq_f32_e32 v160, v147
	s_waitcnt lgkmcnt(0)
	v_add_f32_e32 v147, v149, v151
	v_fmamk_f32 v147, v147, 0x3a800000, v175
	v_rsq_f32_e32 v156, v147
	s_waitcnt lgkmcnt(0)
	v_add_f32_e32 v147, v152, v155
	v_fmamk_f32 v147, v147, 0x3a800000, v175
	v_pk_mul_f32 v[124:125], v[124:125], v[176:177] op_sel_hi:[1,0]
	v_rsq_f32_e32 v152, v147
	v_lshlrev_b32_e32 v251, 5, v153
	v_add_u32_e32 v251, 0x24080, v251
	ds_write_b32 v251, v176
	ds_write_b32 v251, v174 offset:4
	ds_write_b32 v251, v172 offset:8
	ds_write_b32 v251, v168 offset:12
	ds_write_b32 v251, v164 offset:16
	ds_write_b32 v251, v160 offset:20
	ds_write_b32 v251, v156 offset:24
	ds_write_b32 v251, v152 offset:28
	s_branch .Lrsj_3
.Lrsf_3:
	v_lshlrev_b32_e32 v251, 5, v153
	v_add_u32_e32 v251, 0x24080, v251
	ds_read_b32 v176, v251
	ds_read_b32 v174, v251 offset:4
	ds_read_b32 v172, v251 offset:8
	ds_read_b32 v168, v251 offset:12
	ds_read_b32 v164, v251 offset:16
	ds_read_b32 v160, v251 offset:20
	ds_read_b32 v156, v251 offset:24
	ds_read_b32 v152, v251 offset:28
	s_waitcnt lgkmcnt(0)
	v_lshl_add_u32 v170, s24, 8, v153
	v_or_b32_e32 v166, 16, v170
	v_or_b32_e32 v162, 32, v170
	v_or_b32_e32 v158, 48, v170
	v_add_u32_e32 v154, 0x80, v170
	v_add_u32_e32 v150, 0x90, v170
	v_add_u32_e32 v148, 0xa0, v170
	v_add_u32_e32 v146, 0xb0, v170
	s_andn2_b64 vcc, exec, s[6:7]
	s_mov_b64 s[6:7], -1
	s_waitcnt lgkmcnt(0)
	s_waitcnt lgkmcnt(0)
	s_waitcnt lgkmcnt(0)
	s_waitcnt lgkmcnt(0)
	s_waitcnt lgkmcnt(0)
	s_waitcnt lgkmcnt(0)
	s_waitcnt lgkmcnt(0)
	s_waitcnt lgkmcnt(0)
	s_waitcnt lgkmcnt(0)
	s_waitcnt lgkmcnt(0)
	s_waitcnt lgkmcnt(0)
	s_waitcnt lgkmcnt(0)
	s_waitcnt lgkmcnt(0)
	s_waitcnt lgkmcnt(0)
	s_waitcnt lgkmcnt(0)
	s_waitcnt lgkmcnt(0)
	s_waitcnt lgkmcnt(0)
	v_pk_mul_f32 v[124:125], v[124:125], v[176:177] op_sel_hi:[1,0]
.Lrsj_3:
	v_mul_f32_e32 v147, 0xbfb8aa3b, v124
	v_exp_f32_e32 v147, v147
	v_mul_f32_e32 v149, 0xbfb8aa3b, v125
	v_exp_f32_e32 v149, v149
	v_pk_mul_f32 v[126:127], v[126:127], v[176:177] op_sel_hi:[1,0]
	v_add_f32_e32 v147, 1.0, v147
	v_rcp_f32_e32 v178, v147
	v_add_f32_e32 v147, 1.0, v149
	v_mul_f32_e32 v149, 0xbfb8aa3b, v126
	v_exp_f32_e32 v149, v149
	v_mul_f32_e32 v151, 0xbfb8aa3b, v127
	v_exp_f32_e32 v151, v151
	v_rcp_f32_e32 v179, v147
	v_add_f32_e32 v147, 1.0, v149
	v_rcp_f32_e32 v180, v147
	v_add_f32_e32 v147, 1.0, v151
	v_pk_mul_f32 v[120:121], v[120:121], v[176:177] op_sel_hi:[1,0]
	v_rcp_f32_e32 v181, v147
	v_mul_f32_e32 v147, 0xbfb8aa3b, v120
	v_exp_f32_e32 v147, v147
	v_mul_f32_e32 v149, 0xbfb8aa3b, v121
	v_exp_f32_e32 v149, v149
	v_pk_mul_f32 v[122:123], v[122:123], v[176:177] op_sel_hi:[1,0]
	v_add_f32_e32 v147, 1.0, v147
	v_pk_mul_f32 v[124:125], v[124:125], v[178:179]
	v_rcp_f32_e32 v178, v147
	v_add_f32_e32 v147, 1.0, v149
	v_mul_f32_e32 v149, 0xbfb8aa3b, v122
	v_exp_f32_e32 v149, v149
	v_mul_f32_e32 v151, 0xbfb8aa3b, v123
	v_exp_f32_e32 v151, v151
	v_rcp_f32_e32 v179, v147
	v_add_f32_e32 v147, 1.0, v149
	v_pk_mul_f32 v[126:127], v[126:127], v[180:181]
	v_rcp_f32_e32 v180, v147
	v_add_f32_e32 v147, 1.0, v151
	v_rcp_f32_e32 v181, v147
	v_pk_mul_f32 v[116:117], v[116:117], v[176:177] op_sel_hi:[1,0]
	v_pk_mul_f32 v[118:119], v[118:119], v[176:177] op_sel_hi:[1,0]
	v_pk_mul_f32 v[120:121], v[120:121], v[178:179]
	v_pk_mul_f32 v[112:113], v[112:113], v[176:177] op_sel_hi:[1,0]
	v_lshl_or_b32 v182, s48, 7, v161
	v_pk_mul_f32 v[118:119], v[118:119], v[126:127]
	v_pk_mul_f32 v[116:117], v[116:117], v[124:125]
	v_pk_mul_f32 v[122:123], v[122:123], v[180:181]
	v_pk_mul_f32 v[114:115], v[114:115], v[176:177] op_sel_hi:[1,0]
	v_pk_mul_f32 v[112:113], v[112:113], v[120:121]
	v_ashrrev_i32_e32 v183, 31, v182
	v_pk_mul_f32 v[114:115], v[114:115], v[122:123]
	v_cvt_pk_bf16_f32 v116, v116, v117
	v_cvt_pk_bf16_f32 v117, v118, v119
	v_cvt_pk_bf16_f32 v118, v112, v113
	v_mov_b64_e32 v[112:113], s[10:11]
	v_cvt_pk_bf16_f32 v119, v114, v115
	v_mad_i64_i32 v[120:121], s[26:27], v170, s47, v[112:113]
	v_lshlrev_b64 v[114:115], 1, v[182:183]
	v_pk_mul_f32 v[108:109], v[108:109], v[174:175] op_sel_hi:[1,0]
	v_pk_mul_f32 v[110:111], v[110:111], v[174:175] op_sel_hi:[1,0]
	v_mul_f32_e32 v122, 0xbfb8aa3b, v108
	v_mul_f32_e32 v123, 0xbfb8aa3b, v109
	v_lshl_add_u64 v[120:121], v[120:121], 0, v[114:115]
	v_pk_mul_f32 v[104:105], v[104:105], v[174:175] op_sel_hi:[1,0]
	v_pk_mul_f32 v[106:107], v[106:107], v[174:175] op_sel_hi:[1,0]
	v_exp_f32_e32 v122, v122
	v_exp_f32_e32 v123, v123
	v_mul_f32_e32 v124, 0xbfb8aa3b, v110
	v_mul_f32_e32 v125, 0xbfb8aa3b, v111
; __device__ __forceinline__ unsigned cvt_pk_bf16(float lo, float hi) { unsigned r; asm volatile("v_cvt_pk_bf16_f32 %0, %1, %2" : "=v"(r) : "v"(lo), "v"(hi)); return r; }
; __device__ __forceinline__ float silu_f(float v) { return v * __builtin_amdgcn_rcpf(1.0f + __builtin_amdgcn_exp2f(v * -1.4426950408889634f)); }
; __device__ __forceinline__ f32x4 silu4(f32x4 v) { return (f32x4){silu_f(v[0]), silu_f(v[1]), silu_f(v[2]), silu_f(v[3])}; }
; __device__ __forceinline__ float sq4(f32x4 v) { return (v[0] * v[0] + v[1] * v[1]) + (v[2] * v[2] + v[3] * v[3]); }
; __device__ __forceinline__ u32x4 pack8(f32x4 a, f32x4 b) { u32x4 w; w.x = cvt_pk_bf16(a[0], a[1]); w.y = cvt_pk_bf16(a[2], a[3]); w.z = cvt_pk_bf16(b[0], b[1]); w.w = cvt_pk_bf16(b[2], b[3]); return w; }
;     __device__ __forceinline__ void operator()(const f32x4 (&acc)[2][2][4][2], const Unit& u, int wr, int wc, int fr, int fq) const {
;     ...
;         for (int ai = 0; ai < 2; ++ai)
; #pragma unroll
;             for (int m = 0; m < 4; ++m) {
;                 const int row = u.pm * BM + ai * HALF + wr * 64 + m * 16 + fr;
;                 const float rstd = rs[ai][m];
;                 const f32x4 a0 = silu4(acc[ai][0][m][0] * rstd) * (acc[ai][1][m][0] * rstd);
;                 const f32x4 a1 = silu4(acc[ai][0][m][1] * rstd) * (acc[ai][1][m][1] * rstd);
;                 *(u32x4*)(ACT + (size_t)row * 2816 + col0) = pack8(a0, a1);
;             }
	global_store_dwordx4 v[120:121], v[116:119], off
	v_exp_f32_e32 v124, v124
	v_exp_f32_e32 v125, v125
	v_mul_f32_e32 v116, 0xbfb8aa3b, v104
	v_mul_f32_e32 v117, 0xbfb8aa3b, v105
	v_mul_f32_e32 v118, 0xbfb8aa3b, v106
	v_mul_f32_e32 v119, 0xbfb8aa3b, v107
	v_exp_f32_e32 v116, v116
	v_exp_f32_e32 v117, v117
	v_exp_f32_e32 v118, v118
	v_exp_f32_e32 v119, v119
	v_add_f32_e32 v122, 1.0, v122
	v_add_f32_e32 v123, 1.0, v123
	v_rcp_f32_e32 v122, v122
	v_rcp_f32_e32 v123, v123
	v_add_f32_e32 v124, 1.0, v124
	v_add_f32_e32 v125, 1.0, v125
	v_add_f32_e32 v116, 1.0, v116
	v_add_f32_e32 v117, 1.0, v117
	v_add_f32_e32 v118, 1.0, v118
	v_add_f32_e32 v119, 1.0, v119
	v_rcp_f32_e32 v124, v124
	v_rcp_f32_e32 v125, v125
	v_rcp_f32_e32 v116, v116
	v_rcp_f32_e32 v117, v117
	v_rcp_f32_e32 v118, v118
	v_rcp_f32_e32 v119, v119
	v_pk_mul_f32 v[108:109], v[108:109], v[122:123]
	v_pk_mul_f32 v[100:101], v[100:101], v[174:175] op_sel_hi:[1,0]
	v_pk_mul_f32 v[110:111], v[110:111], v[124:125]
	v_pk_mul_f32 v[102:103], v[102:103], v[174:175] op_sel_hi:[1,0]
	v_pk_mul_f32 v[100:101], v[100:101], v[108:109]
	v_pk_mul_f32 v[104:105], v[104:105], v[116:117]
	v_pk_mul_f32 v[106:107], v[106:107], v[118:119]
	v_pk_mul_f32 v[96:97], v[96:97], v[174:175] op_sel_hi:[1,0]
	v_pk_mul_f32 v[98:99], v[98:99], v[174:175] op_sel_hi:[1,0]
	v_pk_mul_f32 v[102:103], v[102:103], v[110:111]
	v_pk_mul_f32 v[106:107], v[98:99], v[106:107]
	v_pk_mul_f32 v[98:99], v[96:97], v[104:105]
	v_cvt_pk_bf16_f32 v96, v100, v101
	v_mad_i64_i32 v[100:101], s[26:27], v166, s47, v[112:113]
	v_pk_mul_f32 v[92:93], v[92:93], v[172:173] op_sel_hi:[1,0]
	v_cvt_pk_bf16_f32 v97, v102, v103
	v_cvt_pk_bf16_f32 v98, v98, v99
	v_cvt_pk_bf16_f32 v99, v106, v107
	v_pk_mul_f32 v[94:95], v[94:95], v[172:173] op_sel_hi:[1,0]
	v_mul_f32_e32 v102, 0xbfb8aa3b, v92
	v_mul_f32_e32 v103, 0xbfb8aa3b, v93
	v_lshl_add_u64 v[100:101], v[100:101], 0, v[114:115]
	v_pk_mul_f32 v[88:89], v[88:89], v[172:173] op_sel_hi:[1,0]
	v_pk_mul_f32 v[90:91], v[90:91], v[172:173] op_sel_hi:[1,0]
	v_exp_f32_e32 v102, v102
	v_exp_f32_e32 v103, v103
	v_mul_f32_e32 v104, 0xbfb8aa3b, v94
	v_mul_f32_e32 v105, 0xbfb8aa3b, v95
	global_store_dwordx4 v[100:101], v[96:99], off
	v_exp_f32_e32 v104, v104
	v_exp_f32_e32 v105, v105
	v_mul_f32_e32 v96, 0xbfb8aa3b, v88
	v_mul_f32_e32 v97, 0xbfb8aa3b, v89
	v_mul_f32_e32 v98, 0xbfb8aa3b, v90
	v_mul_f32_e32 v99, 0xbfb8aa3b, v91
	v_exp_f32_e32 v96, v96
	v_exp_f32_e32 v97, v97
	v_exp_f32_e32 v98, v98
	v_exp_f32_e32 v99, v99
	v_add_f32_e32 v102, 1.0, v102
	v_add_f32_e32 v103, 1.0, v103
	v_rcp_f32_e32 v102, v102
	v_rcp_f32_e32 v103, v103
	v_add_f32_e32 v104, 1.0, v104
	v_add_f32_e32 v105, 1.0, v105
	v_add_f32_e32 v96, 1.0, v96
	v_add_f32_e32 v97, 1.0, v97
	v_add_f32_e32 v98, 1.0, v98
	v_add_f32_e32 v99, 1.0, v99
	v_rcp_f32_e32 v104, v104
	v_rcp_f32_e32 v105, v105
	v_rcp_f32_e32 v96, v96
	v_rcp_f32_e32 v97, v97
	v_rcp_f32_e32 v98, v98
	v_rcp_f32_e32 v99, v99
	v_pk_mul_f32 v[92:93], v[92:93], v[102:103]
	v_pk_mul_f32 v[84:85], v[84:85], v[172:173] op_sel_hi:[1,0]
	v_pk_mul_f32 v[94:95], v[94:95], v[104:105]
	v_pk_mul_f32 v[86:87], v[86:87], v[172:173] op_sel_hi:[1,0]
	v_pk_mul_f32 v[84:85], v[84:85], v[92:93]
	v_pk_mul_f32 v[88:89], v[88:89], v[96:97]
	v_pk_mul_f32 v[90:91], v[90:91], v[98:99]
	v_pk_mul_f32 v[80:81], v[80:81], v[172:173] op_sel_hi:[1,0]
	v_pk_mul_f32 v[82:83], v[82:83], v[172:173] op_sel_hi:[1,0]
	v_pk_mul_f32 v[86:87], v[86:87], v[94:95]
	v_pk_mul_f32 v[90:91], v[82:83], v[90:91]
	v_pk_mul_f32 v[82:83], v[80:81], v[88:89]
	v_cvt_pk_bf16_f32 v80, v84, v85
	v_mad_i64_i32 v[84:85], s[26:27], v162, s47, v[112:113]
	v_pk_mul_f32 v[76:77], v[76:77], v[168:169] op_sel_hi:[1,0]
	v_cvt_pk_bf16_f32 v81, v86, v87
	v_cvt_pk_bf16_f32 v82, v82, v83
	v_cvt_pk_bf16_f32 v83, v90, v91
	v_pk_mul_f32 v[78:79], v[78:79], v[168:169] op_sel_hi:[1,0]
	v_mul_f32_e32 v86, 0xbfb8aa3b, v76
	v_mul_f32_e32 v87, 0xbfb8aa3b, v77
	v_lshl_add_u64 v[84:85], v[84:85], 0, v[114:115]
	v_pk_mul_f32 v[72:73], v[72:73], v[168:169] op_sel_hi:[1,0]
	v_pk_mul_f32 v[74:75], v[74:75], v[168:169] op_sel_hi:[1,0]
	v_exp_f32_e32 v86, v86
	v_exp_f32_e32 v87, v87
	v_mul_f32_e32 v88, 0xbfb8aa3b, v78
	v_mul_f32_e32 v89, 0xbfb8aa3b, v79
	global_store_dwordx4 v[84:85], v[80:83], off
	v_exp_f32_e32 v88, v88
	v_exp_f32_e32 v89, v89
	v_mul_f32_e32 v80, 0xbfb8aa3b, v72
	v_mul_f32_e32 v81, 0xbfb8aa3b, v73
	v_mul_f32_e32 v82, 0xbfb8aa3b, v74
	v_mul_f32_e32 v83, 0xbfb8aa3b, v75
	v_exp_f32_e32 v80, v80
	v_exp_f32_e32 v81, v81
	v_exp_f32_e32 v82, v82
	v_exp_f32_e32 v83, v83
	v_add_f32_e32 v86, 1.0, v86
	v_add_f32_e32 v87, 1.0, v87
	v_rcp_f32_e32 v86, v86
	v_rcp_f32_e32 v87, v87
	v_add_f32_e32 v88, 1.0, v88
	v_add_f32_e32 v89, 1.0, v89
	v_add_f32_e32 v80, 1.0, v80
	v_add_f32_e32 v81, 1.0, v81
	v_add_f32_e32 v82, 1.0, v82
	v_add_f32_e32 v83, 1.0, v83
	v_rcp_f32_e32 v88, v88
	v_rcp_f32_e32 v89, v89
	v_rcp_f32_e32 v80, v80
	v_rcp_f32_e32 v81, v81
	v_rcp_f32_e32 v82, v82
	v_rcp_f32_e32 v83, v83
	v_pk_mul_f32 v[76:77], v[76:77], v[86:87]
	v_pk_mul_f32 v[68:69], v[68:69], v[168:169] op_sel_hi:[1,0]
	v_pk_mul_f32 v[78:79], v[78:79], v[88:89]
	v_pk_mul_f32 v[70:71], v[70:71], v[168:169] op_sel_hi:[1,0]
	v_pk_mul_f32 v[68:69], v[68:69], v[76:77]
	v_pk_mul_f32 v[72:73], v[72:73], v[80:81]
	v_pk_mul_f32 v[74:75], v[74:75], v[82:83]
	v_pk_mul_f32 v[64:65], v[64:65], v[168:169] op_sel_hi:[1,0]
	v_pk_mul_f32 v[66:67], v[66:67], v[168:169] op_sel_hi:[1,0]
	v_pk_mul_f32 v[70:71], v[70:71], v[78:79]
	v_pk_mul_f32 v[74:75], v[66:67], v[74:75]
	v_pk_mul_f32 v[66:67], v[64:65], v[72:73]
	v_cvt_pk_bf16_f32 v64, v68, v69
	v_mad_i64_i32 v[68:69], s[26:27], v158, s47, v[112:113]
; __device__ __forceinline__ unsigned cvt_pk_bf16(float lo, float hi) { unsigned r; asm volatile("v_cvt_pk_bf16_f32 %0, %1, %2" : "=v"(r) : "v"(lo), "v"(hi)); return r; }
; __device__ __forceinline__ float silu_f(float v) { return v * __builtin_amdgcn_rcpf(1.0f + __builtin_amdgcn_exp2f(v * -1.4426950408889634f)); }
; __device__ __forceinline__ f32x4 silu4(f32x4 v) { return (f32x4){silu_f(v[0]), silu_f(v[1]), silu_f(v[2]), silu_f(v[3])}; }
; __device__ __forceinline__ float sq4(f32x4 v) { return (v[0] * v[0] + v[1] * v[1]) + (v[2] * v[2] + v[3] * v[3]); }
; __device__ __forceinline__ u32x4 pack8(f32x4 a, f32x4 b) { u32x4 w; w.x = cvt_pk_bf16(a[0], a[1]); w.y = cvt_pk_bf16(a[2], a[3]); w.z = cvt_pk_bf16(b[0], b[1]); w.w = cvt_pk_bf16(b[2], b[3]); return w; }
;     __device__ __forceinline__ void operator()(const f32x4 (&acc)[2][2][4][2], const Unit& u, int wr, int wc, int fr, int fq) const {
;     ...
;         for (int ai = 0; ai < 2; ++ai)
; #pragma unroll
;             for (int m = 0; m < 4; ++m) {
;                 const int row = u.pm * BM + ai * HALF + wr * 64 + m * 16 + fr;
;                 const float rstd = rs[ai][m];
;                 const f32x4 a0 = silu4(acc[ai][0][m][0] * rstd) * (acc[ai][1][m][0] * rstd);
;                 const f32x4 a1 = silu4(acc[ai][0][m][1] * rstd) * (acc[ai][1][m][1] * rstd);
;                 *(u32x4*)(ACT + (size_t)row * 2816 + col0) = pack8(a0, a1);
;             }
	v_pk_mul_f32 v[60:61], v[60:61], v[164:165] op_sel_hi:[1,0]
	v_cvt_pk_bf16_f32 v65, v70, v71
	v_cvt_pk_bf16_f32 v66, v66, v67
	v_cvt_pk_bf16_f32 v67, v74, v75
	v_pk_mul_f32 v[62:63], v[62:63], v[164:165] op_sel_hi:[1,0]
	v_mul_f32_e32 v70, 0xbfb8aa3b, v60
	v_mul_f32_e32 v71, 0xbfb8aa3b, v61
	v_lshl_add_u64 v[68:69], v[68:69], 0, v[114:115]
	v_pk_mul_f32 v[56:57], v[56:57], v[164:165] op_sel_hi:[1,0]
	v_pk_mul_f32 v[58:59], v[58:59], v[164:165] op_sel_hi:[1,0]
	v_exp_f32_e32 v70, v70
	v_exp_f32_e32 v71, v71
	v_mul_f32_e32 v72, 0xbfb8aa3b, v62
	v_mul_f32_e32 v73, 0xbfb8aa3b, v63
	global_store_dwordx4 v[68:69], v[64:67], off
	v_exp_f32_e32 v72, v72
	v_exp_f32_e32 v73, v73
	v_mul_f32_e32 v64, 0xbfb8aa3b, v56
	v_mul_f32_e32 v65, 0xbfb8aa3b, v57
	v_mul_f32_e32 v66, 0xbfb8aa3b, v58
	v_mul_f32_e32 v67, 0xbfb8aa3b, v59
	v_exp_f32_e32 v64, v64
	v_exp_f32_e32 v65, v65
	v_exp_f32_e32 v66, v66
	v_exp_f32_e32 v67, v67
	v_add_f32_e32 v70, 1.0, v70
	v_add_f32_e32 v71, 1.0, v71
	v_rcp_f32_e32 v70, v70
	v_rcp_f32_e32 v71, v71
	v_add_f32_e32 v72, 1.0, v72
	v_add_f32_e32 v73, 1.0, v73
	v_add_f32_e32 v64, 1.0, v64
	v_add_f32_e32 v65, 1.0, v65
	v_add_f32_e32 v66, 1.0, v66
	v_add_f32_e32 v67, 1.0, v67
	v_rcp_f32_e32 v72, v72
	v_rcp_f32_e32 v73, v73
	v_rcp_f32_e32 v64, v64
	v_rcp_f32_e32 v65, v65
	v_rcp_f32_e32 v66, v66
	v_rcp_f32_e32 v67, v67
	v_pk_mul_f32 v[60:61], v[60:61], v[70:71]
	v_pk_mul_f32 v[52:53], v[52:53], v[164:165] op_sel_hi:[1,0]
	v_pk_mul_f32 v[62:63], v[62:63], v[72:73]
	v_pk_mul_f32 v[54:55], v[54:55], v[164:165] op_sel_hi:[1,0]
	v_pk_mul_f32 v[52:53], v[52:53], v[60:61]
	v_pk_mul_f32 v[56:57], v[56:57], v[64:65]
	v_pk_mul_f32 v[58:59], v[58:59], v[66:67]
	v_pk_mul_f32 v[48:49], v[48:49], v[164:165] op_sel_hi:[1,0]
	v_pk_mul_f32 v[50:51], v[50:51], v[164:165] op_sel_hi:[1,0]
	v_pk_mul_f32 v[54:55], v[54:55], v[62:63]
	v_pk_mul_f32 v[58:59], v[50:51], v[58:59]
	v_pk_mul_f32 v[50:51], v[48:49], v[56:57]
	v_cvt_pk_bf16_f32 v48, v52, v53
	v_mad_i64_i32 v[52:53], s[26:27], v154, s47, v[112:113]
	v_pk_mul_f32 v[44:45], v[44:45], v[160:161] op_sel_hi:[1,0]
	v_cvt_pk_bf16_f32 v49, v54, v55
	v_cvt_pk_bf16_f32 v50, v50, v51
	v_cvt_pk_bf16_f32 v51, v58, v59
	v_pk_mul_f32 v[46:47], v[46:47], v[160:161] op_sel_hi:[1,0]
	v_mul_f32_e32 v54, 0xbfb8aa3b, v44
	v_mul_f32_e32 v55, 0xbfb8aa3b, v45
	v_lshl_add_u64 v[52:53], v[52:53], 0, v[114:115]
	v_pk_mul_f32 v[40:41], v[40:41], v[160:161] op_sel_hi:[1,0]
	v_pk_mul_f32 v[42:43], v[42:43], v[160:161] op_sel_hi:[1,0]
	v_exp_f32_e32 v54, v54
	v_exp_f32_e32 v55, v55
	v_mul_f32_e32 v56, 0xbfb8aa3b, v46
	v_mul_f32_e32 v57, 0xbfb8aa3b, v47
	global_store_dwordx4 v[52:53], v[48:51], off
	v_exp_f32_e32 v56, v56
	v_exp_f32_e32 v57, v57
	v_mul_f32_e32 v48, 0xbfb8aa3b, v40
	v_mul_f32_e32 v49, 0xbfb8aa3b, v41
	v_mul_f32_e32 v50, 0xbfb8aa3b, v42
	v_mul_f32_e32 v51, 0xbfb8aa3b, v43
	v_exp_f32_e32 v48, v48
	v_exp_f32_e32 v49, v49
	v_exp_f32_e32 v50, v50
	v_exp_f32_e32 v51, v51
	v_add_f32_e32 v54, 1.0, v54
	v_add_f32_e32 v55, 1.0, v55
	v_rcp_f32_e32 v54, v54
	v_rcp_f32_e32 v55, v55
	v_add_f32_e32 v56, 1.0, v56
	v_add_f32_e32 v57, 1.0, v57
	v_add_f32_e32 v48, 1.0, v48
	v_add_f32_e32 v49, 1.0, v49
	v_add_f32_e32 v50, 1.0, v50
	v_add_f32_e32 v51, 1.0, v51
	v_rcp_f32_e32 v56, v56
	v_rcp_f32_e32 v57, v57
	v_rcp_f32_e32 v48, v48
	v_rcp_f32_e32 v49, v49
	v_rcp_f32_e32 v50, v50
	v_rcp_f32_e32 v51, v51
	v_pk_mul_f32 v[44:45], v[44:45], v[54:55]
	v_pk_mul_f32 v[36:37], v[36:37], v[160:161] op_sel_hi:[1,0]
	v_pk_mul_f32 v[46:47], v[46:47], v[56:57]
	v_pk_mul_f32 v[38:39], v[38:39], v[160:161] op_sel_hi:[1,0]
	v_pk_mul_f32 v[36:37], v[36:37], v[44:45]
	v_pk_mul_f32 v[40:41], v[40:41], v[48:49]
	v_pk_mul_f32 v[42:43], v[42:43], v[50:51]
	v_pk_mul_f32 v[32:33], v[32:33], v[160:161] op_sel_hi:[1,0]
	v_pk_mul_f32 v[34:35], v[34:35], v[160:161] op_sel_hi:[1,0]
	v_pk_mul_f32 v[38:39], v[38:39], v[46:47]
	v_pk_mul_f32 v[42:43], v[34:35], v[42:43]
	v_pk_mul_f32 v[34:35], v[32:33], v[40:41]
	v_cvt_pk_bf16_f32 v32, v36, v37
	v_mad_i64_i32 v[36:37], s[26:27], v150, s47, v[112:113]
	v_pk_mul_f32 v[28:29], v[28:29], v[156:157] op_sel_hi:[1,0]
	v_cvt_pk_bf16_f32 v33, v38, v39
	v_cvt_pk_bf16_f32 v34, v34, v35
; __device__ __forceinline__ unsigned cvt_pk_bf16(float lo, float hi) { unsigned r; asm volatile("v_cvt_pk_bf16_f32 %0, %1, %2" : "=v"(r) : "v"(lo), "v"(hi)); return r; }
; __device__ __forceinline__ float silu_f(float v) { return v * __builtin_amdgcn_rcpf(1.0f + __builtin_amdgcn_exp2f(v * -1.4426950408889634f)); }
; __device__ __forceinline__ f32x4 silu4(f32x4 v) { return (f32x4){silu_f(v[0]), silu_f(v[1]), silu_f(v[2]), silu_f(v[3])}; }
; __device__ __forceinline__ float sq4(f32x4 v) { return (v[0] * v[0] + v[1] * v[1]) + (v[2] * v[2] + v[3] * v[3]); }
; __device__ __forceinline__ u32x4 pack8(f32x4 a, f32x4 b) { u32x4 w; w.x = cvt_pk_bf16(a[0], a[1]); w.y = cvt_pk_bf16(a[2], a[3]); w.z = cvt_pk_bf16(b[0], b[1]); w.w = cvt_pk_bf16(b[2], b[3]); return w; }
;     __device__ __forceinline__ void operator()(const f32x4 (&acc)[2][2][4][2], const Unit& u, int wr, int wc, int fr, int fq) const {
;     ...
;         for (int ai = 0; ai < 2; ++ai)
; #pragma unroll
;             for (int m = 0; m < 4; ++m) {
;                 const int row = u.pm * BM + ai * HALF + wr * 64 + m * 16 + fr;
;                 const float rstd = rs[ai][m];
;                 const f32x4 a0 = silu4(acc[ai][0][m][0] * rstd) * (acc[ai][1][m][0] * rstd);
;                 const f32x4 a1 = silu4(acc[ai][0][m][1] * rstd) * (acc[ai][1][m][1] * rstd);
;                 *(u32x4*)(ACT + (size_t)row * 2816 + col0) = pack8(a0, a1);
;             }
	v_cvt_pk_bf16_f32 v35, v42, v43
	v_pk_mul_f32 v[30:31], v[30:31], v[156:157] op_sel_hi:[1,0]
	v_mul_f32_e32 v38, 0xbfb8aa3b, v28
	v_mul_f32_e32 v39, 0xbfb8aa3b, v29
	v_lshl_add_u64 v[36:37], v[36:37], 0, v[114:115]
	v_pk_mul_f32 v[24:25], v[24:25], v[156:157] op_sel_hi:[1,0]
	v_pk_mul_f32 v[26:27], v[26:27], v[156:157] op_sel_hi:[1,0]
	v_exp_f32_e32 v38, v38
	v_exp_f32_e32 v39, v39
	v_mul_f32_e32 v40, 0xbfb8aa3b, v30
	v_mul_f32_e32 v41, 0xbfb8aa3b, v31
	global_store_dwordx4 v[36:37], v[32:35], off
	v_exp_f32_e32 v40, v40
	v_exp_f32_e32 v41, v41
	v_mul_f32_e32 v32, 0xbfb8aa3b, v24
	v_mul_f32_e32 v33, 0xbfb8aa3b, v25
	v_mul_f32_e32 v34, 0xbfb8aa3b, v26
	v_mul_f32_e32 v35, 0xbfb8aa3b, v27
	v_exp_f32_e32 v32, v32
	v_exp_f32_e32 v33, v33
	v_exp_f32_e32 v34, v34
	v_exp_f32_e32 v35, v35
	v_add_f32_e32 v38, 1.0, v38
	v_add_f32_e32 v39, 1.0, v39
	v_rcp_f32_e32 v38, v38
	v_rcp_f32_e32 v39, v39
	v_add_f32_e32 v40, 1.0, v40
	v_add_f32_e32 v41, 1.0, v41
	v_add_f32_e32 v32, 1.0, v32
	v_add_f32_e32 v33, 1.0, v33
	v_add_f32_e32 v34, 1.0, v34
	v_add_f32_e32 v35, 1.0, v35
	v_rcp_f32_e32 v40, v40
	v_rcp_f32_e32 v41, v41
	v_rcp_f32_e32 v32, v32
	v_rcp_f32_e32 v33, v33
	v_rcp_f32_e32 v34, v34
	v_rcp_f32_e32 v35, v35
	v_pk_mul_f32 v[28:29], v[28:29], v[38:39]
	v_pk_mul_f32 v[20:21], v[20:21], v[156:157] op_sel_hi:[1,0]
	v_pk_mul_f32 v[30:31], v[30:31], v[40:41]
	v_pk_mul_f32 v[22:23], v[22:23], v[156:157] op_sel_hi:[1,0]
	v_pk_mul_f32 v[20:21], v[20:21], v[28:29]
	v_pk_mul_f32 v[24:25], v[24:25], v[32:33]
	v_pk_mul_f32 v[26:27], v[26:27], v[34:35]
	v_pk_mul_f32 v[16:17], v[16:17], v[156:157] op_sel_hi:[1,0]
	v_pk_mul_f32 v[18:19], v[18:19], v[156:157] op_sel_hi:[1,0]
	v_pk_mul_f32 v[22:23], v[22:23], v[30:31]
	v_pk_mul_f32 v[26:27], v[18:19], v[26:27]
	v_pk_mul_f32 v[18:19], v[16:17], v[24:25]
	v_cvt_pk_bf16_f32 v16, v20, v21
	v_mad_i64_i32 v[20:21], s[26:27], v148, s47, v[112:113]
	v_pk_mul_f32 v[12:13], v[12:13], v[152:153] op_sel_hi:[1,0]
	v_cvt_pk_bf16_f32 v17, v22, v23
	v_cvt_pk_bf16_f32 v18, v18, v19
	v_cvt_pk_bf16_f32 v19, v26, v27
	v_lshl_add_u64 v[20:21], v[20:21], 0, v[114:115]
	v_mul_f32_e32 v22, 0xbfb8aa3b, v12
	v_mul_f32_e32 v23, 0xbfb8aa3b, v13
	v_pk_mul_f32 v[8:9], v[8:9], v[152:153] op_sel_hi:[1,0]
	v_pk_mul_f32 v[10:11], v[10:11], v[152:153] op_sel_hi:[1,0]
	v_exp_f32_e32 v22, v22
	v_exp_f32_e32 v23, v23
	global_store_dwordx4 v[20:21], v[16:19], off
	v_pk_mul_f32 v[14:15], v[14:15], v[152:153] op_sel_hi:[1,0]
	v_add_f32_e32 v22, 1.0, v22
	v_mul_f32_e32 v16, 0xbfb8aa3b, v8
	v_mul_f32_e32 v17, 0xbfb8aa3b, v9
	v_mul_f32_e32 v18, 0xbfb8aa3b, v10
	v_mul_f32_e32 v19, 0xbfb8aa3b, v11
	v_exp_f32_e32 v16, v16
	v_exp_f32_e32 v17, v17
	v_exp_f32_e32 v18, v18
	v_exp_f32_e32 v19, v19
	v_mul_f32_e32 v24, 0xbfb8aa3b, v14
	v_mul_f32_e32 v25, 0xbfb8aa3b, v15
	v_exp_f32_e32 v24, v24
	v_exp_f32_e32 v25, v25
	v_add_f32_e32 v23, 1.0, v23
	v_rcp_f32_e32 v22, v22
	v_rcp_f32_e32 v23, v23
	v_add_f32_e32 v16, 1.0, v16
	v_add_f32_e32 v17, 1.0, v17
	v_add_f32_e32 v18, 1.0, v18
	v_add_f32_e32 v19, 1.0, v19
	v_rcp_f32_e32 v16, v16
	v_rcp_f32_e32 v17, v17
	v_rcp_f32_e32 v18, v18
	v_rcp_f32_e32 v19, v19
	v_add_f32_e32 v24, 1.0, v24
	v_add_f32_e32 v25, 1.0, v25
	v_rcp_f32_e32 v24, v24
	v_rcp_f32_e32 v25, v25
	v_pk_mul_f32 v[12:13], v[12:13], v[22:23]
	v_pk_mul_f32 v[4:5], v[4:5], v[152:153] op_sel_hi:[1,0]
	v_pk_mul_f32 v[8:9], v[8:9], v[16:17]
	v_pk_mul_f32 v[4:5], v[4:5], v[12:13]
	v_pk_mul_f32 v[10:11], v[10:11], v[18:19]
	v_pk_mul_f32 v[0:1], v[0:1], v[152:153] op_sel_hi:[1,0]
	v_pk_mul_f32 v[2:3], v[2:3], v[152:153] op_sel_hi:[1,0]
	v_pk_mul_f32 v[14:15], v[14:15], v[24:25]
	v_pk_mul_f32 v[10:11], v[2:3], v[10:11]
	v_pk_mul_f32 v[2:3], v[0:1], v[8:9]
	v_cvt_pk_bf16_f32 v0, v4, v5
	v_mad_i64_i32 v[4:5], s[26:27], v146, s47, v[112:113]
	v_pk_mul_f32 v[6:7], v[6:7], v[152:153] op_sel_hi:[1,0]
	v_lshl_add_u64 v[4:5], v[4:5], 0, v[114:115]
	v_pk_mul_f32 v[6:7], v[6:7], v[14:15]
	s_nop 0
	v_cvt_pk_bf16_f32 v1, v6, v7
	v_cvt_pk_bf16_f32 v2, v2, v3
	v_cvt_pk_bf16_f32 v3, v10, v11
	global_store_dwordx4 v[4:5], v[0:3], off
	s_cbranch_vccnz .LBB0_2036
	s_andn2_b64 vcc, exec, s[8:9]
	s_cbranch_vccnz .LBB0_2035
	s_barrier
	s_branch .LBB0_2035

; __global__ void __launch_bounds__(NTHR, 2) fwd_megakernel(Args a_unused) {
;     extern __shared__ __attribute__((aligned(16))) unsigned char lds[];
	.amdhsa_kernel _Z14fwd_megakernel4Args
		.amdhsa_group_segment_fixed_size 8192
		.amdhsa_private_segment_fixed_size 0
		.amdhsa_kernarg_size 432
		.amdhsa_user_sgpr_count 2
		.amdhsa_user_sgpr_dispatch_ptr 0
		.amdhsa_user_sgpr_queue_ptr 0
		.amdhsa_user_sgpr_kernarg_segment_ptr 1
		.amdhsa_user_sgpr_dispatch_id 0
		.amdhsa_user_sgpr_kernarg_preload_length 0
		.amdhsa_user_sgpr_kernarg_preload_offset 0
		.amdhsa_user_sgpr_private_segment_size 0
		.amdhsa_uses_dynamic_stack 0
		.amdhsa_enable_private_segment 0
		.amdhsa_system_sgpr_workgroup_id_x 1
		.amdhsa_system_sgpr_workgroup_id_y 0
		.amdhsa_system_sgpr_workgroup_id_z 0
		.amdhsa_system_sgpr_workgroup_info 0
		.amdhsa_system_vgpr_workitem_id 2
		.amdhsa_next_free_vgpr 256
		.amdhsa_next_free_sgpr 102
		.amdhsa_accum_offset 256
		.amdhsa_reserve_vcc 1
		.amdhsa_float_round_mode_32 0
		.amdhsa_float_round_mode_16_64 0
		.amdhsa_float_denorm_mode_32 3
		.amdhsa_float_denorm_mode_16_64 3
		.amdhsa_dx10_clamp 1
		.amdhsa_ieee_mode 1
		.amdhsa_fp16_overflow 0
		.amdhsa_tg_split 0
		.amdhsa_exception_fp_ieee_invalid_op 0
		.amdhsa_exception_fp_denorm_src 0
		.amdhsa_exception_fp_ieee_div_zero 0
		.amdhsa_exception_fp_ieee_overflow 0
		.amdhsa_exception_fp_ieee_underflow 0
		.amdhsa_exception_fp_ieee_inexact 0
		.amdhsa_exception_int_div_zero 0
	.end_amdhsa_kernel

; __global__ void __launch_bounds__(NTHR, 2) fwd_megakernel(Args a_unused) {
;     extern __shared__ __attribute__((aligned(16))) unsigned char lds[];
amdhsa.kernels:
  - .agpr_count:     0
    .args:
      - .offset:         0
        .size:           176
        .value_kind:     by_value
      - .offset:         176
        .size:           4
        .value_kind:     hidden_block_count_x
      - .offset:         180
        .size:           4
        .value_kind:     hidden_block_count_y
      - .offset:         184
        .size:           4
        .value_kind:     hidden_block_count_z
      - .offset:         188
        .size:           2
        .value_kind:     hidden_group_size_x
      - .offset:         190
        .size:           2
        .value_kind:     hidden_group_size_y
      - .offset:         192
        .size:           2
        .value_kind:     hidden_group_size_z
      - .offset:         194
        .size:           2
        .value_kind:     hidden_remainder_x
      - .offset:         196
        .size:           2
        .value_kind:     hidden_remainder_y
      - .offset:         198
        .size:           2
        .value_kind:     hidden_remainder_z
      - .offset:         216
        .size:           8
        .value_kind:     hidden_global_offset_x
      - .offset:         224
        .size:           8
        .value_kind:     hidden_global_offset_y
      - .offset:         232
        .size:           8
        .value_kind:     hidden_global_offset_z
      - .offset:         240
        .size:           2
        .value_kind:     hidden_grid_dims
      - .offset:         264
        .size:           8
        .value_kind:     hidden_multigrid_sync_arg
      - .offset:         296
        .size:           4
        .value_kind:     hidden_dynamic_lds_size
    .group_segment_fixed_size: 8192
    .kernarg_segment_align: 8
    .kernarg_segment_size: 432
    .language:       OpenCL C
    .language_version:
      - 2
      - 0
    .max_flat_workgroup_size: 512
    .name:           _Z14fwd_megakernel4Args
    .private_segment_fixed_size: 0
    .sgpr_count:     108
    .sgpr_spill_count: 35
    .symbol:         _Z14fwd_megakernel4Args.kd
    .uniform_work_group_size: 1
    .uses_dynamic_stack: false
    .vgpr_count:     256
    .vgpr_spill_count: 0
    .wavefront_size: 64
